# sample-SSD head loop unrolled with counted vmcnt; EpiResT epilogues use dwordx4 residual loads/stores via permlane16_swap
# speedup vs baseline: 1.0114x; 1.0114x over previous
.LBB0_515:
	v_bfe_u32 v218, v193, 4, 1
	v_mul_u32_u24_e32 v218, 24, v218
	v_mov_b32_e32 v219, 0
	v_lshl_or_b32 v0, s8, 8, v210
	v_lshl_add_u32 v150, s12, 8, v189
	v_ashrrev_i32_e32 v1, 31, v0
	v_readlane_b32 s10, v255, 9
	v_lshlrev_b64 v[196:197], 1, v[0:1]
	v_readlane_b32 s11, v255, 10
	v_ashrrev_i32_e32 v151, 31, v150
	v_lshlrev_b64 v[198:199], 11, v[150:151]
	v_lshl_add_u64 v[148:149], s[10:11], 0, v[196:197]
	v_lshl_add_u64 v[152:153], v[148:149], 0, v[198:199]
	v_lshl_add_u64 v[152:153], v[152:153], 0, v[218:219]
	global_load_dwordx4 v[220:223], v[152:153], off
	global_load_dwordx4 v[224:227], v[152:153], off offset:256
	v_or_b32_e32 v172, 16, v150
	v_ashrrev_i32_e32 v173, 31, v172
	v_or_b32_e32 v156, 32, v150
	v_lshlrev_b64 v[186:187], 11, v[172:173]
	v_ashrrev_i32_e32 v157, 31, v156
	v_lshl_add_u64 v[152:153], v[148:149], 0, v[186:187]
	v_lshlrev_b64 v[176:177], 11, v[156:157]
	v_lshl_add_u64 v[152:153], v[152:153], 0, v[218:219]
	global_load_dwordx4 v[228:231], v[152:153], off
	global_load_dwordx4 v[232:235], v[152:153], off offset:256
	v_lshl_add_u64 v[152:153], v[148:149], 0, v[176:177]
	v_lshl_add_u64 v[152:153], v[152:153], 0, v[218:219]
	global_load_dwordx4 v[236:239], v[152:153], off
	global_load_dwordx4 v[240:243], v[152:153], off offset:256
	v_or_b32_e32 v152, 48, v150
	v_ashrrev_i32_e32 v153, 31, v152
	v_lshlrev_b64 v[160:161], 11, v[152:153]
	v_lshl_add_u64 v[154:155], v[148:149], 0, v[160:161]
	v_lshl_add_u64 v[154:155], v[154:155], 0, v[218:219]
	global_load_dwordx4 v[244:247], v[154:155], off
	global_load_dwordx4 v[248:251], v[154:155], off offset:256
	v_lshl_add_u64 v[198:199], s[10:11], 0, v[198:199]
	v_lshl_add_u64 v[196:197], v[198:199], 0, v[196:197]
	s_lshl_b32 s16, s8, 2
	s_ashr_i32 s17, s16, 31
	s_waitcnt vmcnt(0)
	v_permlane16_swap_b32_e32 v220, v222
	v_permlane16_swap_b32_e32 v221, v223
	v_permlane16_swap_b32_e32 v224, v226
	v_permlane16_swap_b32_e32 v225, v227
	v_permlane16_swap_b32_e32 v228, v230
	v_permlane16_swap_b32_e32 v229, v231
	v_permlane16_swap_b32_e32 v232, v234
	v_permlane16_swap_b32_e32 v233, v235
	v_permlane16_swap_b32_e32 v236, v238
	v_permlane16_swap_b32_e32 v237, v239
	v_permlane16_swap_b32_e32 v240, v242
	v_permlane16_swap_b32_e32 v241, v243
	v_permlane16_swap_b32_e32 v244, v246
	v_permlane16_swap_b32_e32 v245, v247
	v_permlane16_swap_b32_e32 v248, v250
	v_permlane16_swap_b32_e32 v249, v251
	v_lshlrev_b32_e32 v198, 16, v220
	v_and_b32_e32 v199, 0xffff0000, v220
	v_lshlrev_b32_e32 v200, 16, v221
	v_and_b32_e32 v201, 0xffff0000, v221
	v_pk_add_f32 v[128:129], v[128:129], v[198:199]
	v_pk_add_f32 v[130:131], v[130:131], v[200:201]
	v_mul_f32_e32 v2, v129, v129
	v_cvt_pk_bf16_f32 v220, v128, v129
	v_fmac_f32_e32 v2, v128, v128
	v_mul_f32_e32 v128, v131, v131
	v_fmac_f32_e32 v128, v130, v130
	v_add_f32_e32 v2, v2, v128
	v_lshlrev_b32_e32 v128, 16, v222
	v_and_b32_e32 v129, 0xffff0000, v222
	v_cvt_pk_bf16_f32 v221, v130, v131
	v_lshlrev_b32_e32 v130, 16, v223
	v_and_b32_e32 v131, 0xffff0000, v223
	v_pk_add_f32 v[124:125], v[124:125], v[128:129]
	v_pk_add_f32 v[126:127], v[126:127], v[130:131]
	v_cvt_pk_bf16_f32 v222, v124, v125
	v_mul_f32_e32 v125, v125, v125
	v_fmac_f32_e32 v125, v124, v124
	v_mul_f32_e32 v124, v127, v127
	v_fmac_f32_e32 v124, v126, v126
	v_add_f32_e32 v124, v125, v124
	v_add_f32_e32 v2, v2, v124
	v_lshlrev_b32_e32 v124, 16, v224
	v_and_b32_e32 v125, 0xffff0000, v224
	v_cvt_pk_bf16_f32 v223, v126, v127
	v_lshlrev_b32_e32 v126, 16, v225
	v_and_b32_e32 v127, 0xffff0000, v225
	v_pk_add_f32 v[120:121], v[120:121], v[124:125]
	s_nop 1
	v_permlane16_swap_b32_e32 v220, v222
	v_permlane16_swap_b32_e32 v221, v223
	v_lshl_add_u64 v[196:197], v[196:197], 0, v[218:219]
	global_store_dwordx4 v[196:197], v[220:223], off
	v_pk_add_f32 v[122:123], v[122:123], v[126:127]
	v_cvt_pk_bf16_f32 v224, v120, v121
	v_mul_f32_e32 v121, v121, v121
	v_fmac_f32_e32 v121, v120, v120
	v_mul_f32_e32 v120, v123, v123
	v_fmac_f32_e32 v120, v122, v122
	v_add_f32_e32 v120, v121, v120
	v_add_f32_e32 v2, v2, v120
	v_lshlrev_b32_e32 v120, 16, v226
	v_and_b32_e32 v121, 0xffff0000, v226
	v_cvt_pk_bf16_f32 v225, v122, v123
	v_lshlrev_b32_e32 v122, 16, v227
	v_and_b32_e32 v123, 0xffff0000, v227
	v_pk_add_f32 v[116:117], v[116:117], v[120:121]
	v_pk_add_f32 v[118:119], v[118:119], v[122:123]
	v_cvt_pk_bf16_f32 v226, v116, v117
	v_mul_f32_e32 v117, v117, v117
	v_fmac_f32_e32 v117, v116, v116
	v_mul_f32_e32 v116, v119, v119
	v_cvt_pk_bf16_f32 v227, v118, v119
	v_fmac_f32_e32 v116, v118, v118
	v_mbcnt_hi_u32_b32 v118, -1, v192
	v_add_f32_e32 v116, v117, v116
	v_and_b32_e32 v117, 64, v118
	v_add_f32_e32 v116, v2, v116
	v_xor_b32_e32 v2, 16, v118
	v_add_u32_e32 v119, 64, v117
	v_cmp_lt_i32_e32 vcc, v2, v119
	s_nop 1
	v_permlane16_swap_b32_e32 v224, v226
	v_permlane16_swap_b32_e32 v225, v227
	global_store_dwordx4 v[196:197], v[224:227], off offset:256
	s_nop 0
	v_cndmask_b32_e32 v2, v118, v2, vcc
	v_lshlrev_b32_e32 v2, 2, v2
	ds_bpermute_b32 v117, v2, v116
	s_waitcnt lgkmcnt(0)
	v_add_f32_e32 v117, v116, v117
	v_xor_b32_e32 v116, 32, v118
	v_cmp_lt_i32_e32 vcc, v116, v119
	s_nop 1
	v_cndmask_b32_e32 v116, v118, v116, vcc
	v_lshlrev_b32_e32 v116, 2, v116
	ds_bpermute_b32 v118, v116, v117
	s_and_saveexec_b64 s[10:11], s[38:39]
	s_cbranch_execz .LBB0_517
	v_readlane_b32 s12, v255, 11
	v_lshlrev_b64 v[120:121], 6, v[150:151]
	v_readlane_b32 s13, v255, 12
	s_lshl_b32 s8, s51, 2
	s_waitcnt lgkmcnt(0)
	v_add_f32_e32 v117, v117, v118
	v_lshl_add_u64 v[120:121], s[12:13], 0, v[120:121]
	v_lshl_add_u64 v[120:121], s[16:17], 2, v[120:121]
	v_lshl_add_u64 v[120:121], v[120:121], 0, s[8:9]
	global_store_dword v[120:121], v117, off
.LBB0_517:
	s_or_b64 exec, exec, s[10:11]
	v_lshlrev_b32_e32 v120, 16, v228
	v_and_b32_e32 v121, 0xffff0000, v228
	v_lshlrev_b32_e32 v122, 16, v229
	v_and_b32_e32 v123, 0xffff0000, v229
	v_pk_add_f32 v[112:113], v[112:113], v[120:121]
	v_pk_add_f32 v[114:115], v[114:115], v[122:123]
	v_cvt_pk_bf16_f32 v228, v112, v113
	v_mul_f32_e32 v113, v113, v113
	v_readlane_b32 s10, v255, 9
	v_fmac_f32_e32 v113, v112, v112
	v_mul_f32_e32 v112, v115, v115
	v_readlane_b32 s11, v255, 10
	v_fmac_f32_e32 v112, v114, v114
	v_add_f32_e32 v117, v113, v112
	s_waitcnt lgkmcnt(0)
	v_lshl_add_u64 v[118:119], s[10:11], 0, v[186:187]
	v_lshlrev_b32_e32 v112, 16, v230
	v_and_b32_e32 v113, 0xffff0000, v230
	v_lshl_add_u64 v[118:119], v[0:1], 1, v[118:119]
	v_cvt_pk_bf16_f32 v229, v114, v115
	v_lshlrev_b32_e32 v114, 16, v231
	v_and_b32_e32 v115, 0xffff0000, v231
	v_pk_add_f32 v[108:109], v[108:109], v[112:113]
	v_pk_add_f32 v[110:111], v[110:111], v[114:115]
	v_cvt_pk_bf16_f32 v230, v108, v109
	v_mul_f32_e32 v109, v109, v109
	v_fmac_f32_e32 v109, v108, v108
	v_mul_f32_e32 v108, v111, v111
	v_fmac_f32_e32 v108, v110, v110
	v_add_f32_e32 v108, v109, v108
	v_add_f32_e32 v113, v117, v108
	v_lshlrev_b32_e32 v108, 16, v232
	v_and_b32_e32 v109, 0xffff0000, v232
	v_lshlrev_b32_e32 v114, 16, v233
	v_and_b32_e32 v115, 0xffff0000, v233
	v_pk_add_f32 v[106:107], v[106:107], v[114:115]
	v_pk_add_f32 v[104:105], v[104:105], v[108:109]
	v_mul_f32_e32 v109, v107, v107
	v_mul_f32_e32 v108, v105, v105
	v_fmac_f32_e32 v108, v104, v104
	v_fmac_f32_e32 v109, v106, v106
	v_add_f32_e32 v108, v108, v109
	v_add_f32_e32 v113, v113, v108
	v_lshlrev_b32_e32 v108, 16, v234
	v_and_b32_e32 v109, 0xffff0000, v234
	v_lshlrev_b32_e32 v114, 16, v235
	v_and_b32_e32 v115, 0xffff0000, v235
	v_pk_add_f32 v[102:103], v[102:103], v[114:115]
	v_pk_add_f32 v[108:109], v[100:101], v[108:109]
	v_mul_f32_e32 v101, v103, v103
	v_mul_f32_e32 v100, v109, v109
	v_fmac_f32_e32 v100, v108, v108
	v_fmac_f32_e32 v101, v102, v102
	v_add_f32_e32 v100, v100, v101
	v_add_f32_e32 v100, v113, v100
	ds_bpermute_b32 v101, v2, v100
	v_cvt_pk_bf16_f32 v231, v110, v111
	s_nop 1
	v_permlane16_swap_b32_e32 v228, v230
	v_permlane16_swap_b32_e32 v229, v231
	v_lshl_add_u64 v[118:119], v[118:119], 0, v[218:219]
	global_store_dwordx4 v[118:119], v[228:231], off
	v_cvt_pk_bf16_f32 v232, v104, v105
	v_cvt_pk_bf16_f32 v233, v106, v107
	s_waitcnt lgkmcnt(0)
	v_add_f32_e32 v100, v100, v101
	ds_bpermute_b32 v101, v116, v100
	v_cvt_pk_bf16_f32 v234, v108, v109
	v_cvt_pk_bf16_f32 v235, v102, v103
	s_nop 1
	v_permlane16_swap_b32_e32 v232, v234
	v_permlane16_swap_b32_e32 v233, v235
	global_store_dwordx4 v[118:119], v[232:235], off offset:256
	s_and_saveexec_b64 s[10:11], s[38:39]
	s_cbranch_execz .LBB0_519
	v_readlane_b32 s12, v255, 11
	v_lshlrev_b64 v[102:103], 6, v[172:173]
	v_readlane_b32 s13, v255, 12
	s_lshl_b32 s8, s51, 2
	s_waitcnt lgkmcnt(0)
	v_add_f32_e32 v100, v100, v101
	v_lshl_add_u64 v[102:103], s[12:13], 0, v[102:103]
	v_lshl_add_u64 v[102:103], s[16:17], 2, v[102:103]
	v_lshl_add_u64 v[102:103], v[102:103], 0, s[8:9]
	global_store_dword v[102:103], v100, off
.LBB0_519:
	s_or_b64 exec, exec, s[10:11]
	v_lshlrev_b32_e32 v102, 16, v236
	v_and_b32_e32 v103, 0xffff0000, v236
	v_readlane_b32 s10, v255, 9
	v_lshlrev_b32_e32 v104, 16, v237
	v_and_b32_e32 v105, 0xffff0000, v237
	v_pk_add_f32 v[96:97], v[96:97], v[102:103]
	v_readlane_b32 s11, v255, 10
	v_pk_add_f32 v[98:99], v[98:99], v[104:105]
	v_cvt_pk_bf16_f32 v236, v96, v97
	v_mul_f32_e32 v97, v97, v97
	s_waitcnt lgkmcnt(0)
	v_lshl_add_u64 v[100:101], s[10:11], 0, v[176:177]
	v_fmac_f32_e32 v97, v96, v96
	v_mul_f32_e32 v96, v99, v99
	v_lshl_add_u64 v[100:101], v[0:1], 1, v[100:101]
	v_fmac_f32_e32 v96, v98, v98
	v_cvt_pk_bf16_f32 v237, v98, v99
	v_add_f32_e32 v102, v97, v96
	v_lshlrev_b32_e32 v96, 16, v238
	v_and_b32_e32 v97, 0xffff0000, v238
	v_lshlrev_b32_e32 v98, 16, v239
	v_and_b32_e32 v99, 0xffff0000, v239
	v_pk_add_f32 v[92:93], v[92:93], v[96:97]
	v_pk_add_f32 v[94:95], v[94:95], v[98:99]
	v_cvt_pk_bf16_f32 v238, v92, v93
	v_mul_f32_e32 v93, v93, v93
	v_fmac_f32_e32 v93, v92, v92
	v_mul_f32_e32 v92, v95, v95
	v_fmac_f32_e32 v92, v94, v94
	v_add_f32_e32 v92, v93, v92
	v_add_f32_e32 v97, v102, v92
	v_lshlrev_b32_e32 v92, 16, v240
	v_and_b32_e32 v93, 0xffff0000, v240
	v_lshlrev_b32_e32 v98, 16, v241
	v_and_b32_e32 v99, 0xffff0000, v241
	v_pk_add_f32 v[90:91], v[90:91], v[98:99]
	v_pk_add_f32 v[88:89], v[88:89], v[92:93]
	v_mul_f32_e32 v93, v91, v91
	v_mul_f32_e32 v92, v89, v89
	v_fmac_f32_e32 v92, v88, v88
	v_fmac_f32_e32 v93, v90, v90
	v_add_f32_e32 v92, v92, v93
	v_add_f32_e32 v97, v97, v92
	v_lshlrev_b32_e32 v92, 16, v242
	v_and_b32_e32 v93, 0xffff0000, v242
	v_lshlrev_b32_e32 v98, 16, v243
	v_and_b32_e32 v99, 0xffff0000, v243
	v_pk_add_f32 v[86:87], v[86:87], v[98:99]
	v_pk_add_f32 v[92:93], v[84:85], v[92:93]
	v_mul_f32_e32 v85, v87, v87
	v_mul_f32_e32 v84, v93, v93
	v_fmac_f32_e32 v84, v92, v92
	v_fmac_f32_e32 v85, v86, v86
	v_add_f32_e32 v84, v84, v85
	v_add_f32_e32 v84, v97, v84
	ds_bpermute_b32 v85, v2, v84
	v_cvt_pk_bf16_f32 v239, v94, v95
	s_nop 1
	v_permlane16_swap_b32_e32 v236, v238
	v_permlane16_swap_b32_e32 v237, v239
	v_lshl_add_u64 v[100:101], v[100:101], 0, v[218:219]
	global_store_dwordx4 v[100:101], v[236:239], off
	v_cvt_pk_bf16_f32 v240, v88, v89
	v_cvt_pk_bf16_f32 v241, v90, v91
	s_waitcnt lgkmcnt(0)
	v_add_f32_e32 v84, v84, v85
	ds_bpermute_b32 v85, v116, v84
	v_cvt_pk_bf16_f32 v242, v92, v93
	v_cvt_pk_bf16_f32 v243, v86, v87
	s_nop 1
	v_permlane16_swap_b32_e32 v240, v242
	v_permlane16_swap_b32_e32 v241, v243
	global_store_dwordx4 v[100:101], v[240:243], off offset:256
	s_and_saveexec_b64 s[10:11], s[38:39]
	s_cbranch_execz .LBB0_521
	v_readlane_b32 s12, v255, 11
	v_lshlrev_b64 v[86:87], 6, v[156:157]
	v_readlane_b32 s13, v255, 12
	s_lshl_b32 s8, s51, 2
	s_waitcnt lgkmcnt(0)
	v_add_f32_e32 v84, v84, v85
	v_lshl_add_u64 v[86:87], s[12:13], 0, v[86:87]
	v_lshl_add_u64 v[86:87], s[16:17], 2, v[86:87]
	v_lshl_add_u64 v[86:87], v[86:87], 0, s[8:9]
	global_store_dword v[86:87], v84, off
.LBB0_521:
	s_or_b64 exec, exec, s[10:11]
	v_lshlrev_b32_e32 v86, 16, v244
	v_and_b32_e32 v87, 0xffff0000, v244
	v_readlane_b32 s10, v255, 9
	v_lshlrev_b32_e32 v88, 16, v245
	v_and_b32_e32 v89, 0xffff0000, v245
	v_pk_add_f32 v[80:81], v[80:81], v[86:87]
	v_readlane_b32 s11, v255, 10
	v_pk_add_f32 v[82:83], v[82:83], v[88:89]
	v_cvt_pk_bf16_f32 v244, v80, v81
	v_mul_f32_e32 v81, v81, v81
	s_waitcnt lgkmcnt(0)
	v_lshl_add_u64 v[84:85], s[10:11], 0, v[160:161]
	v_fmac_f32_e32 v81, v80, v80
	v_mul_f32_e32 v80, v83, v83
	v_lshl_add_u64 v[84:85], v[0:1], 1, v[84:85]
	v_fmac_f32_e32 v80, v82, v82
	v_cvt_pk_bf16_f32 v245, v82, v83
	v_add_f32_e32 v86, v81, v80
	v_lshlrev_b32_e32 v80, 16, v246
	v_and_b32_e32 v81, 0xffff0000, v246
	v_lshlrev_b32_e32 v82, 16, v247
	v_and_b32_e32 v83, 0xffff0000, v247
	v_pk_add_f32 v[76:77], v[76:77], v[80:81]
	v_pk_add_f32 v[78:79], v[78:79], v[82:83]
	v_cvt_pk_bf16_f32 v246, v76, v77
	v_mul_f32_e32 v77, v77, v77
	v_fmac_f32_e32 v77, v76, v76
	v_mul_f32_e32 v76, v79, v79
	v_fmac_f32_e32 v76, v78, v78
	v_add_f32_e32 v76, v77, v76
	v_add_f32_e32 v81, v86, v76
	v_lshlrev_b32_e32 v76, 16, v248
	v_and_b32_e32 v77, 0xffff0000, v248
	v_lshlrev_b32_e32 v82, 16, v249
	v_and_b32_e32 v83, 0xffff0000, v249
	v_pk_add_f32 v[74:75], v[74:75], v[82:83]
	v_pk_add_f32 v[72:73], v[72:73], v[76:77]
	v_mul_f32_e32 v77, v75, v75
	v_mul_f32_e32 v76, v73, v73
	v_fmac_f32_e32 v76, v72, v72
	v_fmac_f32_e32 v77, v74, v74
	v_add_f32_e32 v76, v76, v77
	v_add_f32_e32 v81, v81, v76
	v_lshlrev_b32_e32 v76, 16, v250
	v_and_b32_e32 v77, 0xffff0000, v250
	v_lshlrev_b32_e32 v82, 16, v251
	v_and_b32_e32 v83, 0xffff0000, v251
	v_pk_add_f32 v[70:71], v[70:71], v[82:83]
	v_pk_add_f32 v[76:77], v[68:69], v[76:77]
	v_mul_f32_e32 v69, v71, v71
	v_mul_f32_e32 v68, v77, v77
	v_fmac_f32_e32 v68, v76, v76
	v_fmac_f32_e32 v69, v70, v70
	v_add_f32_e32 v68, v68, v69
	v_add_f32_e32 v68, v81, v68
	ds_bpermute_b32 v69, v2, v68
	v_cvt_pk_bf16_f32 v247, v78, v79
	s_nop 1
	v_permlane16_swap_b32_e32 v244, v246
	v_permlane16_swap_b32_e32 v245, v247
	v_lshl_add_u64 v[84:85], v[84:85], 0, v[218:219]
	global_store_dwordx4 v[84:85], v[244:247], off
	v_cvt_pk_bf16_f32 v248, v72, v73
	v_cvt_pk_bf16_f32 v249, v74, v75
	s_waitcnt lgkmcnt(0)
	v_add_f32_e32 v68, v68, v69
	ds_bpermute_b32 v69, v116, v68
	v_cvt_pk_bf16_f32 v250, v76, v77
	v_cvt_pk_bf16_f32 v251, v70, v71
	s_nop 1
	v_permlane16_swap_b32_e32 v248, v250
	v_permlane16_swap_b32_e32 v249, v251
	global_store_dwordx4 v[84:85], v[248:251], off offset:256
	s_and_saveexec_b64 s[10:11], s[38:39]
	s_cbranch_execz .LBB0_523
	v_readlane_b32 s12, v255, 11
	v_lshlrev_b64 v[70:71], 6, v[152:153]
	v_readlane_b32 s13, v255, 12
	s_lshl_b32 s8, s51, 2
	s_waitcnt lgkmcnt(0)
	v_add_f32_e32 v68, v68, v69
	v_lshl_add_u64 v[70:71], s[12:13], 0, v[70:71]
	v_lshl_add_u64 v[70:71], s[16:17], 2, v[70:71]
	v_lshl_add_u64 v[70:71], v[70:71], 0, s[8:9]
	global_store_dword v[70:71], v68, off
.LBB0_523:
	s_or_b64 exec, exec, s[10:11]
	v_add_u32_e32 v104, 0x80, v150
	v_ashrrev_i32_e32 v105, 31, v104
	v_lshlrev_b64 v[110:111], 11, v[104:105]
	s_waitcnt lgkmcnt(0)
	v_lshl_add_u64 v[68:69], v[148:149], 0, v[110:111]
	v_lshl_add_u64 v[68:69], v[68:69], 0, v[218:219]
	global_load_dwordx4 v[220:223], v[68:69], off
	global_load_dwordx4 v[224:227], v[68:69], off offset:256
	v_add_u32_e32 v88, 0x90, v150
	v_ashrrev_i32_e32 v89, 31, v88
	v_add_u32_e32 v72, 0xa0, v150
	v_lshlrev_b64 v[102:103], 11, v[88:89]
	v_ashrrev_i32_e32 v73, 31, v72
	v_lshl_add_u64 v[68:69], v[148:149], 0, v[102:103]
	v_lshlrev_b64 v[92:93], 11, v[72:73]
	v_lshl_add_u64 v[68:69], v[68:69], 0, v[218:219]
	global_load_dwordx4 v[228:231], v[68:69], off
	global_load_dwordx4 v[232:235], v[68:69], off offset:256
	v_lshl_add_u64 v[68:69], v[148:149], 0, v[92:93]
	v_lshl_add_u64 v[68:69], v[68:69], 0, v[218:219]
	global_load_dwordx4 v[236:239], v[68:69], off
	global_load_dwordx4 v[240:243], v[68:69], off offset:256
	v_add_u32_e32 v68, 0xb0, v150
	v_ashrrev_i32_e32 v69, 31, v68
	v_lshlrev_b64 v[76:77], 11, v[68:69]
	v_lshl_add_u64 v[70:71], v[148:149], 0, v[76:77]
	v_lshl_add_u64 v[70:71], v[70:71], 0, v[218:219]
	global_load_dwordx4 v[244:247], v[70:71], off
	global_load_dwordx4 v[248:251], v[70:71], off offset:256
	v_readlane_b32 s10, v255, 9
	v_readlane_b32 s11, v255, 10
	s_waitcnt vmcnt(0)
	v_permlane16_swap_b32_e32 v220, v222
	v_permlane16_swap_b32_e32 v221, v223
	v_permlane16_swap_b32_e32 v224, v226
	v_permlane16_swap_b32_e32 v225, v227
	v_permlane16_swap_b32_e32 v228, v230
	v_permlane16_swap_b32_e32 v229, v231
	v_permlane16_swap_b32_e32 v232, v234
	v_permlane16_swap_b32_e32 v233, v235
	v_permlane16_swap_b32_e32 v236, v238
	v_permlane16_swap_b32_e32 v237, v239
	v_permlane16_swap_b32_e32 v240, v242
	v_permlane16_swap_b32_e32 v241, v243
	v_permlane16_swap_b32_e32 v244, v246
	v_permlane16_swap_b32_e32 v245, v247
	v_permlane16_swap_b32_e32 v248, v250
	v_permlane16_swap_b32_e32 v249, v251
	v_lshlrev_b32_e32 v118, 16, v220
	v_and_b32_e32 v119, 0xffff0000, v220
	v_lshlrev_b32_e32 v112, 16, v221
	v_and_b32_e32 v113, 0xffff0000, v221
	v_pk_add_f32 v[64:65], v[64:65], v[118:119]
	v_pk_add_f32 v[66:67], v[66:67], v[112:113]
	v_cvt_pk_bf16_f32 v220, v64, v65
	v_mul_f32_e32 v65, v65, v65
	v_lshl_add_u64 v[110:111], s[10:11], 0, v[110:111]
	v_fmac_f32_e32 v65, v64, v64
	v_mul_f32_e32 v64, v67, v67
	v_lshl_add_u64 v[110:111], v[0:1], 1, v[110:111]
	v_fmac_f32_e32 v64, v66, v66
	v_cvt_pk_bf16_f32 v221, v66, v67
	v_add_f32_e32 v112, v65, v64
	s_waitcnt vmcnt(15)
	v_lshlrev_b32_e32 v64, 16, v222
	v_and_b32_e32 v65, 0xffff0000, v222
	v_lshlrev_b32_e32 v66, 16, v223
	v_and_b32_e32 v67, 0xffff0000, v223
	v_pk_add_f32 v[60:61], v[60:61], v[64:65]
	v_pk_add_f32 v[62:63], v[62:63], v[66:67]
	v_cvt_pk_bf16_f32 v222, v60, v61
	v_mul_f32_e32 v61, v61, v61
	v_fmac_f32_e32 v61, v60, v60
	v_mul_f32_e32 v60, v63, v63
	v_fmac_f32_e32 v60, v62, v62
	v_add_f32_e32 v60, v61, v60
	v_cvt_pk_bf16_f32 v223, v62, v63
	s_nop 1
	v_permlane16_swap_b32_e32 v220, v222
	v_permlane16_swap_b32_e32 v221, v223
	v_lshl_add_u64 v[110:111], v[110:111], 0, v[218:219]
	global_store_dwordx4 v[110:111], v[220:223], off
	v_add_f32_e32 v64, v112, v60
	s_waitcnt vmcnt(15)
	v_lshlrev_b32_e32 v60, 16, v224
	v_and_b32_e32 v61, 0xffff0000, v224
	v_lshlrev_b32_e32 v62, 16, v225
	v_and_b32_e32 v63, 0xffff0000, v225
	v_pk_add_f32 v[56:57], v[56:57], v[60:61]
	v_pk_add_f32 v[58:59], v[58:59], v[62:63]
	v_cvt_pk_bf16_f32 v224, v56, v57
	v_mul_f32_e32 v57, v57, v57
	v_fmac_f32_e32 v57, v56, v56
	v_mul_f32_e32 v56, v59, v59
	v_fmac_f32_e32 v56, v58, v58
	v_add_f32_e32 v56, v57, v56
	v_cvt_pk_bf16_f32 v225, v58, v59
	v_add_f32_e32 v60, v64, v56
	s_waitcnt vmcnt(15)
	v_lshlrev_b32_e32 v56, 16, v226
	v_and_b32_e32 v57, 0xffff0000, v226
	v_lshlrev_b32_e32 v58, 16, v227
	v_and_b32_e32 v59, 0xffff0000, v227
	v_pk_add_f32 v[52:53], v[52:53], v[56:57]
	v_pk_add_f32 v[54:55], v[54:55], v[58:59]
	v_cvt_pk_bf16_f32 v226, v52, v53
	v_mul_f32_e32 v53, v53, v53
	v_fmac_f32_e32 v53, v52, v52
	v_mul_f32_e32 v52, v55, v55
	v_fmac_f32_e32 v52, v54, v54
	v_add_f32_e32 v52, v53, v52
	v_add_f32_e32 v52, v60, v52
	ds_bpermute_b32 v53, v2, v52
	v_cvt_pk_bf16_f32 v227, v54, v55
	s_nop 1
	v_permlane16_swap_b32_e32 v224, v226
	v_permlane16_swap_b32_e32 v225, v227
	global_store_dwordx4 v[110:111], v[224:227], off offset:256
	s_waitcnt lgkmcnt(0)
	v_add_f32_e32 v52, v52, v53
	ds_bpermute_b32 v53, v116, v52
	s_and_saveexec_b64 s[10:11], s[38:39]
	s_cbranch_execz .LBB0_525
	v_readlane_b32 s12, v255, 11
	v_lshlrev_b64 v[54:55], 6, v[104:105]
	v_readlane_b32 s13, v255, 12
	s_lshl_b32 s8, s51, 2
	s_waitcnt lgkmcnt(0)
	v_add_f32_e32 v52, v52, v53
	v_lshl_add_u64 v[54:55], s[12:13], 0, v[54:55]
	v_lshl_add_u64 v[54:55], s[16:17], 2, v[54:55]
	v_lshl_add_u64 v[54:55], v[54:55], 0, s[8:9]
	global_store_dword v[54:55], v52, off
.LBB0_525:
	s_or_b64 exec, exec, s[10:11]
	s_waitcnt vmcnt(15)
	v_lshlrev_b32_e32 v54, 16, v228
	v_and_b32_e32 v55, 0xffff0000, v228
	v_readlane_b32 s10, v255, 9
	v_lshlrev_b32_e32 v56, 16, v229
	v_and_b32_e32 v57, 0xffff0000, v229
	v_pk_add_f32 v[48:49], v[48:49], v[54:55]
	v_readlane_b32 s11, v255, 10
	v_pk_add_f32 v[50:51], v[50:51], v[56:57]
	v_cvt_pk_bf16_f32 v228, v48, v49
	v_mul_f32_e32 v49, v49, v49
	s_waitcnt lgkmcnt(0)
	v_lshl_add_u64 v[52:53], s[10:11], 0, v[102:103]
	v_fmac_f32_e32 v49, v48, v48
	v_mul_f32_e32 v48, v51, v51
	v_lshl_add_u64 v[52:53], v[0:1], 1, v[52:53]
	v_fmac_f32_e32 v48, v50, v50
	v_cvt_pk_bf16_f32 v229, v50, v51
	v_add_f32_e32 v54, v49, v48
	s_waitcnt vmcnt(15)
	v_lshlrev_b32_e32 v48, 16, v230
	v_and_b32_e32 v49, 0xffff0000, v230
	v_lshlrev_b32_e32 v50, 16, v231
	v_and_b32_e32 v51, 0xffff0000, v231
	v_pk_add_f32 v[44:45], v[44:45], v[48:49]
	v_pk_add_f32 v[46:47], v[46:47], v[50:51]
	v_cvt_pk_bf16_f32 v230, v44, v45
	v_mul_f32_e32 v45, v45, v45
	v_fmac_f32_e32 v45, v44, v44
	v_mul_f32_e32 v44, v47, v47
	v_fmac_f32_e32 v44, v46, v46
	v_add_f32_e32 v44, v45, v44
	v_add_f32_e32 v49, v54, v44
	s_waitcnt vmcnt(14)
	v_lshlrev_b32_e32 v44, 16, v232
	v_and_b32_e32 v45, 0xffff0000, v232
	v_lshlrev_b32_e32 v50, 16, v233
	v_and_b32_e32 v51, 0xffff0000, v233
	v_pk_add_f32 v[42:43], v[42:43], v[50:51]
	v_pk_add_f32 v[40:41], v[40:41], v[44:45]
	v_mul_f32_e32 v45, v43, v43
	v_mul_f32_e32 v44, v41, v41
	v_fmac_f32_e32 v44, v40, v40
	v_fmac_f32_e32 v45, v42, v42
	v_add_f32_e32 v44, v44, v45
	v_add_f32_e32 v49, v49, v44
	s_waitcnt vmcnt(13)
	v_lshlrev_b32_e32 v44, 16, v234
	v_and_b32_e32 v45, 0xffff0000, v234
	v_lshlrev_b32_e32 v50, 16, v235
	v_and_b32_e32 v51, 0xffff0000, v235
	v_pk_add_f32 v[38:39], v[38:39], v[50:51]
	v_pk_add_f32 v[44:45], v[36:37], v[44:45]
	v_mul_f32_e32 v37, v39, v39
	v_mul_f32_e32 v36, v45, v45
	v_fmac_f32_e32 v36, v44, v44
	v_fmac_f32_e32 v37, v38, v38
	v_add_f32_e32 v36, v36, v37
	v_add_f32_e32 v36, v49, v36
	ds_bpermute_b32 v37, v2, v36
	v_cvt_pk_bf16_f32 v231, v46, v47
	s_nop 1
	v_permlane16_swap_b32_e32 v228, v230
	v_permlane16_swap_b32_e32 v229, v231
	v_lshl_add_u64 v[52:53], v[52:53], 0, v[218:219]
	global_store_dwordx4 v[52:53], v[228:231], off
	v_cvt_pk_bf16_f32 v232, v40, v41
	v_cvt_pk_bf16_f32 v233, v42, v43
	s_waitcnt lgkmcnt(0)
	v_add_f32_e32 v36, v36, v37
	ds_bpermute_b32 v37, v116, v36
	v_cvt_pk_bf16_f32 v234, v44, v45
	v_cvt_pk_bf16_f32 v235, v38, v39
	s_nop 1
	v_permlane16_swap_b32_e32 v232, v234
	v_permlane16_swap_b32_e32 v233, v235
	global_store_dwordx4 v[52:53], v[232:235], off offset:256
	s_and_saveexec_b64 s[10:11], s[38:39]
	s_cbranch_execz .LBB0_527
	v_readlane_b32 s12, v255, 11
	v_lshlrev_b64 v[38:39], 6, v[88:89]
	v_readlane_b32 s13, v255, 12
	s_lshl_b32 s8, s51, 2
	s_waitcnt lgkmcnt(0)
	v_add_f32_e32 v36, v36, v37
	v_lshl_add_u64 v[38:39], s[12:13], 0, v[38:39]
	v_lshl_add_u64 v[38:39], s[16:17], 2, v[38:39]
	v_lshl_add_u64 v[38:39], v[38:39], 0, s[8:9]
	global_store_dword v[38:39], v36, off
.LBB0_527:
	s_or_b64 exec, exec, s[10:11]
	s_waitcnt vmcnt(15)
	v_lshlrev_b32_e32 v38, 16, v236
	v_and_b32_e32 v39, 0xffff0000, v236
	v_readlane_b32 s10, v255, 9
	v_lshlrev_b32_e32 v40, 16, v237
	v_and_b32_e32 v41, 0xffff0000, v237
	v_pk_add_f32 v[32:33], v[32:33], v[38:39]
	v_readlane_b32 s11, v255, 10
	v_pk_add_f32 v[34:35], v[34:35], v[40:41]
	v_cvt_pk_bf16_f32 v236, v32, v33
	v_mul_f32_e32 v33, v33, v33
	s_waitcnt lgkmcnt(0)
	v_lshl_add_u64 v[36:37], s[10:11], 0, v[92:93]
	v_fmac_f32_e32 v33, v32, v32
	v_mul_f32_e32 v32, v35, v35
	v_lshl_add_u64 v[36:37], v[0:1], 1, v[36:37]
	v_fmac_f32_e32 v32, v34, v34
	v_cvt_pk_bf16_f32 v237, v34, v35
	v_add_f32_e32 v38, v33, v32
	s_waitcnt vmcnt(15)
	v_lshlrev_b32_e32 v32, 16, v238
	v_and_b32_e32 v33, 0xffff0000, v238
	v_lshlrev_b32_e32 v34, 16, v239
	v_and_b32_e32 v35, 0xffff0000, v239
	v_pk_add_f32 v[28:29], v[28:29], v[32:33]
	v_pk_add_f32 v[30:31], v[30:31], v[34:35]
	v_cvt_pk_bf16_f32 v238, v28, v29
	v_mul_f32_e32 v29, v29, v29
	v_fmac_f32_e32 v29, v28, v28
	v_mul_f32_e32 v28, v31, v31
	v_fmac_f32_e32 v28, v30, v30
	v_add_f32_e32 v28, v29, v28
	v_add_f32_e32 v33, v38, v28
	s_waitcnt vmcnt(14)
	v_lshlrev_b32_e32 v28, 16, v240
	v_and_b32_e32 v29, 0xffff0000, v240
	v_lshlrev_b32_e32 v34, 16, v241
	v_and_b32_e32 v35, 0xffff0000, v241
	v_pk_add_f32 v[26:27], v[26:27], v[34:35]
	v_pk_add_f32 v[24:25], v[24:25], v[28:29]
	v_mul_f32_e32 v29, v27, v27
	v_mul_f32_e32 v28, v25, v25
	v_fmac_f32_e32 v28, v24, v24
	v_fmac_f32_e32 v29, v26, v26
	v_add_f32_e32 v28, v28, v29
	v_add_f32_e32 v33, v33, v28
	s_waitcnt vmcnt(13)
	v_lshlrev_b32_e32 v28, 16, v242
	v_and_b32_e32 v29, 0xffff0000, v242
	v_lshlrev_b32_e32 v34, 16, v243
	v_and_b32_e32 v35, 0xffff0000, v243
	v_pk_add_f32 v[22:23], v[22:23], v[34:35]
	v_pk_add_f32 v[28:29], v[20:21], v[28:29]
	v_mul_f32_e32 v21, v23, v23
	v_mul_f32_e32 v20, v29, v29
	v_fmac_f32_e32 v20, v28, v28
	v_fmac_f32_e32 v21, v22, v22
	v_add_f32_e32 v20, v20, v21
	v_add_f32_e32 v20, v33, v20
	ds_bpermute_b32 v21, v2, v20
	v_cvt_pk_bf16_f32 v239, v30, v31
	s_nop 1
	v_permlane16_swap_b32_e32 v236, v238
	v_permlane16_swap_b32_e32 v237, v239
	v_lshl_add_u64 v[36:37], v[36:37], 0, v[218:219]
	global_store_dwordx4 v[36:37], v[236:239], off
	v_cvt_pk_bf16_f32 v240, v24, v25
	v_cvt_pk_bf16_f32 v241, v26, v27
	s_waitcnt lgkmcnt(0)
	v_add_f32_e32 v20, v20, v21
	ds_bpermute_b32 v21, v116, v20
	v_cvt_pk_bf16_f32 v242, v28, v29
	v_cvt_pk_bf16_f32 v243, v22, v23
	s_nop 1
	v_permlane16_swap_b32_e32 v240, v242
	v_permlane16_swap_b32_e32 v241, v243
	global_store_dwordx4 v[36:37], v[240:243], off offset:256
	s_and_saveexec_b64 s[10:11], s[38:39]
	s_cbranch_execz .LBB0_529
	v_readlane_b32 s12, v255, 11
	v_lshlrev_b64 v[22:23], 6, v[72:73]
	v_readlane_b32 s13, v255, 12
	s_lshl_b32 s8, s51, 2
	s_waitcnt lgkmcnt(0)
	v_add_f32_e32 v20, v20, v21
	v_lshl_add_u64 v[22:23], s[12:13], 0, v[22:23]
	v_lshl_add_u64 v[22:23], s[16:17], 2, v[22:23]
	v_lshl_add_u64 v[22:23], v[22:23], 0, s[8:9]
	global_store_dword v[22:23], v20, off
.LBB0_529:
	s_or_b64 exec, exec, s[10:11]
	v_readlane_b32 s10, v255, 9
	v_readlane_b32 s11, v255, 10
	s_waitcnt vmcnt(15)
	v_lshlrev_b32_e32 v22, 16, v245
	v_and_b32_e32 v23, 0xffff0000, v245
	s_waitcnt lgkmcnt(0)
	v_lshl_add_u64 v[20:21], s[10:11], 0, v[76:77]
	v_lshl_add_u64 v[20:21], v[0:1], 1, v[20:21]
	v_lshlrev_b32_e32 v0, 16, v244
	v_and_b32_e32 v1, 0xffff0000, v244
	v_pk_add_f32 v[0:1], v[16:17], v[0:1]
	v_pk_add_f32 v[18:19], v[18:19], v[22:23]
	v_cvt_pk_bf16_f32 v244, v0, v1
	v_mul_f32_e32 v1, v1, v1
	v_fmac_f32_e32 v1, v0, v0
	v_mul_f32_e32 v0, v19, v19
	v_fmac_f32_e32 v0, v18, v18
	v_cvt_pk_bf16_f32 v245, v18, v19
	v_add_f32_e32 v18, v1, v0
	s_waitcnt vmcnt(14)
	v_lshlrev_b32_e32 v0, 16, v246
	v_and_b32_e32 v1, 0xffff0000, v246
	v_lshlrev_b32_e32 v16, 16, v247
	v_and_b32_e32 v17, 0xffff0000, v247
	v_pk_add_f32 v[0:1], v[12:13], v[0:1]
	v_pk_add_f32 v[14:15], v[14:15], v[16:17]
	v_cvt_pk_bf16_f32 v246, v0, v1
	v_mul_f32_e32 v1, v1, v1
	v_fmac_f32_e32 v1, v0, v0
	v_mul_f32_e32 v0, v15, v15
	v_fmac_f32_e32 v0, v14, v14
	v_add_f32_e32 v0, v1, v0
	v_add_f32_e32 v13, v18, v0
	s_waitcnt vmcnt(14)
	v_lshlrev_b32_e32 v0, 16, v248
	v_and_b32_e32 v1, 0xffff0000, v248
	v_lshlrev_b32_e32 v16, 16, v249
	v_and_b32_e32 v17, 0xffff0000, v249
	v_pk_add_f32 v[10:11], v[10:11], v[16:17]
	v_pk_add_f32 v[0:1], v[8:9], v[0:1]
	v_mul_f32_e32 v9, v11, v11
	v_mul_f32_e32 v8, v1, v1
	v_fmac_f32_e32 v8, v0, v0
	v_fmac_f32_e32 v9, v10, v10
	v_add_f32_e32 v8, v8, v9
	v_add_f32_e32 v13, v13, v8
	s_waitcnt vmcnt(13)
	v_lshlrev_b32_e32 v8, 16, v250
	v_and_b32_e32 v9, 0xffff0000, v250
	v_lshlrev_b32_e32 v16, 16, v251
	v_and_b32_e32 v17, 0xffff0000, v251
	v_pk_add_f32 v[6:7], v[6:7], v[16:17]
	v_pk_add_f32 v[4:5], v[4:5], v[8:9]
	v_mul_f32_e32 v9, v7, v7
	v_mul_f32_e32 v8, v5, v5
	v_fmac_f32_e32 v8, v4, v4
	v_fmac_f32_e32 v9, v6, v6
	v_add_f32_e32 v8, v8, v9
	v_add_f32_e32 v16, v13, v8
	ds_bpermute_b32 v2, v2, v16
	v_cvt_pk_bf16_f32 v247, v14, v15
	s_nop 1
	v_permlane16_swap_b32_e32 v244, v246
	v_permlane16_swap_b32_e32 v245, v247
	v_lshl_add_u64 v[20:21], v[20:21], 0, v[218:219]
	global_store_dwordx4 v[20:21], v[244:247], off
	v_cvt_pk_bf16_f32 v248, v0, v1
	v_cvt_pk_bf16_f32 v249, v10, v11
	s_waitcnt lgkmcnt(0)
	v_add_f32_e32 v0, v16, v2
	ds_bpermute_b32 v1, v116, v0
	v_cvt_pk_bf16_f32 v250, v4, v5
	v_cvt_pk_bf16_f32 v251, v6, v7
	s_nop 1
	v_permlane16_swap_b32_e32 v248, v250
	v_permlane16_swap_b32_e32 v249, v251
	global_store_dwordx4 v[20:21], v[248:251], off offset:256
	s_and_saveexec_b64 s[10:11], s[38:39]
	s_cbranch_execz .LBB0_531
	v_readlane_b32 s12, v255, 11
	v_lshlrev_b64 v[4:5], 6, v[68:69]
	v_readlane_b32 s13, v255, 12
	s_lshl_b32 s8, s51, 2
	s_waitcnt lgkmcnt(0)
	v_add_f32_e32 v0, v0, v1
	v_lshl_add_u64 v[4:5], s[12:13], 0, v[4:5]
	v_lshl_add_u64 v[4:5], s[16:17], 2, v[4:5]
	v_lshl_add_u64 v[4:5], v[4:5], 0, s[8:9]
	global_store_dword v[4:5], v0, off

.LBB0_673:
	s_and_b64 vcc, exec, s[2:3]
	s_cbranch_vccz .LBB0_783
	v_readlane_b32 s2, v254, 31
	s_cmpk_gt_i32 s2, 0x1ff
	s_cbranch_scc1 .LBB0_783
	v_writelane_b32 v255, s90, 28
	v_readlane_b32 s93, v254, 31
	v_readlane_b32 s12, v254, 53
	v_writelane_b32 v255, s91, 29
	v_readlane_b32 s14, v254, 55
	v_readlane_b32 s8, v255, 2
	s_lshl_b32 s10, s8, 4
	s_mul_i32 s3, s8, 0x6000
	s_lshl_b32 s28, s8, 7
	s_ashr_i32 s11, s10, 31
	s_mul_hi_i32 s2, s8, 0x6000
	s_waitcnt lgkmcnt(0)
	s_add_u32 s90, s78, s3
	s_mul_i32 s5, s8, 0x1800
	s_addc_u32 s91, s79, s2
	s_mul_hi_i32 s4, s8, 0x1800
	s_add_u32 s78, s80, s5
	s_mul_i32 s7, s8, 0x688000
	s_addc_u32 s79, s81, s4
	v_readlane_b32 s4, v255, 17
	s_mul_hi_i32 s6, s8, 0x688000
	v_readlane_b32 s5, v255, 18
	s_add_u32 s29, s4, s7
	s_addc_u32 s6, s5, s6
	s_lshl_b64 s[2:3], s[10:11], 2
	s_add_u32 s60, s84, s2
	s_addc_u32 s61, s85, s3
	s_add_u32 s62, s90, 0x1800
	s_addc_u32 s63, s91, 0
	s_add_u32 s72, s90, 0x3000
	s_addc_u32 s73, s91, 0
	s_add_u32 s74, s90, 0x4800
	s_addc_u32 s75, s91, 0
	s_bitcmp1_b32 s93, 0
	v_readlane_b32 s2, v254, 32
	s_cselect_b64 s[76:77], -1, 0
	s_bitcmp1_b32 s2, 0
	s_cselect_b64 s[80:81], -1, 0
	v_readlane_b32 s15, v254, 56
	s_add_u32 s2, s14, 0xaba4020
	v_readlane_b32 s13, v254, 54
	s_addc_u32 s3, s15, 0
	v_writelane_b32 v255, s2, 33
	v_readlane_b32 s12, v254, 33
	s_add_i32 s11, s93, 0xffffff00
	v_writelane_b32 v255, s3, 34
	s_lshl_b32 s2, s8, 11
	v_readlane_b32 s22, v254, 43
	v_readlane_b32 s23, v254, 44
	s_add_u32 s84, s22, 0x18020
	v_readlane_b32 s26, v254, 47
	s_addc_u32 s85, s23, 0
	v_readlane_b32 s27, v254, 48
	s_add_u32 s26, s4, 0x7918a00
	s_addc_u32 s27, s5, 0
	s_add_u32 s4, s29, 0x680200
	v_writelane_b32 v255, s2, 26
	s_mov_b32 s67, s6
	s_addc_u32 s5, s6, 0
	s_mov_b32 s92, s93
	v_mov_b32_e32 v157, v207
	v_readlane_b32 s13, v254, 34
	v_readlane_b32 s14, v254, 35
	v_readlane_b32 s15, v254, 36
	v_readlane_b32 s16, v254, 37
	v_readlane_b32 s17, v254, 38
	v_readlane_b32 s18, v254, 39
	v_readlane_b32 s19, v254, 40
	v_readlane_b32 s20, v254, 41
	v_readlane_b32 s21, v254, 42
	v_readlane_b32 s24, v254, 45
	v_readlane_b32 s25, v254, 46
	s_branch .LBB0_677
.Ltramp_1293:
	s_branch .LBB0_1293
.LBB0_676:
	v_readlane_b32 s2, v254, 32
	s_add_i32 s93, s93, s2
	s_xor_b64 s[76:77], s[76:77], s[80:81]
	s_add_i32 s11, s11, s2
	s_add_i32 s92, s92, s2
	s_cmpk_gt_i32 s93, 0x1ff
	s_cbranch_scc1 .LBB0_782

.LBB0_735:
	s_or_b64 exec, exec, s[2:3]
	s_and_saveexec_b64 s[2:3], vcc
	v_mov_b32_e32 v54, s16
	ds_write_b32 v54, v55 offset:12384
	s_or_b64 exec, exec, s[2:3]
	s_lshr_b32 s8, s11, 1
	s_lshl_b32 s2, s8, 4
	v_readlane_b32 s3, v255, 26
	s_add_i32 s2, s3, s2
	s_lshl_b32 s12, s57, 3
	s_add_i32 s2, s2, s12
	s_ashr_i32 s3, s2, 31
	s_lshl_b64 s[6:7], s[2:3], 15
	s_mulk_i32 s8, 0x3400
	s_lshl_b32 s2, s57, 9
	s_or_b32 s13, s8, s2
	s_add_i32 s2, s10, s12
	s_add_i32 s8, s13, 0x6801000
	s_ashr_i32 s3, s2, 31
	s_lshl_b64 s[14:15], s[8:9], 1
	s_add_i32 s22, s13, 0x6801d00
	s_lshl_b64 s[2:3], s[2:3], 2
	s_add_u32 s2, s86, s2
	s_addc_u32 s3, s87, s3
	s_add_i32 s8, s13, 0x6800000
	s_lshl_b64 s[16:17], s[8:9], 1
	s_add_i32 s8, s13, 0x6802a00
	v_lshl_add_u64 v[52:53], s[6:7], 0, v[52:53]
	v_readlane_b32 s6, v255, 33
	s_lshl_b64 s[18:19], s[8:9], 1
	v_readlane_b32 s20, v255, 24
	v_lshl_add_u64 v[52:53], v[52:53], 0, v[2:3]
	v_readlane_b32 s7, v255, 34
	v_lshlrev_b32_e32 v54, 5, v65
	v_mov_b32_e32 v55, v3
	v_readlane_b32 s21, v255, 25
	v_lshl_add_u64 v[140:141], s[6:7], 0, v[52:53]
	s_add_u32 s6, s20, s14
	v_lshl_add_u64 v[128:129], s[60:61], 0, v[54:55]
	v_lshlrev_b64 v[54:55], 1, v[0:1]
	s_addc_u32 s7, s21, s15
	v_lshl_add_u64 v[142:143], s[6:7], 0, v[54:55]
	s_add_u32 s6, s26, s16
	s_addc_u32 s7, s27, s17
	v_lshlrev_b32_e32 v185, 2, v0
	v_lshl_add_u64 v[0:1], s[6:7], 0, v[54:55]
	s_add_u32 s6, s20, s18
	s_addc_u32 s7, s21, s19
	v_cmp_eq_u32_e32 vcc, 0, v64
	v_lshl_add_u32 v137, v66, 2, 0
	v_lshl_add_u64 v[130:131], s[20:21], 0, v[54:55]
	v_lshl_add_u64 v[144:145], s[84:85], 0, v[52:53]
	v_lshl_add_u64 v[146:147], s[6:7], 0, v[54:55]
	s_mov_b32 s12, 0
	s_movk_i32 s13, 0x3000
	s_mov_b64 s[6:7], 0
	s_mov_b32 s8, s22
	v_and_b32_e32 v70, 7, v157
	v_lshlrev_b32_e32 v70, 7, v70
	v_mov_b32_e32 v71, 0
	v_lshl_add_u64 v[68:69], v[0:1], 0, v[70:71]
	global_load_ushort v209, v[68:69], off
	v_lshl_add_u64 v[68:69], v[142:143], 0, v[70:71]
	global_load_ushort v188, v[68:69], off
	v_lshl_add_u64 v[68:69], s[8:9], 1, v[130:131]
	v_lshl_add_u64 v[68:69], v[68:69], 0, v[70:71]
	global_load_ushort v187, v[68:69], off
	v_lshl_add_u64 v[68:69], v[146:147], 0, v[70:71]
	global_load_ushort v186, v[68:69], off
	s_waitcnt lgkmcnt(0)
	s_barrier
	global_load_dwordx4 v[52:55], v[144:145], off offset:16
	global_load_dwordx4 v[56:59], v[144:145], off
	global_load_dwordx4 v[60:63], v[144:145], off offset:-16
	global_load_dwordx4 v[64:67], v[144:145], off offset:-32
	s_lshl_b32 s14, s57, 5
	s_add_u32 s14, s60, s14
	s_addc_u32 s15, s61, 0
	s_nop 0
	s_load_dword s12, s[2:3], 0x0
	s_load_dword s14, s[14:15], 0x0
	v_and_b32_e32 v2, 7, v157
	v_cmp_eq_u32_e32 vcc, 0, v2
	v_add_u32_e32 v189, 0, v185
	s_waitcnt lgkmcnt(0)
	v_mov_b32_e32 v2, s14
	s_mov_b32 s14, 0x3fb8aa3b
	s_waitcnt vmcnt(8)
	v_mul_f32_e32 v68, 0x3fb8aa3b, v2
	v_fma_f32 v69, v2, s14, -v68
	v_rndne_f32_e32 v70, v68
	v_fmac_f32_e32 v69, 0x32a5705f, v2
	v_sub_f32_e32 v68, v68, v70
	v_add_f32_e32 v68, v68, v69
	v_exp_f32_e32 v68, v68
	v_cvt_i32_f32_e32 v69, v70
	s_mov_b32 s14, 0xc2ce8ed0
	v_cmp_ngt_f32_e64 s[38:39], s14, v2
	s_mov_b32 s14, 0x42b17218
	v_ldexp_f32 v68, v68, v69
	v_cndmask_b32_e64 v68, 0, v68, s[38:39]
	v_cmp_nlt_f32_e64 s[38:39], s14, v2
	s_add_i32 s14, s13, 0
	v_mov_b32_e32 v72, s14
	v_cndmask_b32_e64 v116, v203, v68, s[38:39]
	ds_read2_b32 v[68:69], v72 offset1:8
	ds_read2st64_b32 v[70:71], v189 offset1:8
	ds_read_b128 v[104:107], v137 offset:10240
	ds_read_b128 v[112:115], v137 offset:10256
	ds_read_b128 v[120:123], v137 offset:10272
	ds_read_b128 v[108:111], v137 offset:10288
	s_waitcnt lgkmcnt(5)
	v_mul_f32_e64 v2, v68, -v116
	s_waitcnt lgkmcnt(4)
	v_mul_f32_e32 v156, v68, v70
	v_mul_f32_e64 v68, v69, -v116
	v_mul_f32_e32 v68, 0x3fb8aa3b, v68
	v_exp_f32_e32 v158, v68
	v_mul_f32_e32 v160, v69, v71
	ds_read_b128 v[100:103], v137 offset:10752
	ds_read_b128 v[96:99], v137 offset:10768
	ds_read_b128 v[92:95], v137 offset:10784
	ds_read_b128 v[88:91], v137 offset:10800
	ds_read2_b32 v[68:69], v72 offset0:16 offset1:24
	v_mul_f32_e32 v2, 0x3fb8aa3b, v2
	v_exp_f32_e32 v2, v2
	s_waitcnt lgkmcnt(0)
	v_mul_f32_e64 v70, v68, -v116
	v_mul_f32_e32 v70, 0x3fb8aa3b, v70
	v_exp_f32_e32 v162, v70
	ds_read2st64_b32 v[70:71], v189 offset0:16 offset1:24
	ds_read_b128 v[84:87], v137 offset:11264
	ds_read_b128 v[80:83], v137 offset:11280
	ds_read_b128 v[76:79], v137 offset:11296
	ds_read_b128 v[72:75], v137 offset:11312
	s_waitcnt lgkmcnt(4)
	v_mul_f32_e32 v164, v68, v70
	v_mul_f32_e64 v68, v69, -v116
	v_mul_f32_e32 v68, 0x3fb8aa3b, v68
	v_exp_f32_e32 v166, v68
	v_mul_f32_e32 v168, v69, v71
	ds_read_b128 v[68:71], v137 offset:11776
	ds_read_b128 v[148:151], v137 offset:8192
	ds_read_b128 v[170:173], v137 offset:8208
	ds_read_b128 v[124:127], v137 offset:8224
	ds_read_b128 v[116:119], v137 offset:8240
	ds_read_b128 v[152:155], v137 offset:8704
	ds_read_b128 v[174:177], v137 offset:9216
	s_waitcnt lgkmcnt(5)
	v_pk_mul_f32 v[148:149], v[156:157], v[148:149] op_sel_hi:[0,1]
	v_pk_fma_f32 v[48:49], v[48:49], v[2:3], v[148:149] op_sel_hi:[1,0,1]
	s_waitcnt lgkmcnt(4)
	v_pk_mul_f32 v[170:171], v[156:157], v[170:171] op_sel_hi:[0,1]
	v_fma_f32 v210, v48, v104, 0
	v_fmac_f32_e32 v210, v49, v105
	s_waitcnt lgkmcnt(1)
	v_pk_mul_f32 v[104:105], v[160:161], v[152:153] op_sel_hi:[0,1]
	v_pk_fma_f32 v[152:153], v[48:49], v[158:159], v[104:105] op_sel_hi:[1,0,1]
	v_pk_mul_f32 v[104:105], v[156:157], v[150:151] op_sel_hi:[0,1]
	v_pk_fma_f32 v[50:51], v[50:51], v[2:3], v[104:105] op_sel_hi:[1,0,1]
	v_pk_fma_f32 v[44:45], v[44:45], v[2:3], v[170:171] op_sel_hi:[1,0,1]
	v_fmac_f32_e32 v210, v50, v106
	v_fmac_f32_e32 v210, v51, v107
	v_fmac_f32_e32 v210, v44, v112
	v_fmac_f32_e32 v210, v45, v113
	v_pk_mul_f32 v[112:113], v[156:157], v[172:173] op_sel_hi:[0,1]
	v_pk_fma_f32 v[46:47], v[46:47], v[2:3], v[112:113] op_sel_hi:[1,0,1]
	v_pk_mul_f32 v[124:125], v[156:157], v[124:125] op_sel_hi:[0,1]
	v_fmac_f32_e32 v210, v46, v114
	v_fmac_f32_e32 v210, v47, v115
	v_pk_fma_f32 v[40:41], v[40:41], v[2:3], v[124:125] op_sel_hi:[1,0,1]
	ds_read_b128 v[178:181], v137 offset:9728
	ds_read_b128 v[212:215], v137 offset:9744
	v_fmac_f32_e32 v210, v40, v120
	v_fmac_f32_e32 v210, v41, v121
	v_pk_mul_f32 v[120:121], v[156:157], v[126:127] op_sel_hi:[0,1]
	v_pk_fma_f32 v[42:43], v[42:43], v[2:3], v[120:121] op_sel_hi:[1,0,1]
	v_pk_mul_f32 v[116:117], v[156:157], v[116:117] op_sel_hi:[0,1]
	v_fmac_f32_e32 v210, v42, v122
	v_fmac_f32_e32 v210, v43, v123
	v_pk_fma_f32 v[36:37], v[36:37], v[2:3], v[116:117] op_sel_hi:[1,0,1]
	v_pk_mul_f32 v[104:105], v[160:161], v[154:155] op_sel_hi:[0,1]
	v_fmac_f32_e32 v210, v36, v108
	s_waitcnt lgkmcnt(2)
	v_pk_mul_f32 v[48:49], v[164:165], v[174:175] op_sel_hi:[0,1]
	v_pk_fma_f32 v[154:155], v[50:51], v[158:159], v[104:105] op_sel_hi:[1,0,1]
	v_pk_mul_f32 v[104:105], v[164:165], v[176:177] op_sel_hi:[0,1]
	ds_read_b128 v[174:177], v137 offset:8720
	v_fmac_f32_e32 v210, v37, v109
	v_pk_mul_f32 v[108:109], v[156:157], v[118:119] op_sel_hi:[0,1]
	v_pk_fma_f32 v[148:149], v[152:153], v[162:163], v[48:49] op_sel_hi:[1,0,1]
	s_waitcnt lgkmcnt(2)
	v_pk_mul_f32 v[48:49], v[168:169], v[178:179] op_sel_hi:[0,1]
	v_pk_mul_f32 v[50:51], v[168:169], v[180:181] op_sel_hi:[0,1]
	ds_read_b128 v[178:181], v137 offset:9232
	v_pk_fma_f32 v[38:39], v[38:39], v[2:3], v[108:109] op_sel_hi:[1,0,1]
	s_waitcnt lgkmcnt(1)
	v_pk_mul_f32 v[170:171], v[160:161], v[174:175] op_sel_hi:[0,1]
	v_fmac_f32_e32 v210, v38, v110
	v_fmac_f32_e32 v210, v39, v111
	ds_bpermute_b32 v2, v161, v210
	v_pk_mul_f32 v[112:113], v[160:161], v[176:177] op_sel_hi:[0,1]
	v_pk_fma_f32 v[174:175], v[44:45], v[158:159], v[170:171] op_sel_hi:[1,0,1]
	s_waitcnt lgkmcnt(1)
	v_pk_mul_f32 v[170:171], v[164:165], v[178:179] op_sel_hi:[0,1]
	v_pk_fma_f32 v[176:177], v[46:47], v[158:159], v[112:113] op_sel_hi:[1,0,1]
	v_pk_mul_f32 v[112:113], v[164:165], v[180:181] op_sel_hi:[0,1]
	ds_read_b128 v[178:181], v137 offset:8736
	v_pk_mul_f32 v[44:45], v[168:169], v[212:213] op_sel_hi:[0,1]
	v_pk_mul_f32 v[46:47], v[168:169], v[214:215] op_sel_hi:[0,1]
	ds_read_b128 v[212:215], v137 offset:9248
	ds_read_b128 v[216:219], v137 offset:9760
	ds_read_b128 v[220:223], v137 offset:9776
	s_waitcnt lgkmcnt(4)
	v_add_f32_e32 v2, v210, v2
	ds_bpermute_b32 v110, v163, v2
	s_waitcnt lgkmcnt(4)
	v_pk_mul_f32 v[124:125], v[160:161], v[178:179] op_sel_hi:[0,1]
	v_pk_mul_f32 v[120:121], v[160:161], v[180:181] op_sel_hi:[0,1]
	v_pk_fma_f32 v[178:179], v[40:41], v[158:159], v[124:125] op_sel_hi:[1,0,1]
	s_waitcnt lgkmcnt(3)
	v_pk_mul_f32 v[124:125], v[164:165], v[212:213] op_sel_hi:[0,1]
	v_pk_fma_f32 v[180:181], v[42:43], v[158:159], v[120:121] op_sel_hi:[1,0,1]
	v_pk_mul_f32 v[120:121], v[164:165], v[214:215] op_sel_hi:[0,1]
	ds_read_b128 v[212:215], v137 offset:8752
	s_waitcnt lgkmcnt(3)
	v_pk_mul_f32 v[40:41], v[168:169], v[216:217] op_sel_hi:[0,1]
	v_pk_mul_f32 v[42:43], v[168:169], v[218:219] op_sel_hi:[0,1]
	ds_read_b128 v[216:219], v137 offset:9264
	s_waitcnt lgkmcnt(2)
	v_add_f32_e32 v2, v2, v110
	v_pk_fma_f32 v[150:151], v[154:155], v[162:163], v[104:105] op_sel_hi:[1,0,1]
	ds_read_b128 v[104:107], v137 offset:11792
	v_pk_fma_f32 v[172:173], v[176:177], v[162:163], v[112:113] op_sel_hi:[1,0,1]
	ds_read_b128 v[112:115], v137 offset:11808
	v_pk_fma_f32 v[126:127], v[180:181], v[162:163], v[120:121] op_sel_hi:[1,0,1]
	ds_read_b128 v[120:123], v137 offset:11824
	ds_bpermute_b32 v110, v165, v2
	s_waitcnt lgkmcnt(5)
	v_pk_mul_f32 v[116:117], v[160:161], v[212:213] op_sel_hi:[0,1]
	v_pk_mul_f32 v[108:109], v[160:161], v[214:215] op_sel_hi:[0,1]
	v_pk_fma_f32 v[182:183], v[36:37], v[158:159], v[116:117] op_sel_hi:[1,0,1]
	s_waitcnt lgkmcnt(4)
	v_pk_mul_f32 v[116:117], v[164:165], v[216:217] op_sel_hi:[0,1]
	v_pk_fma_f32 v[118:119], v[38:39], v[158:159], v[108:109] op_sel_hi:[1,0,1]
	v_pk_mul_f32 v[108:109], v[164:165], v[218:219] op_sel_hi:[0,1]
	v_pk_fma_f32 v[170:171], v[174:175], v[162:163], v[170:171] op_sel_hi:[1,0,1]
	v_pk_fma_f32 v[124:125], v[178:179], v[162:163], v[124:125] op_sel_hi:[1,0,1]
	v_pk_fma_f32 v[116:117], v[182:183], v[162:163], v[116:117] op_sel_hi:[1,0,1]
	v_pk_mul_f32 v[36:37], v[168:169], v[220:221] op_sel_hi:[0,1]
	v_pk_fma_f32 v[108:109], v[118:119], v[162:163], v[108:109] op_sel_hi:[1,0,1]
	v_pk_mul_f32 v[38:39], v[168:169], v[222:223] op_sel_hi:[0,1]
	v_pk_fma_f32 v[48:49], v[148:149], v[166:167], v[48:49] op_sel_hi:[1,0,1]
	v_pk_fma_f32 v[50:51], v[150:151], v[166:167], v[50:51] op_sel_hi:[1,0,1]
	v_pk_fma_f32 v[44:45], v[170:171], v[166:167], v[44:45] op_sel_hi:[1,0,1]
	v_pk_fma_f32 v[46:47], v[172:173], v[166:167], v[46:47] op_sel_hi:[1,0,1]
	v_pk_fma_f32 v[40:41], v[124:125], v[166:167], v[40:41] op_sel_hi:[1,0,1]
	v_pk_fma_f32 v[42:43], v[126:127], v[166:167], v[42:43] op_sel_hi:[1,0,1]
	v_pk_fma_f32 v[36:37], v[116:117], v[166:167], v[36:37] op_sel_hi:[1,0,1]
	v_pk_fma_f32 v[38:39], v[108:109], v[166:167], v[38:39] op_sel_hi:[1,0,1]
	global_store_dwordx4 v[140:141], v[48:51], off offset:-32
	global_store_dwordx4 v[140:141], v[44:47], off offset:-16
	global_store_dwordx4 v[140:141], v[40:43], off
	global_store_dwordx4 v[140:141], v[36:39], off offset:16
	s_waitcnt vmcnt(8)
	s_and_saveexec_b64 s[16:17], vcc
	s_cbranch_execz .Lsmp_h0_743
	v_lshlrev_b32_e32 v111, 16, v209
	v_mul_f32_e32 v156, 0xbfb8aa3b, v111
	v_exp_f32_e32 v156, v156
	ds_read_b32 v158, v189
	s_waitcnt lgkmcnt(1)
	v_add_f32_e32 v2, v2, v110
	v_add_f32_e32 v156, 1.0, v156
	v_rcp_f32_e32 v156, v156
	s_waitcnt lgkmcnt(0)
	v_fmac_f32_e32 v2, s12, v158
	v_mul_f32_e32 v110, v156, v111
	v_mul_f32_e32 v2, v110, v2
	ds_write_b32 v189, v2 offset:12544
.Lsmp_h0_743:
	s_or_b64 exec, exec, s[16:17]
	v_fma_f32 v2, v152, v100, 0
	v_fmac_f32_e32 v2, v153, v101
	v_fmac_f32_e32 v2, v154, v102
	v_fmac_f32_e32 v2, v155, v103
	v_fmac_f32_e32 v2, v174, v96
	v_fmac_f32_e32 v2, v175, v97
	v_fmac_f32_e32 v2, v176, v98
	v_fmac_f32_e32 v2, v177, v99
	v_fmac_f32_e32 v2, v178, v92
	v_fmac_f32_e32 v2, v179, v93
	v_fmac_f32_e32 v2, v180, v94
	v_fmac_f32_e32 v2, v181, v95
	v_fmac_f32_e32 v2, v182, v88
	v_fmac_f32_e32 v2, v183, v89
	v_fmac_f32_e32 v2, v118, v90
	v_fmac_f32_e32 v2, v119, v91
	ds_bpermute_b32 v88, v161, v2
	s_waitcnt lgkmcnt(0)
	v_add_f32_e32 v2, v2, v88
	ds_bpermute_b32 v88, v163, v2
	s_waitcnt lgkmcnt(0)
	v_add_f32_e32 v2, v2, v88
	ds_bpermute_b32 v88, v165, v2
	s_and_saveexec_b64 s[16:17], vcc
	s_cbranch_execz .Lsmp_h0_745
	v_lshlrev_b32_e32 v89, 16, v188
	v_mul_f32_e32 v90, 0xbfb8aa3b, v89
	v_exp_f32_e32 v90, v90
	ds_read_b32 v91, v189 offset:2048
	s_waitcnt lgkmcnt(1)
	v_add_f32_e32 v2, v2, v88
	v_add_f32_e32 v90, 1.0, v90
	v_rcp_f32_e32 v90, v90
	s_waitcnt lgkmcnt(0)
	v_fmac_f32_e32 v2, s12, v91
	v_mul_f32_e32 v88, v90, v89
	v_mul_f32_e32 v2, v88, v2
	ds_write_b32 v189, v2 offset:14592
.Lsmp_h0_745:
	s_or_b64 exec, exec, s[16:17]
	v_fma_f32 v2, v148, v84, 0
	v_fmac_f32_e32 v2, v149, v85
	v_fmac_f32_e32 v2, v150, v86
	v_fmac_f32_e32 v2, v151, v87
	v_fmac_f32_e32 v2, v170, v80
	v_fmac_f32_e32 v2, v171, v81
	v_fmac_f32_e32 v2, v172, v82
	v_fmac_f32_e32 v2, v173, v83
	v_fmac_f32_e32 v2, v124, v76
	v_fmac_f32_e32 v2, v125, v77
	v_fmac_f32_e32 v2, v126, v78
	v_fmac_f32_e32 v2, v127, v79
	v_fmac_f32_e32 v2, v116, v72
	v_fmac_f32_e32 v2, v117, v73
	v_fmac_f32_e32 v2, v108, v74
	v_fmac_f32_e32 v2, v109, v75
	ds_bpermute_b32 v72, v161, v2
	s_waitcnt lgkmcnt(0)
	v_add_f32_e32 v2, v2, v72
	ds_bpermute_b32 v72, v163, v2
	s_waitcnt lgkmcnt(0)
	v_add_f32_e32 v2, v2, v72
	ds_bpermute_b32 v72, v165, v2
	s_and_saveexec_b64 s[16:17], vcc
	s_cbranch_execz .Lsmp_h0_747
	v_lshlrev_b32_e32 v73, 16, v187
	v_mul_f32_e32 v74, 0xbfb8aa3b, v73
	v_exp_f32_e32 v74, v74
	ds_read_b32 v75, v189 offset:4096
	s_waitcnt lgkmcnt(1)
	v_add_f32_e32 v2, v2, v72
	v_add_f32_e32 v74, 1.0, v74
	v_rcp_f32_e32 v74, v74
	s_waitcnt lgkmcnt(0)
	v_fmac_f32_e32 v2, s12, v75
	v_mul_f32_e32 v72, v74, v73
	v_mul_f32_e32 v2, v72, v2
	ds_write_b32 v189, v2 offset:16640
.Lsmp_h0_747:
	s_or_b64 exec, exec, s[16:17]
	v_fma_f32 v2, v48, v68, 0
	v_fmac_f32_e32 v2, v49, v69
	v_fmac_f32_e32 v2, v50, v70
	v_fmac_f32_e32 v2, v51, v71
	v_fmac_f32_e32 v2, v44, v104
	v_fmac_f32_e32 v2, v45, v105
	v_fmac_f32_e32 v2, v46, v106
	v_fmac_f32_e32 v2, v47, v107
	v_fmac_f32_e32 v2, v40, v112
	v_fmac_f32_e32 v2, v41, v113
	v_fmac_f32_e32 v2, v42, v114
	v_fmac_f32_e32 v2, v43, v115
	v_fmac_f32_e32 v2, v36, v120
	v_fmac_f32_e32 v2, v37, v121
	v_fmac_f32_e32 v2, v38, v122
	v_fmac_f32_e32 v2, v39, v123
	ds_bpermute_b32 v36, v161, v2
	s_waitcnt lgkmcnt(0)
	v_add_f32_e32 v2, v2, v36
	ds_bpermute_b32 v36, v163, v2
	s_waitcnt lgkmcnt(0)
	v_add_f32_e32 v2, v2, v36
	ds_bpermute_b32 v36, v165, v2
	s_and_saveexec_b64 s[16:17], vcc
	s_cbranch_execz .Lsmp_h0_end
	v_lshlrev_b32_e32 v37, 16, v186
	v_mul_f32_e32 v38, 0xbfb8aa3b, v37
	v_exp_f32_e32 v38, v38
	ds_read_b32 v39, v189 offset:6144
	s_waitcnt lgkmcnt(1)
	v_add_f32_e32 v2, v2, v36
	v_add_f32_e32 v38, 1.0, v38
	v_rcp_f32_e32 v38, v38
	s_waitcnt lgkmcnt(0)
	v_fmac_f32_e32 v2, s12, v39
	v_mul_f32_e32 v36, v38, v37
	v_mul_f32_e32 v2, v36, v2
	ds_write_b32 v189, v2 offset:18688
.Lsmp_h0_end:
	s_or_b64 exec, exec, s[16:17]
	s_add_i32 s13, s13, 4
	s_waitcnt lgkmcnt(0)
	s_mov_b64 s[14:15], 0x8000
	v_lshl_add_u64 v[140:141], v[140:141], 0, s[14:15]
	v_lshl_add_u64 v[144:145], v[144:145], 0, s[14:15]
	v_add_u32_e32 v185, 0x100, v185
	global_load_dwordx4 v[36:39], v[144:145], off offset:16
	global_load_dwordx4 v[40:43], v[144:145], off
	global_load_dwordx4 v[44:47], v[144:145], off offset:-16
	global_load_dwordx4 v[48:51], v[144:145], off offset:-32
	s_lshl_b32 s14, s57, 5
	s_add_u32 s14, s60, s14
	s_addc_u32 s15, s61, 0
	s_nop 0
	s_load_dword s12, s[2:3], 0x4
	s_load_dword s14, s[14:15], 0x4
	v_and_b32_e32 v2, 7, v157
	v_cmp_eq_u32_e32 vcc, 1, v2
	v_add_u32_e32 v189, 0, v185
	s_waitcnt lgkmcnt(0)
	v_mov_b32_e32 v2, s14
	s_mov_b32 s14, 0x3fb8aa3b
	v_mul_f32_e32 v68, 0x3fb8aa3b, v2
	v_fma_f32 v69, v2, s14, -v68
	v_rndne_f32_e32 v70, v68
	v_fmac_f32_e32 v69, 0x32a5705f, v2
	v_sub_f32_e32 v68, v68, v70
	v_add_f32_e32 v68, v68, v69
	v_exp_f32_e32 v68, v68
	v_cvt_i32_f32_e32 v69, v70
	s_mov_b32 s14, 0xc2ce8ed0
	v_cmp_ngt_f32_e64 s[38:39], s14, v2
	s_mov_b32 s14, 0x42b17218
	v_ldexp_f32 v68, v68, v69
	v_cndmask_b32_e64 v68, 0, v68, s[38:39]
	v_cmp_nlt_f32_e64 s[38:39], s14, v2
	s_add_i32 s14, s13, 0
	v_mov_b32_e32 v72, s14
	v_cndmask_b32_e64 v116, v203, v68, s[38:39]
	ds_read2_b32 v[68:69], v72 offset1:8
	ds_read2st64_b32 v[70:71], v189 offset1:8
	ds_read_b128 v[104:107], v137 offset:10240
	ds_read_b128 v[112:115], v137 offset:10256
	ds_read_b128 v[120:123], v137 offset:10272
	ds_read_b128 v[108:111], v137 offset:10288
	s_waitcnt lgkmcnt(5)
	v_mul_f32_e64 v2, v68, -v116
	s_waitcnt lgkmcnt(4)
	v_mul_f32_e32 v156, v68, v70
	v_mul_f32_e64 v68, v69, -v116
	v_mul_f32_e32 v68, 0x3fb8aa3b, v68
	v_exp_f32_e32 v158, v68
	v_mul_f32_e32 v160, v69, v71
	ds_read_b128 v[100:103], v137 offset:10752
	ds_read_b128 v[96:99], v137 offset:10768
	ds_read_b128 v[92:95], v137 offset:10784
	ds_read_b128 v[88:91], v137 offset:10800
	ds_read2_b32 v[68:69], v72 offset0:16 offset1:24
	v_mul_f32_e32 v2, 0x3fb8aa3b, v2
	v_exp_f32_e32 v2, v2
	s_waitcnt lgkmcnt(0)
	v_mul_f32_e64 v70, v68, -v116
	v_mul_f32_e32 v70, 0x3fb8aa3b, v70
	v_exp_f32_e32 v162, v70
	ds_read2st64_b32 v[70:71], v189 offset0:16 offset1:24
	ds_read_b128 v[84:87], v137 offset:11264
	ds_read_b128 v[80:83], v137 offset:11280
	ds_read_b128 v[76:79], v137 offset:11296
	ds_read_b128 v[72:75], v137 offset:11312
	s_waitcnt lgkmcnt(4)
	v_mul_f32_e32 v164, v68, v70
	v_mul_f32_e64 v68, v69, -v116
	v_mul_f32_e32 v68, 0x3fb8aa3b, v68
	v_exp_f32_e32 v166, v68
	v_mul_f32_e32 v168, v69, v71
	ds_read_b128 v[68:71], v137 offset:11776
	ds_read_b128 v[148:151], v137 offset:8192
	ds_read_b128 v[170:173], v137 offset:8208
	ds_read_b128 v[124:127], v137 offset:8224
	ds_read_b128 v[116:119], v137 offset:8240
	ds_read_b128 v[152:155], v137 offset:8704
	ds_read_b128 v[174:177], v137 offset:9216
	s_waitcnt lgkmcnt(5)
	v_pk_mul_f32 v[148:149], v[156:157], v[148:149] op_sel_hi:[0,1]
	v_pk_fma_f32 v[12:13], v[12:13], v[2:3], v[148:149] op_sel_hi:[1,0,1]
	s_waitcnt lgkmcnt(4)
	v_pk_mul_f32 v[170:171], v[156:157], v[170:171] op_sel_hi:[0,1]
	v_fma_f32 v210, v12, v104, 0
	v_fmac_f32_e32 v210, v13, v105
	s_waitcnt lgkmcnt(1)
	v_pk_mul_f32 v[104:105], v[160:161], v[152:153] op_sel_hi:[0,1]
	v_pk_fma_f32 v[152:153], v[12:13], v[158:159], v[104:105] op_sel_hi:[1,0,1]
	v_pk_mul_f32 v[104:105], v[156:157], v[150:151] op_sel_hi:[0,1]
	v_pk_fma_f32 v[14:15], v[14:15], v[2:3], v[104:105] op_sel_hi:[1,0,1]
	v_pk_fma_f32 v[8:9], v[8:9], v[2:3], v[170:171] op_sel_hi:[1,0,1]
	v_fmac_f32_e32 v210, v14, v106
	v_fmac_f32_e32 v210, v15, v107
	v_fmac_f32_e32 v210, v8, v112
	v_fmac_f32_e32 v210, v9, v113
	v_pk_mul_f32 v[112:113], v[156:157], v[172:173] op_sel_hi:[0,1]
	v_pk_fma_f32 v[10:11], v[10:11], v[2:3], v[112:113] op_sel_hi:[1,0,1]
	v_pk_mul_f32 v[124:125], v[156:157], v[124:125] op_sel_hi:[0,1]
	v_fmac_f32_e32 v210, v10, v114
	v_fmac_f32_e32 v210, v11, v115
	v_pk_fma_f32 v[4:5], v[4:5], v[2:3], v[124:125] op_sel_hi:[1,0,1]
	ds_read_b128 v[178:181], v137 offset:9728
	ds_read_b128 v[212:215], v137 offset:9744
	v_fmac_f32_e32 v210, v4, v120
	v_fmac_f32_e32 v210, v5, v121
	v_pk_mul_f32 v[120:121], v[156:157], v[126:127] op_sel_hi:[0,1]
	v_pk_fma_f32 v[6:7], v[6:7], v[2:3], v[120:121] op_sel_hi:[1,0,1]
	v_pk_mul_f32 v[116:117], v[156:157], v[116:117] op_sel_hi:[0,1]
	v_fmac_f32_e32 v210, v6, v122
	v_fmac_f32_e32 v210, v7, v123
	v_pk_fma_f32 v[28:29], v[28:29], v[2:3], v[116:117] op_sel_hi:[1,0,1]
	v_pk_mul_f32 v[104:105], v[160:161], v[154:155] op_sel_hi:[0,1]
	v_fmac_f32_e32 v210, v28, v108
	s_waitcnt lgkmcnt(2)
	v_pk_mul_f32 v[12:13], v[164:165], v[174:175] op_sel_hi:[0,1]
	v_pk_fma_f32 v[154:155], v[14:15], v[158:159], v[104:105] op_sel_hi:[1,0,1]
	v_pk_mul_f32 v[104:105], v[164:165], v[176:177] op_sel_hi:[0,1]
	ds_read_b128 v[174:177], v137 offset:8720
	v_fmac_f32_e32 v210, v29, v109
	v_pk_mul_f32 v[108:109], v[156:157], v[118:119] op_sel_hi:[0,1]
	v_pk_fma_f32 v[148:149], v[152:153], v[162:163], v[12:13] op_sel_hi:[1,0,1]
	s_waitcnt lgkmcnt(2)
	v_pk_mul_f32 v[12:13], v[168:169], v[178:179] op_sel_hi:[0,1]
	v_pk_mul_f32 v[14:15], v[168:169], v[180:181] op_sel_hi:[0,1]
	ds_read_b128 v[178:181], v137 offset:9232
	v_pk_fma_f32 v[30:31], v[30:31], v[2:3], v[108:109] op_sel_hi:[1,0,1]
	s_waitcnt lgkmcnt(1)
	v_pk_mul_f32 v[170:171], v[160:161], v[174:175] op_sel_hi:[0,1]
	v_fmac_f32_e32 v210, v30, v110
	v_fmac_f32_e32 v210, v31, v111
	ds_bpermute_b32 v2, v161, v210
	v_pk_mul_f32 v[112:113], v[160:161], v[176:177] op_sel_hi:[0,1]
	v_pk_fma_f32 v[174:175], v[8:9], v[158:159], v[170:171] op_sel_hi:[1,0,1]
	s_waitcnt lgkmcnt(1)
	v_pk_mul_f32 v[170:171], v[164:165], v[178:179] op_sel_hi:[0,1]
	v_pk_fma_f32 v[176:177], v[10:11], v[158:159], v[112:113] op_sel_hi:[1,0,1]
	v_pk_mul_f32 v[112:113], v[164:165], v[180:181] op_sel_hi:[0,1]
	ds_read_b128 v[178:181], v137 offset:8736
	v_pk_mul_f32 v[8:9], v[168:169], v[212:213] op_sel_hi:[0,1]
	v_pk_mul_f32 v[10:11], v[168:169], v[214:215] op_sel_hi:[0,1]
	ds_read_b128 v[212:215], v137 offset:9248
	ds_read_b128 v[216:219], v137 offset:9760
	ds_read_b128 v[220:223], v137 offset:9776
	s_waitcnt lgkmcnt(4)
	v_add_f32_e32 v2, v210, v2
	ds_bpermute_b32 v110, v163, v2
	s_waitcnt lgkmcnt(4)
	v_pk_mul_f32 v[124:125], v[160:161], v[178:179] op_sel_hi:[0,1]
	v_pk_mul_f32 v[120:121], v[160:161], v[180:181] op_sel_hi:[0,1]
	v_pk_fma_f32 v[178:179], v[4:5], v[158:159], v[124:125] op_sel_hi:[1,0,1]
	s_waitcnt lgkmcnt(3)
	v_pk_mul_f32 v[124:125], v[164:165], v[212:213] op_sel_hi:[0,1]
	v_pk_fma_f32 v[180:181], v[6:7], v[158:159], v[120:121] op_sel_hi:[1,0,1]
	v_pk_mul_f32 v[120:121], v[164:165], v[214:215] op_sel_hi:[0,1]
	ds_read_b128 v[212:215], v137 offset:8752
	s_waitcnt lgkmcnt(3)
	v_pk_mul_f32 v[4:5], v[168:169], v[216:217] op_sel_hi:[0,1]
	v_pk_mul_f32 v[6:7], v[168:169], v[218:219] op_sel_hi:[0,1]
	ds_read_b128 v[216:219], v137 offset:9264
	s_waitcnt lgkmcnt(2)
	v_add_f32_e32 v2, v2, v110
	v_pk_fma_f32 v[150:151], v[154:155], v[162:163], v[104:105] op_sel_hi:[1,0,1]
	ds_read_b128 v[104:107], v137 offset:11792
	v_pk_fma_f32 v[172:173], v[176:177], v[162:163], v[112:113] op_sel_hi:[1,0,1]
	ds_read_b128 v[112:115], v137 offset:11808
	v_pk_fma_f32 v[126:127], v[180:181], v[162:163], v[120:121] op_sel_hi:[1,0,1]
	ds_read_b128 v[120:123], v137 offset:11824
	ds_bpermute_b32 v110, v165, v2
	s_waitcnt lgkmcnt(5)
	v_pk_mul_f32 v[116:117], v[160:161], v[212:213] op_sel_hi:[0,1]
	v_pk_mul_f32 v[108:109], v[160:161], v[214:215] op_sel_hi:[0,1]
	v_pk_fma_f32 v[182:183], v[28:29], v[158:159], v[116:117] op_sel_hi:[1,0,1]
	s_waitcnt lgkmcnt(4)
	v_pk_mul_f32 v[116:117], v[164:165], v[216:217] op_sel_hi:[0,1]
	v_pk_fma_f32 v[118:119], v[30:31], v[158:159], v[108:109] op_sel_hi:[1,0,1]
	v_pk_mul_f32 v[108:109], v[164:165], v[218:219] op_sel_hi:[0,1]
	v_pk_fma_f32 v[170:171], v[174:175], v[162:163], v[170:171] op_sel_hi:[1,0,1]
	v_pk_fma_f32 v[124:125], v[178:179], v[162:163], v[124:125] op_sel_hi:[1,0,1]
	v_pk_fma_f32 v[116:117], v[182:183], v[162:163], v[116:117] op_sel_hi:[1,0,1]
	v_pk_mul_f32 v[28:29], v[168:169], v[220:221] op_sel_hi:[0,1]
	v_pk_fma_f32 v[108:109], v[118:119], v[162:163], v[108:109] op_sel_hi:[1,0,1]
	v_pk_mul_f32 v[30:31], v[168:169], v[222:223] op_sel_hi:[0,1]
	v_pk_fma_f32 v[12:13], v[148:149], v[166:167], v[12:13] op_sel_hi:[1,0,1]
	v_pk_fma_f32 v[14:15], v[150:151], v[166:167], v[14:15] op_sel_hi:[1,0,1]
	v_pk_fma_f32 v[8:9], v[170:171], v[166:167], v[8:9] op_sel_hi:[1,0,1]
	v_pk_fma_f32 v[10:11], v[172:173], v[166:167], v[10:11] op_sel_hi:[1,0,1]
	v_pk_fma_f32 v[4:5], v[124:125], v[166:167], v[4:5] op_sel_hi:[1,0,1]
	v_pk_fma_f32 v[6:7], v[126:127], v[166:167], v[6:7] op_sel_hi:[1,0,1]
	v_pk_fma_f32 v[28:29], v[116:117], v[166:167], v[28:29] op_sel_hi:[1,0,1]
	v_pk_fma_f32 v[30:31], v[108:109], v[166:167], v[30:31] op_sel_hi:[1,0,1]
	global_store_dwordx4 v[140:141], v[12:15], off offset:-32
	global_store_dwordx4 v[140:141], v[8:11], off offset:-16
	global_store_dwordx4 v[140:141], v[4:7], off
	global_store_dwordx4 v[140:141], v[28:31], off offset:16
	s_and_saveexec_b64 s[16:17], vcc
	s_cbranch_execz .Lsmp_h1_743
	v_lshlrev_b32_e32 v111, 16, v209
	v_mul_f32_e32 v156, 0xbfb8aa3b, v111
	v_exp_f32_e32 v156, v156
	ds_read_b32 v158, v189
	s_waitcnt lgkmcnt(1)
	v_add_f32_e32 v2, v2, v110
	v_add_f32_e32 v156, 1.0, v156
	v_rcp_f32_e32 v156, v156
	s_waitcnt lgkmcnt(0)
	v_fmac_f32_e32 v2, s12, v158
	v_mul_f32_e32 v110, v156, v111
	v_mul_f32_e32 v2, v110, v2
	ds_write_b32 v189, v2 offset:12544

.Lsmp_h1_747:
	s_or_b64 exec, exec, s[16:17]
	v_fma_f32 v2, v12, v68, 0
	v_fmac_f32_e32 v2, v13, v69
	v_fmac_f32_e32 v2, v14, v70
	v_fmac_f32_e32 v2, v15, v71
	v_fmac_f32_e32 v2, v8, v104
	v_fmac_f32_e32 v2, v9, v105
	v_fmac_f32_e32 v2, v10, v106
	v_fmac_f32_e32 v2, v11, v107
	v_fmac_f32_e32 v2, v4, v112
	v_fmac_f32_e32 v2, v5, v113
	v_fmac_f32_e32 v2, v6, v114
	v_fmac_f32_e32 v2, v7, v115
	v_fmac_f32_e32 v2, v28, v120
	v_fmac_f32_e32 v2, v29, v121
	v_fmac_f32_e32 v2, v30, v122
	v_fmac_f32_e32 v2, v31, v123
	ds_bpermute_b32 v28, v161, v2
	s_waitcnt lgkmcnt(0)
	v_add_f32_e32 v2, v2, v28
	ds_bpermute_b32 v28, v163, v2
	s_waitcnt lgkmcnt(0)
	v_add_f32_e32 v2, v2, v28
	ds_bpermute_b32 v28, v165, v2
	s_and_saveexec_b64 s[16:17], vcc
	s_cbranch_execz .Lsmp_h1_end
	v_lshlrev_b32_e32 v29, 16, v186
	v_mul_f32_e32 v30, 0xbfb8aa3b, v29
	v_exp_f32_e32 v30, v30
	ds_read_b32 v31, v189 offset:6144
	s_waitcnt lgkmcnt(1)
	v_add_f32_e32 v2, v2, v28
	v_add_f32_e32 v30, 1.0, v30
	v_rcp_f32_e32 v30, v30
	s_waitcnt lgkmcnt(0)
	v_fmac_f32_e32 v2, s12, v31
	v_mul_f32_e32 v28, v30, v29
	v_mul_f32_e32 v2, v28, v2
	ds_write_b32 v189, v2 offset:18688
.Lsmp_h1_end:
	s_or_b64 exec, exec, s[16:17]
	s_add_i32 s13, s13, 4
	s_waitcnt lgkmcnt(0)
	s_mov_b64 s[14:15], 0x8000
	v_lshl_add_u64 v[140:141], v[140:141], 0, s[14:15]
	v_lshl_add_u64 v[144:145], v[144:145], 0, s[14:15]
	v_add_u32_e32 v185, 0x100, v185
	global_load_dwordx4 v[28:31], v[144:145], off offset:16
	global_load_dwordx4 v[4:7], v[144:145], off
	global_load_dwordx4 v[8:11], v[144:145], off offset:-16
	global_load_dwordx4 v[12:15], v[144:145], off offset:-32
	s_lshl_b32 s14, s57, 5
	s_add_u32 s14, s60, s14
	s_addc_u32 s15, s61, 0
	s_nop 0
	s_load_dword s12, s[2:3], 0x8
	s_load_dword s14, s[14:15], 0x8
	v_and_b32_e32 v2, 7, v157
	v_cmp_eq_u32_e32 vcc, 2, v2
	v_add_u32_e32 v189, 0, v185
	s_waitcnt lgkmcnt(0)
	v_mov_b32_e32 v2, s14
	s_mov_b32 s14, 0x3fb8aa3b
	v_mul_f32_e32 v68, 0x3fb8aa3b, v2
	v_fma_f32 v69, v2, s14, -v68
	v_rndne_f32_e32 v70, v68
	v_fmac_f32_e32 v69, 0x32a5705f, v2
	v_sub_f32_e32 v68, v68, v70
	v_add_f32_e32 v68, v68, v69
	v_exp_f32_e32 v68, v68
	v_cvt_i32_f32_e32 v69, v70
	s_mov_b32 s14, 0xc2ce8ed0
	v_cmp_ngt_f32_e64 s[38:39], s14, v2
	s_mov_b32 s14, 0x42b17218
	v_ldexp_f32 v68, v68, v69
	v_cndmask_b32_e64 v68, 0, v68, s[38:39]
	v_cmp_nlt_f32_e64 s[38:39], s14, v2
	s_add_i32 s14, s13, 0
	v_mov_b32_e32 v72, s14
	v_cndmask_b32_e64 v116, v203, v68, s[38:39]
	ds_read2_b32 v[68:69], v72 offset1:8
	ds_read2st64_b32 v[70:71], v189 offset1:8
	ds_read_b128 v[104:107], v137 offset:10240
	ds_read_b128 v[112:115], v137 offset:10256
	ds_read_b128 v[120:123], v137 offset:10272
	ds_read_b128 v[108:111], v137 offset:10288
	s_waitcnt lgkmcnt(5)
	v_mul_f32_e64 v2, v68, -v116
	s_waitcnt lgkmcnt(4)
	v_mul_f32_e32 v156, v68, v70
	v_mul_f32_e64 v68, v69, -v116
	v_mul_f32_e32 v68, 0x3fb8aa3b, v68
	v_exp_f32_e32 v158, v68
	v_mul_f32_e32 v160, v69, v71
	ds_read_b128 v[100:103], v137 offset:10752
	ds_read_b128 v[96:99], v137 offset:10768
	ds_read_b128 v[92:95], v137 offset:10784
	ds_read_b128 v[88:91], v137 offset:10800
	ds_read2_b32 v[68:69], v72 offset0:16 offset1:24
	v_mul_f32_e32 v2, 0x3fb8aa3b, v2
	v_exp_f32_e32 v2, v2
	s_waitcnt lgkmcnt(0)
	v_mul_f32_e64 v70, v68, -v116
	v_mul_f32_e32 v70, 0x3fb8aa3b, v70
	v_exp_f32_e32 v162, v70
	ds_read2st64_b32 v[70:71], v189 offset0:16 offset1:24
	ds_read_b128 v[84:87], v137 offset:11264
	ds_read_b128 v[80:83], v137 offset:11280
	ds_read_b128 v[76:79], v137 offset:11296
	ds_read_b128 v[72:75], v137 offset:11312
	s_waitcnt lgkmcnt(4)
	v_mul_f32_e32 v164, v68, v70
	v_mul_f32_e64 v68, v69, -v116
	v_mul_f32_e32 v68, 0x3fb8aa3b, v68
	v_exp_f32_e32 v166, v68
	v_mul_f32_e32 v168, v69, v71
	ds_read_b128 v[68:71], v137 offset:11776
	ds_read_b128 v[148:151], v137 offset:8192
	ds_read_b128 v[170:173], v137 offset:8208
	ds_read_b128 v[124:127], v137 offset:8224
	ds_read_b128 v[116:119], v137 offset:8240
	ds_read_b128 v[152:155], v137 offset:8704
	ds_read_b128 v[174:177], v137 offset:9216
	s_waitcnt lgkmcnt(5)
	v_pk_mul_f32 v[148:149], v[156:157], v[148:149] op_sel_hi:[0,1]
	v_pk_fma_f32 v[16:17], v[16:17], v[2:3], v[148:149] op_sel_hi:[1,0,1]
	s_waitcnt lgkmcnt(4)
	v_pk_mul_f32 v[170:171], v[156:157], v[170:171] op_sel_hi:[0,1]
	v_fma_f32 v210, v16, v104, 0
	v_fmac_f32_e32 v210, v17, v105
	s_waitcnt lgkmcnt(1)
	v_pk_mul_f32 v[104:105], v[160:161], v[152:153] op_sel_hi:[0,1]
	v_pk_fma_f32 v[152:153], v[16:17], v[158:159], v[104:105] op_sel_hi:[1,0,1]
	v_pk_mul_f32 v[104:105], v[156:157], v[150:151] op_sel_hi:[0,1]
	v_pk_fma_f32 v[18:19], v[18:19], v[2:3], v[104:105] op_sel_hi:[1,0,1]
	v_pk_fma_f32 v[32:33], v[32:33], v[2:3], v[170:171] op_sel_hi:[1,0,1]
	v_fmac_f32_e32 v210, v18, v106
	v_fmac_f32_e32 v210, v19, v107
	v_fmac_f32_e32 v210, v32, v112
	v_fmac_f32_e32 v210, v33, v113
	v_pk_mul_f32 v[112:113], v[156:157], v[172:173] op_sel_hi:[0,1]
	v_pk_fma_f32 v[34:35], v[34:35], v[2:3], v[112:113] op_sel_hi:[1,0,1]
	v_pk_mul_f32 v[124:125], v[156:157], v[124:125] op_sel_hi:[0,1]
	v_fmac_f32_e32 v210, v34, v114
	v_fmac_f32_e32 v210, v35, v115
	v_pk_fma_f32 v[24:25], v[24:25], v[2:3], v[124:125] op_sel_hi:[1,0,1]
	ds_read_b128 v[178:181], v137 offset:9728
	ds_read_b128 v[212:215], v137 offset:9744
	v_fmac_f32_e32 v210, v24, v120
	v_fmac_f32_e32 v210, v25, v121
	v_pk_mul_f32 v[120:121], v[156:157], v[126:127] op_sel_hi:[0,1]
	v_pk_fma_f32 v[26:27], v[26:27], v[2:3], v[120:121] op_sel_hi:[1,0,1]
	v_pk_mul_f32 v[116:117], v[156:157], v[116:117] op_sel_hi:[0,1]
	v_fmac_f32_e32 v210, v26, v122
	v_fmac_f32_e32 v210, v27, v123
	v_pk_fma_f32 v[20:21], v[20:21], v[2:3], v[116:117] op_sel_hi:[1,0,1]
	v_pk_mul_f32 v[104:105], v[160:161], v[154:155] op_sel_hi:[0,1]
	v_fmac_f32_e32 v210, v20, v108
	s_waitcnt lgkmcnt(2)
	v_pk_mul_f32 v[16:17], v[164:165], v[174:175] op_sel_hi:[0,1]
	v_pk_fma_f32 v[154:155], v[18:19], v[158:159], v[104:105] op_sel_hi:[1,0,1]
	v_pk_mul_f32 v[104:105], v[164:165], v[176:177] op_sel_hi:[0,1]
	ds_read_b128 v[174:177], v137 offset:8720
	v_fmac_f32_e32 v210, v21, v109
	v_pk_mul_f32 v[108:109], v[156:157], v[118:119] op_sel_hi:[0,1]
	v_pk_fma_f32 v[148:149], v[152:153], v[162:163], v[16:17] op_sel_hi:[1,0,1]
	s_waitcnt lgkmcnt(2)
	v_pk_mul_f32 v[16:17], v[168:169], v[178:179] op_sel_hi:[0,1]
	v_pk_mul_f32 v[18:19], v[168:169], v[180:181] op_sel_hi:[0,1]
	ds_read_b128 v[178:181], v137 offset:9232
	v_pk_fma_f32 v[22:23], v[22:23], v[2:3], v[108:109] op_sel_hi:[1,0,1]
	s_waitcnt lgkmcnt(1)
	v_pk_mul_f32 v[170:171], v[160:161], v[174:175] op_sel_hi:[0,1]
	v_fmac_f32_e32 v210, v22, v110
	v_fmac_f32_e32 v210, v23, v111
	ds_bpermute_b32 v2, v161, v210
	v_pk_mul_f32 v[112:113], v[160:161], v[176:177] op_sel_hi:[0,1]
	v_pk_fma_f32 v[174:175], v[32:33], v[158:159], v[170:171] op_sel_hi:[1,0,1]
	s_waitcnt lgkmcnt(1)
	v_pk_mul_f32 v[170:171], v[164:165], v[178:179] op_sel_hi:[0,1]
	v_pk_fma_f32 v[176:177], v[34:35], v[158:159], v[112:113] op_sel_hi:[1,0,1]
	v_pk_mul_f32 v[112:113], v[164:165], v[180:181] op_sel_hi:[0,1]
	ds_read_b128 v[178:181], v137 offset:8736
	v_pk_mul_f32 v[32:33], v[168:169], v[212:213] op_sel_hi:[0,1]
	v_pk_mul_f32 v[34:35], v[168:169], v[214:215] op_sel_hi:[0,1]
	ds_read_b128 v[212:215], v137 offset:9248
	ds_read_b128 v[216:219], v137 offset:9760
	ds_read_b128 v[220:223], v137 offset:9776
	s_waitcnt lgkmcnt(4)
	v_add_f32_e32 v2, v210, v2
	ds_bpermute_b32 v110, v163, v2
	s_waitcnt lgkmcnt(4)
	v_pk_mul_f32 v[124:125], v[160:161], v[178:179] op_sel_hi:[0,1]
	v_pk_mul_f32 v[120:121], v[160:161], v[180:181] op_sel_hi:[0,1]
	v_pk_fma_f32 v[178:179], v[24:25], v[158:159], v[124:125] op_sel_hi:[1,0,1]
	s_waitcnt lgkmcnt(3)
	v_pk_mul_f32 v[124:125], v[164:165], v[212:213] op_sel_hi:[0,1]
	v_pk_fma_f32 v[180:181], v[26:27], v[158:159], v[120:121] op_sel_hi:[1,0,1]
	v_pk_mul_f32 v[120:121], v[164:165], v[214:215] op_sel_hi:[0,1]
	ds_read_b128 v[212:215], v137 offset:8752
	s_waitcnt lgkmcnt(3)
	v_pk_mul_f32 v[24:25], v[168:169], v[216:217] op_sel_hi:[0,1]
	v_pk_mul_f32 v[26:27], v[168:169], v[218:219] op_sel_hi:[0,1]
	ds_read_b128 v[216:219], v137 offset:9264
	s_waitcnt lgkmcnt(2)
	v_add_f32_e32 v2, v2, v110
	v_pk_fma_f32 v[150:151], v[154:155], v[162:163], v[104:105] op_sel_hi:[1,0,1]
	ds_read_b128 v[104:107], v137 offset:11792
	v_pk_fma_f32 v[172:173], v[176:177], v[162:163], v[112:113] op_sel_hi:[1,0,1]
	ds_read_b128 v[112:115], v137 offset:11808
	v_pk_fma_f32 v[126:127], v[180:181], v[162:163], v[120:121] op_sel_hi:[1,0,1]
	ds_read_b128 v[120:123], v137 offset:11824
	ds_bpermute_b32 v110, v165, v2
	s_waitcnt lgkmcnt(5)
	v_pk_mul_f32 v[116:117], v[160:161], v[212:213] op_sel_hi:[0,1]
	v_pk_mul_f32 v[108:109], v[160:161], v[214:215] op_sel_hi:[0,1]
	v_pk_fma_f32 v[182:183], v[20:21], v[158:159], v[116:117] op_sel_hi:[1,0,1]
	s_waitcnt lgkmcnt(4)
	v_pk_mul_f32 v[116:117], v[164:165], v[216:217] op_sel_hi:[0,1]
	v_pk_fma_f32 v[118:119], v[22:23], v[158:159], v[108:109] op_sel_hi:[1,0,1]
	v_pk_mul_f32 v[108:109], v[164:165], v[218:219] op_sel_hi:[0,1]
	v_pk_fma_f32 v[170:171], v[174:175], v[162:163], v[170:171] op_sel_hi:[1,0,1]
	v_pk_fma_f32 v[124:125], v[178:179], v[162:163], v[124:125] op_sel_hi:[1,0,1]
	v_pk_fma_f32 v[116:117], v[182:183], v[162:163], v[116:117] op_sel_hi:[1,0,1]
	v_pk_mul_f32 v[20:21], v[168:169], v[220:221] op_sel_hi:[0,1]
	v_pk_fma_f32 v[108:109], v[118:119], v[162:163], v[108:109] op_sel_hi:[1,0,1]
	v_pk_mul_f32 v[22:23], v[168:169], v[222:223] op_sel_hi:[0,1]
	v_pk_fma_f32 v[16:17], v[148:149], v[166:167], v[16:17] op_sel_hi:[1,0,1]
	v_pk_fma_f32 v[18:19], v[150:151], v[166:167], v[18:19] op_sel_hi:[1,0,1]
	v_pk_fma_f32 v[32:33], v[170:171], v[166:167], v[32:33] op_sel_hi:[1,0,1]
	v_pk_fma_f32 v[34:35], v[172:173], v[166:167], v[34:35] op_sel_hi:[1,0,1]
	v_pk_fma_f32 v[24:25], v[124:125], v[166:167], v[24:25] op_sel_hi:[1,0,1]
	v_pk_fma_f32 v[26:27], v[126:127], v[166:167], v[26:27] op_sel_hi:[1,0,1]
	v_pk_fma_f32 v[20:21], v[116:117], v[166:167], v[20:21] op_sel_hi:[1,0,1]
	v_pk_fma_f32 v[22:23], v[108:109], v[166:167], v[22:23] op_sel_hi:[1,0,1]
	global_store_dwordx4 v[140:141], v[16:19], off offset:-32
	global_store_dwordx4 v[140:141], v[32:35], off offset:-16
	global_store_dwordx4 v[140:141], v[24:27], off
	global_store_dwordx4 v[140:141], v[20:23], off offset:16
	s_and_saveexec_b64 s[16:17], vcc
	s_cbranch_execz .Lsmp_h2_743
	v_lshlrev_b32_e32 v111, 16, v209
	v_mul_f32_e32 v156, 0xbfb8aa3b, v111
	v_exp_f32_e32 v156, v156
	ds_read_b32 v158, v189
	s_waitcnt lgkmcnt(1)
	v_add_f32_e32 v2, v2, v110
	v_add_f32_e32 v156, 1.0, v156
	v_rcp_f32_e32 v156, v156
	s_waitcnt lgkmcnt(0)
	v_fmac_f32_e32 v2, s12, v158
	v_mul_f32_e32 v110, v156, v111
	v_mul_f32_e32 v2, v110, v2
	ds_write_b32 v189, v2 offset:12544

.Lsmp_h2_747:
	s_or_b64 exec, exec, s[16:17]
	v_fma_f32 v2, v16, v68, 0
	v_fmac_f32_e32 v2, v17, v69
	v_fmac_f32_e32 v2, v18, v70
	v_fmac_f32_e32 v2, v19, v71
	v_fmac_f32_e32 v2, v32, v104
	v_fmac_f32_e32 v2, v33, v105
	v_fmac_f32_e32 v2, v34, v106
	v_fmac_f32_e32 v2, v35, v107
	v_fmac_f32_e32 v2, v24, v112
	v_fmac_f32_e32 v2, v25, v113
	v_fmac_f32_e32 v2, v26, v114
	v_fmac_f32_e32 v2, v27, v115
	v_fmac_f32_e32 v2, v20, v120
	v_fmac_f32_e32 v2, v21, v121
	v_fmac_f32_e32 v2, v22, v122
	v_fmac_f32_e32 v2, v23, v123
	ds_bpermute_b32 v20, v161, v2
	s_waitcnt lgkmcnt(0)
	v_add_f32_e32 v2, v2, v20
	ds_bpermute_b32 v20, v163, v2
	s_waitcnt lgkmcnt(0)
	v_add_f32_e32 v2, v2, v20
	ds_bpermute_b32 v20, v165, v2
	s_and_saveexec_b64 s[16:17], vcc
	s_cbranch_execz .Lsmp_h2_end
	v_lshlrev_b32_e32 v21, 16, v186
	v_mul_f32_e32 v22, 0xbfb8aa3b, v21
	v_exp_f32_e32 v22, v22
	ds_read_b32 v23, v189 offset:6144
	s_waitcnt lgkmcnt(1)
	v_add_f32_e32 v2, v2, v20
	v_add_f32_e32 v22, 1.0, v22
	v_rcp_f32_e32 v22, v22
	s_waitcnt lgkmcnt(0)
	v_fmac_f32_e32 v2, s12, v23
	v_mul_f32_e32 v20, v22, v21
	v_mul_f32_e32 v2, v20, v2
	ds_write_b32 v189, v2 offset:18688
.Lsmp_h2_end:
	s_or_b64 exec, exec, s[16:17]
	s_add_i32 s13, s13, 4
	s_waitcnt lgkmcnt(0)
	s_mov_b64 s[14:15], 0x8000
	v_lshl_add_u64 v[140:141], v[140:141], 0, s[14:15]
	v_lshl_add_u64 v[144:145], v[144:145], 0, s[14:15]
	v_add_u32_e32 v185, 0x100, v185
	global_load_dwordx4 v[20:23], v[144:145], off offset:16
	global_load_dwordx4 v[24:27], v[144:145], off
	global_load_dwordx4 v[32:35], v[144:145], off offset:-16
	global_load_dwordx4 v[16:19], v[144:145], off offset:-32
	s_lshl_b32 s14, s57, 5
	s_add_u32 s14, s60, s14
	s_addc_u32 s15, s61, 0
	s_nop 0
	s_load_dword s12, s[2:3], 0xc
	s_load_dword s14, s[14:15], 0xc
	v_and_b32_e32 v2, 7, v157
	v_cmp_eq_u32_e32 vcc, 3, v2
	v_add_u32_e32 v189, 0, v185
	s_waitcnt lgkmcnt(0)
	v_mov_b32_e32 v2, s14
	s_mov_b32 s14, 0x3fb8aa3b
	s_waitcnt vmcnt(24)
	v_mul_f32_e32 v68, 0x3fb8aa3b, v2
	v_fma_f32 v69, v2, s14, -v68
	v_rndne_f32_e32 v70, v68
	v_fmac_f32_e32 v69, 0x32a5705f, v2
	v_sub_f32_e32 v68, v68, v70
	v_add_f32_e32 v68, v68, v69
	v_exp_f32_e32 v68, v68
	v_cvt_i32_f32_e32 v69, v70
	s_mov_b32 s14, 0xc2ce8ed0
	v_cmp_ngt_f32_e64 s[38:39], s14, v2
	s_mov_b32 s14, 0x42b17218
	v_ldexp_f32 v68, v68, v69
	v_cndmask_b32_e64 v68, 0, v68, s[38:39]
	v_cmp_nlt_f32_e64 s[38:39], s14, v2
	s_add_i32 s14, s13, 0
	v_mov_b32_e32 v72, s14
	v_cndmask_b32_e64 v116, v203, v68, s[38:39]
	ds_read2_b32 v[68:69], v72 offset1:8
	ds_read2st64_b32 v[70:71], v189 offset1:8
	ds_read_b128 v[104:107], v137 offset:10240
	ds_read_b128 v[112:115], v137 offset:10256
	ds_read_b128 v[120:123], v137 offset:10272
	ds_read_b128 v[108:111], v137 offset:10288
	s_waitcnt lgkmcnt(5)
	v_mul_f32_e64 v2, v68, -v116
	s_waitcnt lgkmcnt(4)
	v_mul_f32_e32 v156, v68, v70
	v_mul_f32_e64 v68, v69, -v116
	v_mul_f32_e32 v68, 0x3fb8aa3b, v68
	v_exp_f32_e32 v158, v68
	v_mul_f32_e32 v160, v69, v71
	ds_read_b128 v[100:103], v137 offset:10752
	ds_read_b128 v[96:99], v137 offset:10768
	ds_read_b128 v[92:95], v137 offset:10784
	ds_read_b128 v[88:91], v137 offset:10800
	ds_read2_b32 v[68:69], v72 offset0:16 offset1:24
	v_mul_f32_e32 v2, 0x3fb8aa3b, v2
	v_exp_f32_e32 v2, v2
	s_waitcnt lgkmcnt(0)
	v_mul_f32_e64 v70, v68, -v116
	v_mul_f32_e32 v70, 0x3fb8aa3b, v70
	v_exp_f32_e32 v162, v70
	ds_read2st64_b32 v[70:71], v189 offset0:16 offset1:24
	ds_read_b128 v[84:87], v137 offset:11264
	ds_read_b128 v[80:83], v137 offset:11280
	ds_read_b128 v[76:79], v137 offset:11296
	ds_read_b128 v[72:75], v137 offset:11312
	s_waitcnt lgkmcnt(4)
	v_mul_f32_e32 v164, v68, v70
	v_mul_f32_e64 v68, v69, -v116
	v_mul_f32_e32 v68, 0x3fb8aa3b, v68
	v_exp_f32_e32 v166, v68
	v_mul_f32_e32 v168, v69, v71
	ds_read_b128 v[68:71], v137 offset:11776
	ds_read_b128 v[148:151], v137 offset:8192
	ds_read_b128 v[170:173], v137 offset:8208
	ds_read_b128 v[124:127], v137 offset:8224
	ds_read_b128 v[116:119], v137 offset:8240
	ds_read_b128 v[152:155], v137 offset:8704
	ds_read_b128 v[174:177], v137 offset:9216
	s_waitcnt lgkmcnt(5)
	v_pk_mul_f32 v[148:149], v[156:157], v[148:149] op_sel_hi:[0,1]
	v_pk_fma_f32 v[64:65], v[64:65], v[2:3], v[148:149] op_sel_hi:[1,0,1]
	s_waitcnt lgkmcnt(4)
	v_pk_mul_f32 v[170:171], v[156:157], v[170:171] op_sel_hi:[0,1]
	v_fma_f32 v210, v64, v104, 0
	v_fmac_f32_e32 v210, v65, v105
	s_waitcnt lgkmcnt(1)
	v_pk_mul_f32 v[104:105], v[160:161], v[152:153] op_sel_hi:[0,1]
	v_pk_fma_f32 v[152:153], v[64:65], v[158:159], v[104:105] op_sel_hi:[1,0,1]
	v_pk_mul_f32 v[104:105], v[156:157], v[150:151] op_sel_hi:[0,1]
	v_pk_fma_f32 v[66:67], v[66:67], v[2:3], v[104:105] op_sel_hi:[1,0,1]
	v_pk_fma_f32 v[60:61], v[60:61], v[2:3], v[170:171] op_sel_hi:[1,0,1]
	v_fmac_f32_e32 v210, v66, v106
	v_fmac_f32_e32 v210, v67, v107
	v_fmac_f32_e32 v210, v60, v112
	v_fmac_f32_e32 v210, v61, v113
	v_pk_mul_f32 v[112:113], v[156:157], v[172:173] op_sel_hi:[0,1]
	v_pk_fma_f32 v[62:63], v[62:63], v[2:3], v[112:113] op_sel_hi:[1,0,1]
	v_pk_mul_f32 v[124:125], v[156:157], v[124:125] op_sel_hi:[0,1]
	v_fmac_f32_e32 v210, v62, v114
	v_fmac_f32_e32 v210, v63, v115
	v_pk_fma_f32 v[56:57], v[56:57], v[2:3], v[124:125] op_sel_hi:[1,0,1]
	ds_read_b128 v[178:181], v137 offset:9728
	ds_read_b128 v[212:215], v137 offset:9744
	v_fmac_f32_e32 v210, v56, v120
	v_fmac_f32_e32 v210, v57, v121
	v_pk_mul_f32 v[120:121], v[156:157], v[126:127] op_sel_hi:[0,1]
	v_pk_fma_f32 v[58:59], v[58:59], v[2:3], v[120:121] op_sel_hi:[1,0,1]
	v_pk_mul_f32 v[116:117], v[156:157], v[116:117] op_sel_hi:[0,1]
	v_fmac_f32_e32 v210, v58, v122
	v_fmac_f32_e32 v210, v59, v123
	v_pk_fma_f32 v[52:53], v[52:53], v[2:3], v[116:117] op_sel_hi:[1,0,1]
	v_pk_mul_f32 v[104:105], v[160:161], v[154:155] op_sel_hi:[0,1]
	v_fmac_f32_e32 v210, v52, v108
	s_waitcnt lgkmcnt(2)
	v_pk_mul_f32 v[64:65], v[164:165], v[174:175] op_sel_hi:[0,1]
	v_pk_fma_f32 v[154:155], v[66:67], v[158:159], v[104:105] op_sel_hi:[1,0,1]
	v_pk_mul_f32 v[104:105], v[164:165], v[176:177] op_sel_hi:[0,1]
	ds_read_b128 v[174:177], v137 offset:8720
	v_fmac_f32_e32 v210, v53, v109
	v_pk_mul_f32 v[108:109], v[156:157], v[118:119] op_sel_hi:[0,1]
	v_pk_fma_f32 v[148:149], v[152:153], v[162:163], v[64:65] op_sel_hi:[1,0,1]
	s_waitcnt lgkmcnt(2)
	v_pk_mul_f32 v[64:65], v[168:169], v[178:179] op_sel_hi:[0,1]
	v_pk_mul_f32 v[66:67], v[168:169], v[180:181] op_sel_hi:[0,1]
	ds_read_b128 v[178:181], v137 offset:9232
	v_pk_fma_f32 v[54:55], v[54:55], v[2:3], v[108:109] op_sel_hi:[1,0,1]
	s_waitcnt lgkmcnt(1)
	v_pk_mul_f32 v[170:171], v[160:161], v[174:175] op_sel_hi:[0,1]
	v_fmac_f32_e32 v210, v54, v110
	v_fmac_f32_e32 v210, v55, v111
	ds_bpermute_b32 v2, v161, v210
	v_pk_mul_f32 v[112:113], v[160:161], v[176:177] op_sel_hi:[0,1]
	v_pk_fma_f32 v[174:175], v[60:61], v[158:159], v[170:171] op_sel_hi:[1,0,1]
	s_waitcnt lgkmcnt(1)
	v_pk_mul_f32 v[170:171], v[164:165], v[178:179] op_sel_hi:[0,1]
	v_pk_fma_f32 v[176:177], v[62:63], v[158:159], v[112:113] op_sel_hi:[1,0,1]
	v_pk_mul_f32 v[112:113], v[164:165], v[180:181] op_sel_hi:[0,1]
	ds_read_b128 v[178:181], v137 offset:8736
	v_pk_mul_f32 v[60:61], v[168:169], v[212:213] op_sel_hi:[0,1]
	v_pk_mul_f32 v[62:63], v[168:169], v[214:215] op_sel_hi:[0,1]
	ds_read_b128 v[212:215], v137 offset:9248
	ds_read_b128 v[216:219], v137 offset:9760
	ds_read_b128 v[220:223], v137 offset:9776
	s_waitcnt lgkmcnt(4)
	v_add_f32_e32 v2, v210, v2
	ds_bpermute_b32 v110, v163, v2
	s_waitcnt lgkmcnt(4)
	v_pk_mul_f32 v[124:125], v[160:161], v[178:179] op_sel_hi:[0,1]
	v_pk_mul_f32 v[120:121], v[160:161], v[180:181] op_sel_hi:[0,1]
	v_pk_fma_f32 v[178:179], v[56:57], v[158:159], v[124:125] op_sel_hi:[1,0,1]
	s_waitcnt lgkmcnt(3)
	v_pk_mul_f32 v[124:125], v[164:165], v[212:213] op_sel_hi:[0,1]
	v_pk_fma_f32 v[180:181], v[58:59], v[158:159], v[120:121] op_sel_hi:[1,0,1]
	v_pk_mul_f32 v[120:121], v[164:165], v[214:215] op_sel_hi:[0,1]
	ds_read_b128 v[212:215], v137 offset:8752
	s_waitcnt lgkmcnt(3)
	v_pk_mul_f32 v[56:57], v[168:169], v[216:217] op_sel_hi:[0,1]
	v_pk_mul_f32 v[58:59], v[168:169], v[218:219] op_sel_hi:[0,1]
	ds_read_b128 v[216:219], v137 offset:9264
	s_waitcnt lgkmcnt(2)
	v_add_f32_e32 v2, v2, v110
	v_pk_fma_f32 v[150:151], v[154:155], v[162:163], v[104:105] op_sel_hi:[1,0,1]
	ds_read_b128 v[104:107], v137 offset:11792
	v_pk_fma_f32 v[172:173], v[176:177], v[162:163], v[112:113] op_sel_hi:[1,0,1]
	ds_read_b128 v[112:115], v137 offset:11808
	v_pk_fma_f32 v[126:127], v[180:181], v[162:163], v[120:121] op_sel_hi:[1,0,1]
	ds_read_b128 v[120:123], v137 offset:11824
	ds_bpermute_b32 v110, v165, v2
	s_waitcnt lgkmcnt(5)
	v_pk_mul_f32 v[116:117], v[160:161], v[212:213] op_sel_hi:[0,1]
	v_pk_mul_f32 v[108:109], v[160:161], v[214:215] op_sel_hi:[0,1]
	v_pk_fma_f32 v[182:183], v[52:53], v[158:159], v[116:117] op_sel_hi:[1,0,1]
	s_waitcnt lgkmcnt(4)
	v_pk_mul_f32 v[116:117], v[164:165], v[216:217] op_sel_hi:[0,1]
	v_pk_fma_f32 v[118:119], v[54:55], v[158:159], v[108:109] op_sel_hi:[1,0,1]
	v_pk_mul_f32 v[108:109], v[164:165], v[218:219] op_sel_hi:[0,1]
	v_pk_fma_f32 v[170:171], v[174:175], v[162:163], v[170:171] op_sel_hi:[1,0,1]
	v_pk_fma_f32 v[124:125], v[178:179], v[162:163], v[124:125] op_sel_hi:[1,0,1]
	v_pk_fma_f32 v[116:117], v[182:183], v[162:163], v[116:117] op_sel_hi:[1,0,1]
	v_pk_mul_f32 v[52:53], v[168:169], v[220:221] op_sel_hi:[0,1]
	v_pk_fma_f32 v[108:109], v[118:119], v[162:163], v[108:109] op_sel_hi:[1,0,1]
	v_pk_mul_f32 v[54:55], v[168:169], v[222:223] op_sel_hi:[0,1]
	v_pk_fma_f32 v[64:65], v[148:149], v[166:167], v[64:65] op_sel_hi:[1,0,1]
	v_pk_fma_f32 v[66:67], v[150:151], v[166:167], v[66:67] op_sel_hi:[1,0,1]
	v_pk_fma_f32 v[60:61], v[170:171], v[166:167], v[60:61] op_sel_hi:[1,0,1]
	v_pk_fma_f32 v[62:63], v[172:173], v[166:167], v[62:63] op_sel_hi:[1,0,1]
	v_pk_fma_f32 v[56:57], v[124:125], v[166:167], v[56:57] op_sel_hi:[1,0,1]
	v_pk_fma_f32 v[58:59], v[126:127], v[166:167], v[58:59] op_sel_hi:[1,0,1]
	v_pk_fma_f32 v[52:53], v[116:117], v[166:167], v[52:53] op_sel_hi:[1,0,1]
	v_pk_fma_f32 v[54:55], v[108:109], v[166:167], v[54:55] op_sel_hi:[1,0,1]
	global_store_dwordx4 v[140:141], v[64:67], off offset:-32
	global_store_dwordx4 v[140:141], v[60:63], off offset:-16
	global_store_dwordx4 v[140:141], v[56:59], off
	global_store_dwordx4 v[140:141], v[52:55], off offset:16
	s_and_saveexec_b64 s[16:17], vcc
	s_cbranch_execz .Lsmp_h3_743
	v_lshlrev_b32_e32 v111, 16, v209
	v_mul_f32_e32 v156, 0xbfb8aa3b, v111
	v_exp_f32_e32 v156, v156
	ds_read_b32 v158, v189
	s_waitcnt lgkmcnt(1)
	v_add_f32_e32 v2, v2, v110
	v_add_f32_e32 v156, 1.0, v156
	v_rcp_f32_e32 v156, v156
	s_waitcnt lgkmcnt(0)
	v_fmac_f32_e32 v2, s12, v158
	v_mul_f32_e32 v110, v156, v111
	v_mul_f32_e32 v2, v110, v2
	ds_write_b32 v189, v2 offset:12544

.Lsmp_h3_747:
	s_or_b64 exec, exec, s[16:17]
	v_fma_f32 v2, v64, v68, 0
	v_fmac_f32_e32 v2, v65, v69
	v_fmac_f32_e32 v2, v66, v70
	v_fmac_f32_e32 v2, v67, v71
	v_fmac_f32_e32 v2, v60, v104
	v_fmac_f32_e32 v2, v61, v105
	v_fmac_f32_e32 v2, v62, v106
	v_fmac_f32_e32 v2, v63, v107
	v_fmac_f32_e32 v2, v56, v112
	v_fmac_f32_e32 v2, v57, v113
	v_fmac_f32_e32 v2, v58, v114
	v_fmac_f32_e32 v2, v59, v115
	v_fmac_f32_e32 v2, v52, v120
	v_fmac_f32_e32 v2, v53, v121
	v_fmac_f32_e32 v2, v54, v122
	v_fmac_f32_e32 v2, v55, v123
	ds_bpermute_b32 v52, v161, v2
	s_waitcnt lgkmcnt(0)
	v_add_f32_e32 v2, v2, v52
	ds_bpermute_b32 v52, v163, v2
	s_waitcnt lgkmcnt(0)
	v_add_f32_e32 v2, v2, v52
	ds_bpermute_b32 v52, v165, v2
	s_and_saveexec_b64 s[16:17], vcc
	s_cbranch_execz .Lsmp_h3_end
	v_lshlrev_b32_e32 v53, 16, v186
	v_mul_f32_e32 v54, 0xbfb8aa3b, v53
	v_exp_f32_e32 v54, v54
	ds_read_b32 v55, v189 offset:6144
	s_waitcnt lgkmcnt(1)
	v_add_f32_e32 v2, v2, v52
	v_add_f32_e32 v54, 1.0, v54
	v_rcp_f32_e32 v54, v54
	s_waitcnt lgkmcnt(0)
	v_fmac_f32_e32 v2, s12, v55
	v_mul_f32_e32 v52, v54, v53
	v_mul_f32_e32 v2, v52, v2
	ds_write_b32 v189, v2 offset:18688
.Lsmp_h3_end:
	s_or_b64 exec, exec, s[16:17]
	s_add_i32 s13, s13, 4
	s_waitcnt lgkmcnt(0)
	s_mov_b64 s[14:15], 0x8000
	v_lshl_add_u64 v[140:141], v[140:141], 0, s[14:15]
	v_lshl_add_u64 v[144:145], v[144:145], 0, s[14:15]
	v_add_u32_e32 v185, 0x100, v185
	global_load_dwordx4 v[52:55], v[144:145], off offset:16
	global_load_dwordx4 v[56:59], v[144:145], off
	global_load_dwordx4 v[60:63], v[144:145], off offset:-16
	global_load_dwordx4 v[64:67], v[144:145], off offset:-32
	s_lshl_b32 s14, s57, 5
	s_add_u32 s14, s60, s14
	s_addc_u32 s15, s61, 0
	s_nop 0
	s_load_dword s12, s[2:3], 0x10
	s_load_dword s14, s[14:15], 0x10
	v_and_b32_e32 v2, 7, v157
	v_cmp_eq_u32_e32 vcc, 4, v2
	v_add_u32_e32 v189, 0, v185
	s_waitcnt lgkmcnt(0)
	v_mov_b32_e32 v2, s14
	s_mov_b32 s14, 0x3fb8aa3b
	s_waitcnt vmcnt(24)
	v_mul_f32_e32 v68, 0x3fb8aa3b, v2
	v_fma_f32 v69, v2, s14, -v68
	v_rndne_f32_e32 v70, v68
	v_fmac_f32_e32 v69, 0x32a5705f, v2
	v_sub_f32_e32 v68, v68, v70
	v_add_f32_e32 v68, v68, v69
	v_exp_f32_e32 v68, v68
	v_cvt_i32_f32_e32 v69, v70
	s_mov_b32 s14, 0xc2ce8ed0
	v_cmp_ngt_f32_e64 s[38:39], s14, v2
	s_mov_b32 s14, 0x42b17218
	v_ldexp_f32 v68, v68, v69
	v_cndmask_b32_e64 v68, 0, v68, s[38:39]
	v_cmp_nlt_f32_e64 s[38:39], s14, v2
	s_add_i32 s14, s13, 0
	v_mov_b32_e32 v72, s14
	v_cndmask_b32_e64 v116, v203, v68, s[38:39]
	ds_read2_b32 v[68:69], v72 offset1:8
	ds_read2st64_b32 v[70:71], v189 offset1:8
	ds_read_b128 v[104:107], v137 offset:10240
	ds_read_b128 v[112:115], v137 offset:10256
	ds_read_b128 v[120:123], v137 offset:10272
	ds_read_b128 v[108:111], v137 offset:10288
	s_waitcnt lgkmcnt(5)
	v_mul_f32_e64 v2, v68, -v116
	s_waitcnt lgkmcnt(4)
	v_mul_f32_e32 v156, v68, v70
	v_mul_f32_e64 v68, v69, -v116
	v_mul_f32_e32 v68, 0x3fb8aa3b, v68
	v_exp_f32_e32 v158, v68
	v_mul_f32_e32 v160, v69, v71
	ds_read_b128 v[100:103], v137 offset:10752
	ds_read_b128 v[96:99], v137 offset:10768
	ds_read_b128 v[92:95], v137 offset:10784
	ds_read_b128 v[88:91], v137 offset:10800
	ds_read2_b32 v[68:69], v72 offset0:16 offset1:24
	v_mul_f32_e32 v2, 0x3fb8aa3b, v2
	v_exp_f32_e32 v2, v2
	s_waitcnt lgkmcnt(0)
	v_mul_f32_e64 v70, v68, -v116
	v_mul_f32_e32 v70, 0x3fb8aa3b, v70
	v_exp_f32_e32 v162, v70
	ds_read2st64_b32 v[70:71], v189 offset0:16 offset1:24
	ds_read_b128 v[84:87], v137 offset:11264
	ds_read_b128 v[80:83], v137 offset:11280
	ds_read_b128 v[76:79], v137 offset:11296
	ds_read_b128 v[72:75], v137 offset:11312
	s_waitcnt lgkmcnt(4)
	v_mul_f32_e32 v164, v68, v70
	v_mul_f32_e64 v68, v69, -v116
	v_mul_f32_e32 v68, 0x3fb8aa3b, v68
	v_exp_f32_e32 v166, v68
	v_mul_f32_e32 v168, v69, v71
	ds_read_b128 v[68:71], v137 offset:11776
	ds_read_b128 v[148:151], v137 offset:8192
	ds_read_b128 v[170:173], v137 offset:8208
	ds_read_b128 v[124:127], v137 offset:8224
	ds_read_b128 v[116:119], v137 offset:8240
	ds_read_b128 v[152:155], v137 offset:8704
	ds_read_b128 v[174:177], v137 offset:9216
	s_waitcnt lgkmcnt(5)
	v_pk_mul_f32 v[148:149], v[156:157], v[148:149] op_sel_hi:[0,1]
	v_pk_fma_f32 v[48:49], v[48:49], v[2:3], v[148:149] op_sel_hi:[1,0,1]
	s_waitcnt lgkmcnt(4)
	v_pk_mul_f32 v[170:171], v[156:157], v[170:171] op_sel_hi:[0,1]
	v_fma_f32 v210, v48, v104, 0
	v_fmac_f32_e32 v210, v49, v105
	s_waitcnt lgkmcnt(1)
	v_pk_mul_f32 v[104:105], v[160:161], v[152:153] op_sel_hi:[0,1]
	v_pk_fma_f32 v[152:153], v[48:49], v[158:159], v[104:105] op_sel_hi:[1,0,1]
	v_pk_mul_f32 v[104:105], v[156:157], v[150:151] op_sel_hi:[0,1]
	v_pk_fma_f32 v[50:51], v[50:51], v[2:3], v[104:105] op_sel_hi:[1,0,1]
	v_pk_fma_f32 v[44:45], v[44:45], v[2:3], v[170:171] op_sel_hi:[1,0,1]
	v_fmac_f32_e32 v210, v50, v106
	v_fmac_f32_e32 v210, v51, v107
	v_fmac_f32_e32 v210, v44, v112
	v_fmac_f32_e32 v210, v45, v113
	v_pk_mul_f32 v[112:113], v[156:157], v[172:173] op_sel_hi:[0,1]
	v_pk_fma_f32 v[46:47], v[46:47], v[2:3], v[112:113] op_sel_hi:[1,0,1]
	v_pk_mul_f32 v[124:125], v[156:157], v[124:125] op_sel_hi:[0,1]
	v_fmac_f32_e32 v210, v46, v114
	v_fmac_f32_e32 v210, v47, v115
	v_pk_fma_f32 v[40:41], v[40:41], v[2:3], v[124:125] op_sel_hi:[1,0,1]
	ds_read_b128 v[178:181], v137 offset:9728
	ds_read_b128 v[212:215], v137 offset:9744
	v_fmac_f32_e32 v210, v40, v120
	v_fmac_f32_e32 v210, v41, v121
	v_pk_mul_f32 v[120:121], v[156:157], v[126:127] op_sel_hi:[0,1]
	v_pk_fma_f32 v[42:43], v[42:43], v[2:3], v[120:121] op_sel_hi:[1,0,1]
	v_pk_mul_f32 v[116:117], v[156:157], v[116:117] op_sel_hi:[0,1]
	v_fmac_f32_e32 v210, v42, v122
	v_fmac_f32_e32 v210, v43, v123
	v_pk_fma_f32 v[36:37], v[36:37], v[2:3], v[116:117] op_sel_hi:[1,0,1]
	v_pk_mul_f32 v[104:105], v[160:161], v[154:155] op_sel_hi:[0,1]
	v_fmac_f32_e32 v210, v36, v108
	s_waitcnt lgkmcnt(2)
	v_pk_mul_f32 v[48:49], v[164:165], v[174:175] op_sel_hi:[0,1]
	v_pk_fma_f32 v[154:155], v[50:51], v[158:159], v[104:105] op_sel_hi:[1,0,1]
	v_pk_mul_f32 v[104:105], v[164:165], v[176:177] op_sel_hi:[0,1]
	ds_read_b128 v[174:177], v137 offset:8720
	v_fmac_f32_e32 v210, v37, v109
	v_pk_mul_f32 v[108:109], v[156:157], v[118:119] op_sel_hi:[0,1]
	v_pk_fma_f32 v[148:149], v[152:153], v[162:163], v[48:49] op_sel_hi:[1,0,1]
	s_waitcnt lgkmcnt(2)
	v_pk_mul_f32 v[48:49], v[168:169], v[178:179] op_sel_hi:[0,1]
	v_pk_mul_f32 v[50:51], v[168:169], v[180:181] op_sel_hi:[0,1]
	ds_read_b128 v[178:181], v137 offset:9232
	v_pk_fma_f32 v[38:39], v[38:39], v[2:3], v[108:109] op_sel_hi:[1,0,1]
	s_waitcnt lgkmcnt(1)
	v_pk_mul_f32 v[170:171], v[160:161], v[174:175] op_sel_hi:[0,1]
	v_fmac_f32_e32 v210, v38, v110
	v_fmac_f32_e32 v210, v39, v111
	ds_bpermute_b32 v2, v161, v210
	v_pk_mul_f32 v[112:113], v[160:161], v[176:177] op_sel_hi:[0,1]
	v_pk_fma_f32 v[174:175], v[44:45], v[158:159], v[170:171] op_sel_hi:[1,0,1]
	s_waitcnt lgkmcnt(1)
	v_pk_mul_f32 v[170:171], v[164:165], v[178:179] op_sel_hi:[0,1]
	v_pk_fma_f32 v[176:177], v[46:47], v[158:159], v[112:113] op_sel_hi:[1,0,1]
	v_pk_mul_f32 v[112:113], v[164:165], v[180:181] op_sel_hi:[0,1]
	ds_read_b128 v[178:181], v137 offset:8736
	v_pk_mul_f32 v[44:45], v[168:169], v[212:213] op_sel_hi:[0,1]
	v_pk_mul_f32 v[46:47], v[168:169], v[214:215] op_sel_hi:[0,1]
	ds_read_b128 v[212:215], v137 offset:9248
	ds_read_b128 v[216:219], v137 offset:9760
	ds_read_b128 v[220:223], v137 offset:9776
	s_waitcnt lgkmcnt(4)
	v_add_f32_e32 v2, v210, v2
	ds_bpermute_b32 v110, v163, v2
	s_waitcnt lgkmcnt(4)
	v_pk_mul_f32 v[124:125], v[160:161], v[178:179] op_sel_hi:[0,1]
	v_pk_mul_f32 v[120:121], v[160:161], v[180:181] op_sel_hi:[0,1]
	v_pk_fma_f32 v[178:179], v[40:41], v[158:159], v[124:125] op_sel_hi:[1,0,1]
	s_waitcnt lgkmcnt(3)
	v_pk_mul_f32 v[124:125], v[164:165], v[212:213] op_sel_hi:[0,1]
	v_pk_fma_f32 v[180:181], v[42:43], v[158:159], v[120:121] op_sel_hi:[1,0,1]
	v_pk_mul_f32 v[120:121], v[164:165], v[214:215] op_sel_hi:[0,1]
	ds_read_b128 v[212:215], v137 offset:8752
	s_waitcnt lgkmcnt(3)
	v_pk_mul_f32 v[40:41], v[168:169], v[216:217] op_sel_hi:[0,1]
	v_pk_mul_f32 v[42:43], v[168:169], v[218:219] op_sel_hi:[0,1]
	ds_read_b128 v[216:219], v137 offset:9264
	s_waitcnt lgkmcnt(2)
	v_add_f32_e32 v2, v2, v110
	v_pk_fma_f32 v[150:151], v[154:155], v[162:163], v[104:105] op_sel_hi:[1,0,1]
	ds_read_b128 v[104:107], v137 offset:11792
	v_pk_fma_f32 v[172:173], v[176:177], v[162:163], v[112:113] op_sel_hi:[1,0,1]
	ds_read_b128 v[112:115], v137 offset:11808
	v_pk_fma_f32 v[126:127], v[180:181], v[162:163], v[120:121] op_sel_hi:[1,0,1]
	ds_read_b128 v[120:123], v137 offset:11824
	ds_bpermute_b32 v110, v165, v2
	s_waitcnt lgkmcnt(5)
	v_pk_mul_f32 v[116:117], v[160:161], v[212:213] op_sel_hi:[0,1]
	v_pk_mul_f32 v[108:109], v[160:161], v[214:215] op_sel_hi:[0,1]
	v_pk_fma_f32 v[182:183], v[36:37], v[158:159], v[116:117] op_sel_hi:[1,0,1]
	s_waitcnt lgkmcnt(4)
	v_pk_mul_f32 v[116:117], v[164:165], v[216:217] op_sel_hi:[0,1]
	v_pk_fma_f32 v[118:119], v[38:39], v[158:159], v[108:109] op_sel_hi:[1,0,1]
	v_pk_mul_f32 v[108:109], v[164:165], v[218:219] op_sel_hi:[0,1]
	v_pk_fma_f32 v[170:171], v[174:175], v[162:163], v[170:171] op_sel_hi:[1,0,1]
	v_pk_fma_f32 v[124:125], v[178:179], v[162:163], v[124:125] op_sel_hi:[1,0,1]
	v_pk_fma_f32 v[116:117], v[182:183], v[162:163], v[116:117] op_sel_hi:[1,0,1]
	v_pk_mul_f32 v[36:37], v[168:169], v[220:221] op_sel_hi:[0,1]
	v_pk_fma_f32 v[108:109], v[118:119], v[162:163], v[108:109] op_sel_hi:[1,0,1]
	v_pk_mul_f32 v[38:39], v[168:169], v[222:223] op_sel_hi:[0,1]
	v_pk_fma_f32 v[48:49], v[148:149], v[166:167], v[48:49] op_sel_hi:[1,0,1]
	v_pk_fma_f32 v[50:51], v[150:151], v[166:167], v[50:51] op_sel_hi:[1,0,1]
	v_pk_fma_f32 v[44:45], v[170:171], v[166:167], v[44:45] op_sel_hi:[1,0,1]
	v_pk_fma_f32 v[46:47], v[172:173], v[166:167], v[46:47] op_sel_hi:[1,0,1]
	v_pk_fma_f32 v[40:41], v[124:125], v[166:167], v[40:41] op_sel_hi:[1,0,1]
	v_pk_fma_f32 v[42:43], v[126:127], v[166:167], v[42:43] op_sel_hi:[1,0,1]
	v_pk_fma_f32 v[36:37], v[116:117], v[166:167], v[36:37] op_sel_hi:[1,0,1]
	v_pk_fma_f32 v[38:39], v[108:109], v[166:167], v[38:39] op_sel_hi:[1,0,1]
	global_store_dwordx4 v[140:141], v[48:51], off offset:-32
	global_store_dwordx4 v[140:141], v[44:47], off offset:-16
	global_store_dwordx4 v[140:141], v[40:43], off
	global_store_dwordx4 v[140:141], v[36:39], off offset:16
	s_and_saveexec_b64 s[16:17], vcc
	s_cbranch_execz .Lsmp_h4_743
	v_lshlrev_b32_e32 v111, 16, v209
	v_mul_f32_e32 v156, 0xbfb8aa3b, v111
	v_exp_f32_e32 v156, v156
	ds_read_b32 v158, v189
	s_waitcnt lgkmcnt(1)
	v_add_f32_e32 v2, v2, v110
	v_add_f32_e32 v156, 1.0, v156
	v_rcp_f32_e32 v156, v156
	s_waitcnt lgkmcnt(0)
	v_fmac_f32_e32 v2, s12, v158
	v_mul_f32_e32 v110, v156, v111
	v_mul_f32_e32 v2, v110, v2
	ds_write_b32 v189, v2 offset:12544

.Lsmp_h4_end:
	s_or_b64 exec, exec, s[16:17]
	s_add_i32 s13, s13, 4
	s_waitcnt lgkmcnt(0)
	s_mov_b64 s[14:15], 0x8000
	v_lshl_add_u64 v[140:141], v[140:141], 0, s[14:15]
	v_lshl_add_u64 v[144:145], v[144:145], 0, s[14:15]
	v_add_u32_e32 v185, 0x100, v185
	s_lshl_b32 s14, s57, 5
	s_add_u32 s14, s60, s14
	s_addc_u32 s15, s61, 0
	s_nop 0
	s_load_dword s12, s[2:3], 0x14
	s_load_dword s14, s[14:15], 0x14
	v_and_b32_e32 v2, 7, v157
	v_cmp_eq_u32_e32 vcc, 5, v2
	v_add_u32_e32 v189, 0, v185
	s_waitcnt lgkmcnt(0)
	v_mov_b32_e32 v2, s14
	s_mov_b32 s14, 0x3fb8aa3b
	s_waitcnt vmcnt(20)
	v_mul_f32_e32 v68, 0x3fb8aa3b, v2
	v_fma_f32 v69, v2, s14, -v68
	v_rndne_f32_e32 v70, v68
	v_fmac_f32_e32 v69, 0x32a5705f, v2
	v_sub_f32_e32 v68, v68, v70
	v_add_f32_e32 v68, v68, v69
	v_exp_f32_e32 v68, v68
	v_cvt_i32_f32_e32 v69, v70
	s_mov_b32 s14, 0xc2ce8ed0
	v_cmp_ngt_f32_e64 s[38:39], s14, v2
	s_mov_b32 s14, 0x42b17218
	v_ldexp_f32 v68, v68, v69
	v_cndmask_b32_e64 v68, 0, v68, s[38:39]
	v_cmp_nlt_f32_e64 s[38:39], s14, v2
	s_add_i32 s14, s13, 0
	v_mov_b32_e32 v72, s14
	v_cndmask_b32_e64 v116, v203, v68, s[38:39]
	ds_read2_b32 v[68:69], v72 offset1:8
	ds_read2st64_b32 v[70:71], v189 offset1:8
	ds_read_b128 v[104:107], v137 offset:10240
	ds_read_b128 v[112:115], v137 offset:10256
	ds_read_b128 v[120:123], v137 offset:10272
	ds_read_b128 v[108:111], v137 offset:10288
	s_waitcnt lgkmcnt(5)
	v_mul_f32_e64 v2, v68, -v116
	s_waitcnt lgkmcnt(4)
	v_mul_f32_e32 v156, v68, v70
	v_mul_f32_e64 v68, v69, -v116
	v_mul_f32_e32 v68, 0x3fb8aa3b, v68
	v_exp_f32_e32 v158, v68
	v_mul_f32_e32 v160, v69, v71
	ds_read_b128 v[100:103], v137 offset:10752
	ds_read_b128 v[96:99], v137 offset:10768
	ds_read_b128 v[92:95], v137 offset:10784
	ds_read_b128 v[88:91], v137 offset:10800
	ds_read2_b32 v[68:69], v72 offset0:16 offset1:24
	v_mul_f32_e32 v2, 0x3fb8aa3b, v2
	v_exp_f32_e32 v2, v2
	s_waitcnt lgkmcnt(0)
	v_mul_f32_e64 v70, v68, -v116
	v_mul_f32_e32 v70, 0x3fb8aa3b, v70
	v_exp_f32_e32 v162, v70
	ds_read2st64_b32 v[70:71], v189 offset0:16 offset1:24
	ds_read_b128 v[84:87], v137 offset:11264
	ds_read_b128 v[80:83], v137 offset:11280
	ds_read_b128 v[76:79], v137 offset:11296
	ds_read_b128 v[72:75], v137 offset:11312
	s_waitcnt lgkmcnt(4)
	v_mul_f32_e32 v164, v68, v70
	v_mul_f32_e64 v68, v69, -v116
	v_mul_f32_e32 v68, 0x3fb8aa3b, v68
	v_exp_f32_e32 v166, v68
	v_mul_f32_e32 v168, v69, v71
	ds_read_b128 v[68:71], v137 offset:11776
	ds_read_b128 v[148:151], v137 offset:8192
	ds_read_b128 v[170:173], v137 offset:8208
	ds_read_b128 v[124:127], v137 offset:8224
	ds_read_b128 v[116:119], v137 offset:8240
	ds_read_b128 v[152:155], v137 offset:8704
	ds_read_b128 v[174:177], v137 offset:9216
	s_waitcnt lgkmcnt(5)
	v_pk_mul_f32 v[148:149], v[156:157], v[148:149] op_sel_hi:[0,1]
	v_pk_fma_f32 v[12:13], v[12:13], v[2:3], v[148:149] op_sel_hi:[1,0,1]
	s_waitcnt lgkmcnt(4)
	v_pk_mul_f32 v[170:171], v[156:157], v[170:171] op_sel_hi:[0,1]
	v_fma_f32 v210, v12, v104, 0
	v_fmac_f32_e32 v210, v13, v105
	s_waitcnt lgkmcnt(1)
	v_pk_mul_f32 v[104:105], v[160:161], v[152:153] op_sel_hi:[0,1]
	v_pk_fma_f32 v[152:153], v[12:13], v[158:159], v[104:105] op_sel_hi:[1,0,1]
	v_pk_mul_f32 v[104:105], v[156:157], v[150:151] op_sel_hi:[0,1]
	v_pk_fma_f32 v[14:15], v[14:15], v[2:3], v[104:105] op_sel_hi:[1,0,1]
	v_pk_fma_f32 v[8:9], v[8:9], v[2:3], v[170:171] op_sel_hi:[1,0,1]
	v_fmac_f32_e32 v210, v14, v106
	v_fmac_f32_e32 v210, v15, v107
	v_fmac_f32_e32 v210, v8, v112
	v_fmac_f32_e32 v210, v9, v113
	v_pk_mul_f32 v[112:113], v[156:157], v[172:173] op_sel_hi:[0,1]
	v_pk_fma_f32 v[10:11], v[10:11], v[2:3], v[112:113] op_sel_hi:[1,0,1]
	v_pk_mul_f32 v[124:125], v[156:157], v[124:125] op_sel_hi:[0,1]
	v_fmac_f32_e32 v210, v10, v114
	v_fmac_f32_e32 v210, v11, v115
	v_pk_fma_f32 v[4:5], v[4:5], v[2:3], v[124:125] op_sel_hi:[1,0,1]
	ds_read_b128 v[178:181], v137 offset:9728
	ds_read_b128 v[212:215], v137 offset:9744
	v_fmac_f32_e32 v210, v4, v120
	v_fmac_f32_e32 v210, v5, v121
	v_pk_mul_f32 v[120:121], v[156:157], v[126:127] op_sel_hi:[0,1]
	v_pk_fma_f32 v[6:7], v[6:7], v[2:3], v[120:121] op_sel_hi:[1,0,1]
	v_pk_mul_f32 v[116:117], v[156:157], v[116:117] op_sel_hi:[0,1]
	v_fmac_f32_e32 v210, v6, v122
	v_fmac_f32_e32 v210, v7, v123
	v_pk_fma_f32 v[28:29], v[28:29], v[2:3], v[116:117] op_sel_hi:[1,0,1]
	v_pk_mul_f32 v[104:105], v[160:161], v[154:155] op_sel_hi:[0,1]
	v_fmac_f32_e32 v210, v28, v108
	s_waitcnt lgkmcnt(2)
	v_pk_mul_f32 v[12:13], v[164:165], v[174:175] op_sel_hi:[0,1]
	v_pk_fma_f32 v[154:155], v[14:15], v[158:159], v[104:105] op_sel_hi:[1,0,1]
	v_pk_mul_f32 v[104:105], v[164:165], v[176:177] op_sel_hi:[0,1]
	ds_read_b128 v[174:177], v137 offset:8720
	v_fmac_f32_e32 v210, v29, v109
	v_pk_mul_f32 v[108:109], v[156:157], v[118:119] op_sel_hi:[0,1]
	v_pk_fma_f32 v[148:149], v[152:153], v[162:163], v[12:13] op_sel_hi:[1,0,1]
	s_waitcnt lgkmcnt(2)
	v_pk_mul_f32 v[12:13], v[168:169], v[178:179] op_sel_hi:[0,1]
	v_pk_mul_f32 v[14:15], v[168:169], v[180:181] op_sel_hi:[0,1]
	ds_read_b128 v[178:181], v137 offset:9232
	v_pk_fma_f32 v[30:31], v[30:31], v[2:3], v[108:109] op_sel_hi:[1,0,1]
	s_waitcnt lgkmcnt(1)
	v_pk_mul_f32 v[170:171], v[160:161], v[174:175] op_sel_hi:[0,1]
	v_fmac_f32_e32 v210, v30, v110
	v_fmac_f32_e32 v210, v31, v111
	ds_bpermute_b32 v2, v161, v210
	v_pk_mul_f32 v[112:113], v[160:161], v[176:177] op_sel_hi:[0,1]
	v_pk_fma_f32 v[174:175], v[8:9], v[158:159], v[170:171] op_sel_hi:[1,0,1]
	s_waitcnt lgkmcnt(1)
	v_pk_mul_f32 v[170:171], v[164:165], v[178:179] op_sel_hi:[0,1]
	v_pk_fma_f32 v[176:177], v[10:11], v[158:159], v[112:113] op_sel_hi:[1,0,1]
	v_pk_mul_f32 v[112:113], v[164:165], v[180:181] op_sel_hi:[0,1]
	ds_read_b128 v[178:181], v137 offset:8736
	v_pk_mul_f32 v[8:9], v[168:169], v[212:213] op_sel_hi:[0,1]
	v_pk_mul_f32 v[10:11], v[168:169], v[214:215] op_sel_hi:[0,1]
	ds_read_b128 v[212:215], v137 offset:9248
	ds_read_b128 v[216:219], v137 offset:9760
	ds_read_b128 v[220:223], v137 offset:9776
	s_waitcnt lgkmcnt(4)
	v_add_f32_e32 v2, v210, v2
	ds_bpermute_b32 v110, v163, v2
	s_waitcnt lgkmcnt(4)
	v_pk_mul_f32 v[124:125], v[160:161], v[178:179] op_sel_hi:[0,1]
	v_pk_mul_f32 v[120:121], v[160:161], v[180:181] op_sel_hi:[0,1]
	v_pk_fma_f32 v[178:179], v[4:5], v[158:159], v[124:125] op_sel_hi:[1,0,1]
	s_waitcnt lgkmcnt(3)
	v_pk_mul_f32 v[124:125], v[164:165], v[212:213] op_sel_hi:[0,1]
	v_pk_fma_f32 v[180:181], v[6:7], v[158:159], v[120:121] op_sel_hi:[1,0,1]
	v_pk_mul_f32 v[120:121], v[164:165], v[214:215] op_sel_hi:[0,1]
	ds_read_b128 v[212:215], v137 offset:8752
	s_waitcnt lgkmcnt(3)
	v_pk_mul_f32 v[4:5], v[168:169], v[216:217] op_sel_hi:[0,1]
	v_pk_mul_f32 v[6:7], v[168:169], v[218:219] op_sel_hi:[0,1]
	ds_read_b128 v[216:219], v137 offset:9264
	s_waitcnt lgkmcnt(2)
	v_add_f32_e32 v2, v2, v110
	v_pk_fma_f32 v[150:151], v[154:155], v[162:163], v[104:105] op_sel_hi:[1,0,1]
	ds_read_b128 v[104:107], v137 offset:11792
	v_pk_fma_f32 v[172:173], v[176:177], v[162:163], v[112:113] op_sel_hi:[1,0,1]
	ds_read_b128 v[112:115], v137 offset:11808
	v_pk_fma_f32 v[126:127], v[180:181], v[162:163], v[120:121] op_sel_hi:[1,0,1]
	ds_read_b128 v[120:123], v137 offset:11824
	ds_bpermute_b32 v110, v165, v2
	s_waitcnt lgkmcnt(5)
	v_pk_mul_f32 v[116:117], v[160:161], v[212:213] op_sel_hi:[0,1]
	v_pk_mul_f32 v[108:109], v[160:161], v[214:215] op_sel_hi:[0,1]
	v_pk_fma_f32 v[182:183], v[28:29], v[158:159], v[116:117] op_sel_hi:[1,0,1]
	s_waitcnt lgkmcnt(4)
	v_pk_mul_f32 v[116:117], v[164:165], v[216:217] op_sel_hi:[0,1]
	v_pk_fma_f32 v[118:119], v[30:31], v[158:159], v[108:109] op_sel_hi:[1,0,1]
	v_pk_mul_f32 v[108:109], v[164:165], v[218:219] op_sel_hi:[0,1]
	v_pk_fma_f32 v[170:171], v[174:175], v[162:163], v[170:171] op_sel_hi:[1,0,1]
	v_pk_fma_f32 v[124:125], v[178:179], v[162:163], v[124:125] op_sel_hi:[1,0,1]
	v_pk_fma_f32 v[116:117], v[182:183], v[162:163], v[116:117] op_sel_hi:[1,0,1]
	v_pk_mul_f32 v[28:29], v[168:169], v[220:221] op_sel_hi:[0,1]
	v_pk_fma_f32 v[108:109], v[118:119], v[162:163], v[108:109] op_sel_hi:[1,0,1]
	v_pk_mul_f32 v[30:31], v[168:169], v[222:223] op_sel_hi:[0,1]
	v_pk_fma_f32 v[12:13], v[148:149], v[166:167], v[12:13] op_sel_hi:[1,0,1]
	v_pk_fma_f32 v[14:15], v[150:151], v[166:167], v[14:15] op_sel_hi:[1,0,1]
	v_pk_fma_f32 v[8:9], v[170:171], v[166:167], v[8:9] op_sel_hi:[1,0,1]
	v_pk_fma_f32 v[10:11], v[172:173], v[166:167], v[10:11] op_sel_hi:[1,0,1]
	v_pk_fma_f32 v[4:5], v[124:125], v[166:167], v[4:5] op_sel_hi:[1,0,1]
	v_pk_fma_f32 v[6:7], v[126:127], v[166:167], v[6:7] op_sel_hi:[1,0,1]
	v_pk_fma_f32 v[28:29], v[116:117], v[166:167], v[28:29] op_sel_hi:[1,0,1]
	v_pk_fma_f32 v[30:31], v[108:109], v[166:167], v[30:31] op_sel_hi:[1,0,1]
	global_store_dwordx4 v[140:141], v[12:15], off offset:-32
	global_store_dwordx4 v[140:141], v[8:11], off offset:-16
	global_store_dwordx4 v[140:141], v[4:7], off
	global_store_dwordx4 v[140:141], v[28:31], off offset:16
	s_and_saveexec_b64 s[16:17], vcc
	s_cbranch_execz .Lsmp_h5_743
	v_lshlrev_b32_e32 v111, 16, v209
	v_mul_f32_e32 v156, 0xbfb8aa3b, v111
	v_exp_f32_e32 v156, v156
	ds_read_b32 v158, v189
	s_waitcnt lgkmcnt(1)
	v_add_f32_e32 v2, v2, v110
	v_add_f32_e32 v156, 1.0, v156
	v_rcp_f32_e32 v156, v156
	s_waitcnt lgkmcnt(0)
	v_fmac_f32_e32 v2, s12, v158
	v_mul_f32_e32 v110, v156, v111
	v_mul_f32_e32 v2, v110, v2
	ds_write_b32 v189, v2 offset:12544

.Lsmp_h5_end:
	s_or_b64 exec, exec, s[16:17]
	s_add_i32 s13, s13, 4
	s_waitcnt lgkmcnt(0)
	s_mov_b64 s[14:15], 0x8000
	v_lshl_add_u64 v[140:141], v[140:141], 0, s[14:15]
	v_lshl_add_u64 v[144:145], v[144:145], 0, s[14:15]
	v_add_u32_e32 v185, 0x100, v185
	s_lshl_b32 s14, s57, 5
	s_add_u32 s14, s60, s14
	s_addc_u32 s15, s61, 0
	s_nop 0
	s_load_dword s12, s[2:3], 0x18
	s_load_dword s14, s[14:15], 0x18
	v_and_b32_e32 v2, 7, v157
	v_cmp_eq_u32_e32 vcc, 6, v2
	v_add_u32_e32 v189, 0, v185
	s_waitcnt lgkmcnt(0)
	v_mov_b32_e32 v2, s14
	s_mov_b32 s14, 0x3fb8aa3b
	s_waitcnt vmcnt(16)
	v_mul_f32_e32 v68, 0x3fb8aa3b, v2
	v_fma_f32 v69, v2, s14, -v68
	v_rndne_f32_e32 v70, v68
	v_fmac_f32_e32 v69, 0x32a5705f, v2
	v_sub_f32_e32 v68, v68, v70
	v_add_f32_e32 v68, v68, v69
	v_exp_f32_e32 v68, v68
	v_cvt_i32_f32_e32 v69, v70
	s_mov_b32 s14, 0xc2ce8ed0
	v_cmp_ngt_f32_e64 s[38:39], s14, v2
	s_mov_b32 s14, 0x42b17218
	v_ldexp_f32 v68, v68, v69
	v_cndmask_b32_e64 v68, 0, v68, s[38:39]
	v_cmp_nlt_f32_e64 s[38:39], s14, v2
	s_add_i32 s14, s13, 0
	v_mov_b32_e32 v72, s14
	v_cndmask_b32_e64 v116, v203, v68, s[38:39]
	ds_read2_b32 v[68:69], v72 offset1:8
	ds_read2st64_b32 v[70:71], v189 offset1:8
	ds_read_b128 v[104:107], v137 offset:10240
	ds_read_b128 v[112:115], v137 offset:10256
	ds_read_b128 v[120:123], v137 offset:10272
	ds_read_b128 v[108:111], v137 offset:10288
	s_waitcnt lgkmcnt(5)
	v_mul_f32_e64 v2, v68, -v116
	s_waitcnt lgkmcnt(4)
	v_mul_f32_e32 v156, v68, v70
	v_mul_f32_e64 v68, v69, -v116
	v_mul_f32_e32 v68, 0x3fb8aa3b, v68
	v_exp_f32_e32 v158, v68
	v_mul_f32_e32 v160, v69, v71
	ds_read_b128 v[100:103], v137 offset:10752
	ds_read_b128 v[96:99], v137 offset:10768
	ds_read_b128 v[92:95], v137 offset:10784
	ds_read_b128 v[88:91], v137 offset:10800
	ds_read2_b32 v[68:69], v72 offset0:16 offset1:24
	v_mul_f32_e32 v2, 0x3fb8aa3b, v2
	v_exp_f32_e32 v2, v2
	s_waitcnt lgkmcnt(0)
	v_mul_f32_e64 v70, v68, -v116
	v_mul_f32_e32 v70, 0x3fb8aa3b, v70
	v_exp_f32_e32 v162, v70
	ds_read2st64_b32 v[70:71], v189 offset0:16 offset1:24
	ds_read_b128 v[84:87], v137 offset:11264
	ds_read_b128 v[80:83], v137 offset:11280
	ds_read_b128 v[76:79], v137 offset:11296
	ds_read_b128 v[72:75], v137 offset:11312
	s_waitcnt lgkmcnt(4)
	v_mul_f32_e32 v164, v68, v70
	v_mul_f32_e64 v68, v69, -v116
	v_mul_f32_e32 v68, 0x3fb8aa3b, v68
	v_exp_f32_e32 v166, v68
	v_mul_f32_e32 v168, v69, v71
	ds_read_b128 v[68:71], v137 offset:11776
	ds_read_b128 v[148:151], v137 offset:8192
	ds_read_b128 v[170:173], v137 offset:8208
	ds_read_b128 v[124:127], v137 offset:8224
	ds_read_b128 v[116:119], v137 offset:8240
	ds_read_b128 v[152:155], v137 offset:8704
	ds_read_b128 v[174:177], v137 offset:9216
	s_waitcnt lgkmcnt(5)
	v_pk_mul_f32 v[148:149], v[156:157], v[148:149] op_sel_hi:[0,1]
	v_pk_fma_f32 v[16:17], v[16:17], v[2:3], v[148:149] op_sel_hi:[1,0,1]
	s_waitcnt lgkmcnt(4)
	v_pk_mul_f32 v[170:171], v[156:157], v[170:171] op_sel_hi:[0,1]
	v_fma_f32 v210, v16, v104, 0
	v_fmac_f32_e32 v210, v17, v105
	s_waitcnt lgkmcnt(1)
	v_pk_mul_f32 v[104:105], v[160:161], v[152:153] op_sel_hi:[0,1]
	v_pk_fma_f32 v[152:153], v[16:17], v[158:159], v[104:105] op_sel_hi:[1,0,1]
	v_pk_mul_f32 v[104:105], v[156:157], v[150:151] op_sel_hi:[0,1]
	v_pk_fma_f32 v[18:19], v[18:19], v[2:3], v[104:105] op_sel_hi:[1,0,1]
	v_pk_fma_f32 v[32:33], v[32:33], v[2:3], v[170:171] op_sel_hi:[1,0,1]
	v_fmac_f32_e32 v210, v18, v106
	v_fmac_f32_e32 v210, v19, v107
	v_fmac_f32_e32 v210, v32, v112
	v_fmac_f32_e32 v210, v33, v113
	v_pk_mul_f32 v[112:113], v[156:157], v[172:173] op_sel_hi:[0,1]
	v_pk_fma_f32 v[34:35], v[34:35], v[2:3], v[112:113] op_sel_hi:[1,0,1]
	v_pk_mul_f32 v[124:125], v[156:157], v[124:125] op_sel_hi:[0,1]
	v_fmac_f32_e32 v210, v34, v114
	v_fmac_f32_e32 v210, v35, v115
	v_pk_fma_f32 v[24:25], v[24:25], v[2:3], v[124:125] op_sel_hi:[1,0,1]
	ds_read_b128 v[178:181], v137 offset:9728
	ds_read_b128 v[212:215], v137 offset:9744
	v_fmac_f32_e32 v210, v24, v120
	v_fmac_f32_e32 v210, v25, v121
	v_pk_mul_f32 v[120:121], v[156:157], v[126:127] op_sel_hi:[0,1]
	v_pk_fma_f32 v[26:27], v[26:27], v[2:3], v[120:121] op_sel_hi:[1,0,1]
	v_pk_mul_f32 v[116:117], v[156:157], v[116:117] op_sel_hi:[0,1]
	v_fmac_f32_e32 v210, v26, v122
	v_fmac_f32_e32 v210, v27, v123
	v_pk_fma_f32 v[20:21], v[20:21], v[2:3], v[116:117] op_sel_hi:[1,0,1]
	v_pk_mul_f32 v[104:105], v[160:161], v[154:155] op_sel_hi:[0,1]
	v_fmac_f32_e32 v210, v20, v108
	s_waitcnt lgkmcnt(2)
	v_pk_mul_f32 v[16:17], v[164:165], v[174:175] op_sel_hi:[0,1]
	v_pk_fma_f32 v[154:155], v[18:19], v[158:159], v[104:105] op_sel_hi:[1,0,1]
	v_pk_mul_f32 v[104:105], v[164:165], v[176:177] op_sel_hi:[0,1]
	ds_read_b128 v[174:177], v137 offset:8720
	v_fmac_f32_e32 v210, v21, v109
	v_pk_mul_f32 v[108:109], v[156:157], v[118:119] op_sel_hi:[0,1]
	v_pk_fma_f32 v[148:149], v[152:153], v[162:163], v[16:17] op_sel_hi:[1,0,1]
	s_waitcnt lgkmcnt(2)
	v_pk_mul_f32 v[16:17], v[168:169], v[178:179] op_sel_hi:[0,1]
	v_pk_mul_f32 v[18:19], v[168:169], v[180:181] op_sel_hi:[0,1]
	ds_read_b128 v[178:181], v137 offset:9232
	v_pk_fma_f32 v[22:23], v[22:23], v[2:3], v[108:109] op_sel_hi:[1,0,1]
	s_waitcnt lgkmcnt(1)
	v_pk_mul_f32 v[170:171], v[160:161], v[174:175] op_sel_hi:[0,1]
	v_fmac_f32_e32 v210, v22, v110
	v_fmac_f32_e32 v210, v23, v111
	ds_bpermute_b32 v2, v161, v210
	v_pk_mul_f32 v[112:113], v[160:161], v[176:177] op_sel_hi:[0,1]
	v_pk_fma_f32 v[174:175], v[32:33], v[158:159], v[170:171] op_sel_hi:[1,0,1]
	s_waitcnt lgkmcnt(1)
	v_pk_mul_f32 v[170:171], v[164:165], v[178:179] op_sel_hi:[0,1]
	v_pk_fma_f32 v[176:177], v[34:35], v[158:159], v[112:113] op_sel_hi:[1,0,1]
	v_pk_mul_f32 v[112:113], v[164:165], v[180:181] op_sel_hi:[0,1]
	ds_read_b128 v[178:181], v137 offset:8736
	v_pk_mul_f32 v[32:33], v[168:169], v[212:213] op_sel_hi:[0,1]
	v_pk_mul_f32 v[34:35], v[168:169], v[214:215] op_sel_hi:[0,1]
	ds_read_b128 v[212:215], v137 offset:9248
	ds_read_b128 v[216:219], v137 offset:9760
	ds_read_b128 v[220:223], v137 offset:9776
	s_waitcnt lgkmcnt(4)
	v_add_f32_e32 v2, v210, v2
	ds_bpermute_b32 v110, v163, v2
	s_waitcnt lgkmcnt(4)
	v_pk_mul_f32 v[124:125], v[160:161], v[178:179] op_sel_hi:[0,1]
	v_pk_mul_f32 v[120:121], v[160:161], v[180:181] op_sel_hi:[0,1]
	v_pk_fma_f32 v[178:179], v[24:25], v[158:159], v[124:125] op_sel_hi:[1,0,1]
	s_waitcnt lgkmcnt(3)
	v_pk_mul_f32 v[124:125], v[164:165], v[212:213] op_sel_hi:[0,1]
	v_pk_fma_f32 v[180:181], v[26:27], v[158:159], v[120:121] op_sel_hi:[1,0,1]
	v_pk_mul_f32 v[120:121], v[164:165], v[214:215] op_sel_hi:[0,1]
	ds_read_b128 v[212:215], v137 offset:8752
	s_waitcnt lgkmcnt(3)
	v_pk_mul_f32 v[24:25], v[168:169], v[216:217] op_sel_hi:[0,1]
	v_pk_mul_f32 v[26:27], v[168:169], v[218:219] op_sel_hi:[0,1]
	ds_read_b128 v[216:219], v137 offset:9264
	s_waitcnt lgkmcnt(2)
	v_add_f32_e32 v2, v2, v110
	v_pk_fma_f32 v[150:151], v[154:155], v[162:163], v[104:105] op_sel_hi:[1,0,1]
	ds_read_b128 v[104:107], v137 offset:11792
	v_pk_fma_f32 v[172:173], v[176:177], v[162:163], v[112:113] op_sel_hi:[1,0,1]
	ds_read_b128 v[112:115], v137 offset:11808
	v_pk_fma_f32 v[126:127], v[180:181], v[162:163], v[120:121] op_sel_hi:[1,0,1]
	ds_read_b128 v[120:123], v137 offset:11824
	ds_bpermute_b32 v110, v165, v2
	s_waitcnt lgkmcnt(5)
	v_pk_mul_f32 v[116:117], v[160:161], v[212:213] op_sel_hi:[0,1]
	v_pk_mul_f32 v[108:109], v[160:161], v[214:215] op_sel_hi:[0,1]
	v_pk_fma_f32 v[182:183], v[20:21], v[158:159], v[116:117] op_sel_hi:[1,0,1]
	s_waitcnt lgkmcnt(4)
	v_pk_mul_f32 v[116:117], v[164:165], v[216:217] op_sel_hi:[0,1]
	v_pk_fma_f32 v[118:119], v[22:23], v[158:159], v[108:109] op_sel_hi:[1,0,1]
	v_pk_mul_f32 v[108:109], v[164:165], v[218:219] op_sel_hi:[0,1]
	v_pk_fma_f32 v[170:171], v[174:175], v[162:163], v[170:171] op_sel_hi:[1,0,1]
	v_pk_fma_f32 v[124:125], v[178:179], v[162:163], v[124:125] op_sel_hi:[1,0,1]
	v_pk_fma_f32 v[116:117], v[182:183], v[162:163], v[116:117] op_sel_hi:[1,0,1]
	v_pk_mul_f32 v[20:21], v[168:169], v[220:221] op_sel_hi:[0,1]
	v_pk_fma_f32 v[108:109], v[118:119], v[162:163], v[108:109] op_sel_hi:[1,0,1]
	v_pk_mul_f32 v[22:23], v[168:169], v[222:223] op_sel_hi:[0,1]
	v_pk_fma_f32 v[16:17], v[148:149], v[166:167], v[16:17] op_sel_hi:[1,0,1]
	v_pk_fma_f32 v[18:19], v[150:151], v[166:167], v[18:19] op_sel_hi:[1,0,1]
	v_pk_fma_f32 v[32:33], v[170:171], v[166:167], v[32:33] op_sel_hi:[1,0,1]
	v_pk_fma_f32 v[34:35], v[172:173], v[166:167], v[34:35] op_sel_hi:[1,0,1]
	v_pk_fma_f32 v[24:25], v[124:125], v[166:167], v[24:25] op_sel_hi:[1,0,1]
	v_pk_fma_f32 v[26:27], v[126:127], v[166:167], v[26:27] op_sel_hi:[1,0,1]
	v_pk_fma_f32 v[20:21], v[116:117], v[166:167], v[20:21] op_sel_hi:[1,0,1]
	v_pk_fma_f32 v[22:23], v[108:109], v[166:167], v[22:23] op_sel_hi:[1,0,1]
	global_store_dwordx4 v[140:141], v[16:19], off offset:-32
	global_store_dwordx4 v[140:141], v[32:35], off offset:-16
	global_store_dwordx4 v[140:141], v[24:27], off
	global_store_dwordx4 v[140:141], v[20:23], off offset:16
	s_and_saveexec_b64 s[16:17], vcc
	s_cbranch_execz .Lsmp_h6_743
	v_lshlrev_b32_e32 v111, 16, v209
	v_mul_f32_e32 v156, 0xbfb8aa3b, v111
	v_exp_f32_e32 v156, v156
	ds_read_b32 v158, v189
	s_waitcnt lgkmcnt(1)
	v_add_f32_e32 v2, v2, v110
	v_add_f32_e32 v156, 1.0, v156
	v_rcp_f32_e32 v156, v156
	s_waitcnt lgkmcnt(0)
	v_fmac_f32_e32 v2, s12, v158
	v_mul_f32_e32 v110, v156, v111
	v_mul_f32_e32 v2, v110, v2
	ds_write_b32 v189, v2 offset:12544

.Lsmp_h6_end:
	s_or_b64 exec, exec, s[16:17]
	s_add_i32 s13, s13, 4
	s_waitcnt lgkmcnt(0)
	s_mov_b64 s[14:15], 0x8000
	v_lshl_add_u64 v[140:141], v[140:141], 0, s[14:15]
	v_lshl_add_u64 v[144:145], v[144:145], 0, s[14:15]
	v_add_u32_e32 v185, 0x100, v185
	s_lshl_b32 s14, s57, 5
	s_add_u32 s14, s60, s14
	s_addc_u32 s15, s61, 0
	s_nop 0
	s_load_dword s12, s[2:3], 0x1c
	s_load_dword s14, s[14:15], 0x1c
	v_and_b32_e32 v2, 7, v157
	v_cmp_eq_u32_e32 vcc, 7, v2
	v_add_u32_e32 v189, 0, v185
	s_waitcnt lgkmcnt(0)
	v_mov_b32_e32 v2, s14
	s_mov_b32 s14, 0x3fb8aa3b
	s_waitcnt vmcnt(12)
	v_mul_f32_e32 v68, 0x3fb8aa3b, v2
	v_fma_f32 v69, v2, s14, -v68
	v_rndne_f32_e32 v70, v68
	v_fmac_f32_e32 v69, 0x32a5705f, v2
	v_sub_f32_e32 v68, v68, v70
	v_add_f32_e32 v68, v68, v69
	v_exp_f32_e32 v68, v68
	v_cvt_i32_f32_e32 v69, v70
	s_mov_b32 s14, 0xc2ce8ed0
	v_cmp_ngt_f32_e64 s[38:39], s14, v2
	s_mov_b32 s14, 0x42b17218
	v_ldexp_f32 v68, v68, v69
	v_cndmask_b32_e64 v68, 0, v68, s[38:39]
	v_cmp_nlt_f32_e64 s[38:39], s14, v2
	s_add_i32 s14, s13, 0
	v_mov_b32_e32 v72, s14
	v_cndmask_b32_e64 v116, v203, v68, s[38:39]
	ds_read2_b32 v[68:69], v72 offset1:8
	ds_read2st64_b32 v[70:71], v189 offset1:8
	ds_read_b128 v[104:107], v137 offset:10240
	ds_read_b128 v[112:115], v137 offset:10256
	ds_read_b128 v[120:123], v137 offset:10272
	ds_read_b128 v[108:111], v137 offset:10288
	s_waitcnt lgkmcnt(5)
	v_mul_f32_e64 v2, v68, -v116
	s_waitcnt lgkmcnt(4)
	v_mul_f32_e32 v156, v68, v70
	v_mul_f32_e64 v68, v69, -v116
	v_mul_f32_e32 v68, 0x3fb8aa3b, v68
	v_exp_f32_e32 v158, v68
	v_mul_f32_e32 v160, v69, v71
	ds_read_b128 v[100:103], v137 offset:10752
	ds_read_b128 v[96:99], v137 offset:10768
	ds_read_b128 v[92:95], v137 offset:10784
	ds_read_b128 v[88:91], v137 offset:10800
	ds_read2_b32 v[68:69], v72 offset0:16 offset1:24
	v_mul_f32_e32 v2, 0x3fb8aa3b, v2
	v_exp_f32_e32 v2, v2
	s_waitcnt lgkmcnt(0)
	v_mul_f32_e64 v70, v68, -v116
	v_mul_f32_e32 v70, 0x3fb8aa3b, v70
	v_exp_f32_e32 v162, v70
	ds_read2st64_b32 v[70:71], v189 offset0:16 offset1:24
	ds_read_b128 v[84:87], v137 offset:11264
	ds_read_b128 v[80:83], v137 offset:11280
	ds_read_b128 v[76:79], v137 offset:11296
	ds_read_b128 v[72:75], v137 offset:11312
	s_waitcnt lgkmcnt(4)
	v_mul_f32_e32 v164, v68, v70
	v_mul_f32_e64 v68, v69, -v116
	v_mul_f32_e32 v68, 0x3fb8aa3b, v68
	v_exp_f32_e32 v166, v68
	v_mul_f32_e32 v168, v69, v71
	ds_read_b128 v[68:71], v137 offset:11776
	ds_read_b128 v[148:151], v137 offset:8192
	ds_read_b128 v[170:173], v137 offset:8208
	ds_read_b128 v[124:127], v137 offset:8224
	ds_read_b128 v[116:119], v137 offset:8240
	ds_read_b128 v[152:155], v137 offset:8704
	ds_read_b128 v[174:177], v137 offset:9216
	s_waitcnt lgkmcnt(5)
	v_pk_mul_f32 v[148:149], v[156:157], v[148:149] op_sel_hi:[0,1]
	v_pk_fma_f32 v[64:65], v[64:65], v[2:3], v[148:149] op_sel_hi:[1,0,1]
	s_waitcnt lgkmcnt(4)
	v_pk_mul_f32 v[170:171], v[156:157], v[170:171] op_sel_hi:[0,1]
	v_fma_f32 v210, v64, v104, 0
	v_fmac_f32_e32 v210, v65, v105
	s_waitcnt lgkmcnt(1)
	v_pk_mul_f32 v[104:105], v[160:161], v[152:153] op_sel_hi:[0,1]
	v_pk_fma_f32 v[152:153], v[64:65], v[158:159], v[104:105] op_sel_hi:[1,0,1]
	v_pk_mul_f32 v[104:105], v[156:157], v[150:151] op_sel_hi:[0,1]
	v_pk_fma_f32 v[66:67], v[66:67], v[2:3], v[104:105] op_sel_hi:[1,0,1]
	v_pk_fma_f32 v[60:61], v[60:61], v[2:3], v[170:171] op_sel_hi:[1,0,1]
	v_fmac_f32_e32 v210, v66, v106
	v_fmac_f32_e32 v210, v67, v107
	v_fmac_f32_e32 v210, v60, v112
	v_fmac_f32_e32 v210, v61, v113
	v_pk_mul_f32 v[112:113], v[156:157], v[172:173] op_sel_hi:[0,1]
	v_pk_fma_f32 v[62:63], v[62:63], v[2:3], v[112:113] op_sel_hi:[1,0,1]
	v_pk_mul_f32 v[124:125], v[156:157], v[124:125] op_sel_hi:[0,1]
	v_fmac_f32_e32 v210, v62, v114
	v_fmac_f32_e32 v210, v63, v115
	v_pk_fma_f32 v[56:57], v[56:57], v[2:3], v[124:125] op_sel_hi:[1,0,1]
	ds_read_b128 v[178:181], v137 offset:9728
	ds_read_b128 v[212:215], v137 offset:9744
	v_fmac_f32_e32 v210, v56, v120
	v_fmac_f32_e32 v210, v57, v121
	v_pk_mul_f32 v[120:121], v[156:157], v[126:127] op_sel_hi:[0,1]
	v_pk_fma_f32 v[58:59], v[58:59], v[2:3], v[120:121] op_sel_hi:[1,0,1]
	v_pk_mul_f32 v[116:117], v[156:157], v[116:117] op_sel_hi:[0,1]
	v_fmac_f32_e32 v210, v58, v122
	v_fmac_f32_e32 v210, v59, v123
	v_pk_fma_f32 v[52:53], v[52:53], v[2:3], v[116:117] op_sel_hi:[1,0,1]
	v_pk_mul_f32 v[104:105], v[160:161], v[154:155] op_sel_hi:[0,1]
	v_fmac_f32_e32 v210, v52, v108
	s_waitcnt lgkmcnt(2)
	v_pk_mul_f32 v[64:65], v[164:165], v[174:175] op_sel_hi:[0,1]
	v_pk_fma_f32 v[154:155], v[66:67], v[158:159], v[104:105] op_sel_hi:[1,0,1]
	v_pk_mul_f32 v[104:105], v[164:165], v[176:177] op_sel_hi:[0,1]
	ds_read_b128 v[174:177], v137 offset:8720
	v_fmac_f32_e32 v210, v53, v109
	v_pk_mul_f32 v[108:109], v[156:157], v[118:119] op_sel_hi:[0,1]
	v_pk_fma_f32 v[148:149], v[152:153], v[162:163], v[64:65] op_sel_hi:[1,0,1]
	s_waitcnt lgkmcnt(2)
	v_pk_mul_f32 v[64:65], v[168:169], v[178:179] op_sel_hi:[0,1]
	v_pk_mul_f32 v[66:67], v[168:169], v[180:181] op_sel_hi:[0,1]
	ds_read_b128 v[178:181], v137 offset:9232
	v_pk_fma_f32 v[54:55], v[54:55], v[2:3], v[108:109] op_sel_hi:[1,0,1]
	s_waitcnt lgkmcnt(1)
	v_pk_mul_f32 v[170:171], v[160:161], v[174:175] op_sel_hi:[0,1]
	v_fmac_f32_e32 v210, v54, v110
	v_fmac_f32_e32 v210, v55, v111
	ds_bpermute_b32 v2, v161, v210
	v_pk_mul_f32 v[112:113], v[160:161], v[176:177] op_sel_hi:[0,1]
	v_pk_fma_f32 v[174:175], v[60:61], v[158:159], v[170:171] op_sel_hi:[1,0,1]
	s_waitcnt lgkmcnt(1)
	v_pk_mul_f32 v[170:171], v[164:165], v[178:179] op_sel_hi:[0,1]
	v_pk_fma_f32 v[176:177], v[62:63], v[158:159], v[112:113] op_sel_hi:[1,0,1]
	v_pk_mul_f32 v[112:113], v[164:165], v[180:181] op_sel_hi:[0,1]
	ds_read_b128 v[178:181], v137 offset:8736
	v_pk_mul_f32 v[60:61], v[168:169], v[212:213] op_sel_hi:[0,1]
	v_pk_mul_f32 v[62:63], v[168:169], v[214:215] op_sel_hi:[0,1]
	ds_read_b128 v[212:215], v137 offset:9248
	ds_read_b128 v[216:219], v137 offset:9760
	ds_read_b128 v[220:223], v137 offset:9776
	s_waitcnt lgkmcnt(4)
	v_add_f32_e32 v2, v210, v2
	ds_bpermute_b32 v110, v163, v2
	s_waitcnt lgkmcnt(4)
	v_pk_mul_f32 v[124:125], v[160:161], v[178:179] op_sel_hi:[0,1]
	v_pk_mul_f32 v[120:121], v[160:161], v[180:181] op_sel_hi:[0,1]
	v_pk_fma_f32 v[178:179], v[56:57], v[158:159], v[124:125] op_sel_hi:[1,0,1]
	s_waitcnt lgkmcnt(3)
	v_pk_mul_f32 v[124:125], v[164:165], v[212:213] op_sel_hi:[0,1]
	v_pk_fma_f32 v[180:181], v[58:59], v[158:159], v[120:121] op_sel_hi:[1,0,1]
	v_pk_mul_f32 v[120:121], v[164:165], v[214:215] op_sel_hi:[0,1]
	ds_read_b128 v[212:215], v137 offset:8752
	s_waitcnt lgkmcnt(3)
	v_pk_mul_f32 v[56:57], v[168:169], v[216:217] op_sel_hi:[0,1]
	v_pk_mul_f32 v[58:59], v[168:169], v[218:219] op_sel_hi:[0,1]
	ds_read_b128 v[216:219], v137 offset:9264
	s_waitcnt lgkmcnt(2)
	v_add_f32_e32 v2, v2, v110
	v_pk_fma_f32 v[150:151], v[154:155], v[162:163], v[104:105] op_sel_hi:[1,0,1]
	ds_read_b128 v[104:107], v137 offset:11792
	v_pk_fma_f32 v[172:173], v[176:177], v[162:163], v[112:113] op_sel_hi:[1,0,1]
	ds_read_b128 v[112:115], v137 offset:11808
	v_pk_fma_f32 v[126:127], v[180:181], v[162:163], v[120:121] op_sel_hi:[1,0,1]
	ds_read_b128 v[120:123], v137 offset:11824
	ds_bpermute_b32 v110, v165, v2
	s_waitcnt lgkmcnt(5)
	v_pk_mul_f32 v[116:117], v[160:161], v[212:213] op_sel_hi:[0,1]
	v_pk_mul_f32 v[108:109], v[160:161], v[214:215] op_sel_hi:[0,1]
	v_pk_fma_f32 v[182:183], v[52:53], v[158:159], v[116:117] op_sel_hi:[1,0,1]
	s_waitcnt lgkmcnt(4)
	v_pk_mul_f32 v[116:117], v[164:165], v[216:217] op_sel_hi:[0,1]
	v_pk_fma_f32 v[118:119], v[54:55], v[158:159], v[108:109] op_sel_hi:[1,0,1]
	v_pk_mul_f32 v[108:109], v[164:165], v[218:219] op_sel_hi:[0,1]
	v_pk_fma_f32 v[170:171], v[174:175], v[162:163], v[170:171] op_sel_hi:[1,0,1]
	v_pk_fma_f32 v[124:125], v[178:179], v[162:163], v[124:125] op_sel_hi:[1,0,1]
	v_pk_fma_f32 v[116:117], v[182:183], v[162:163], v[116:117] op_sel_hi:[1,0,1]
	v_pk_mul_f32 v[52:53], v[168:169], v[220:221] op_sel_hi:[0,1]
	v_pk_fma_f32 v[108:109], v[118:119], v[162:163], v[108:109] op_sel_hi:[1,0,1]
	v_pk_mul_f32 v[54:55], v[168:169], v[222:223] op_sel_hi:[0,1]
	v_pk_fma_f32 v[64:65], v[148:149], v[166:167], v[64:65] op_sel_hi:[1,0,1]
	v_pk_fma_f32 v[66:67], v[150:151], v[166:167], v[66:67] op_sel_hi:[1,0,1]
	v_pk_fma_f32 v[60:61], v[170:171], v[166:167], v[60:61] op_sel_hi:[1,0,1]
	v_pk_fma_f32 v[62:63], v[172:173], v[166:167], v[62:63] op_sel_hi:[1,0,1]
	v_pk_fma_f32 v[56:57], v[124:125], v[166:167], v[56:57] op_sel_hi:[1,0,1]
	v_pk_fma_f32 v[58:59], v[126:127], v[166:167], v[58:59] op_sel_hi:[1,0,1]
	v_pk_fma_f32 v[52:53], v[116:117], v[166:167], v[52:53] op_sel_hi:[1,0,1]
	v_pk_fma_f32 v[54:55], v[108:109], v[166:167], v[54:55] op_sel_hi:[1,0,1]
	global_store_dwordx4 v[140:141], v[64:67], off offset:-32
	global_store_dwordx4 v[140:141], v[60:63], off offset:-16
	global_store_dwordx4 v[140:141], v[56:59], off
	global_store_dwordx4 v[140:141], v[52:55], off offset:16
	s_and_saveexec_b64 s[16:17], vcc
	s_cbranch_execz .Lsmp_h7_743
	v_lshlrev_b32_e32 v111, 16, v209
	v_mul_f32_e32 v156, 0xbfb8aa3b, v111
	v_exp_f32_e32 v156, v156
	ds_read_b32 v158, v189
	s_waitcnt lgkmcnt(1)
	v_add_f32_e32 v2, v2, v110
	v_add_f32_e32 v156, 1.0, v156
	v_rcp_f32_e32 v156, v156
	s_waitcnt lgkmcnt(0)
	v_fmac_f32_e32 v2, s12, v158
	v_mul_f32_e32 v110, v156, v111
	v_mul_f32_e32 v2, v110, v2
	ds_write_b32 v189, v2 offset:12544

.Lsmp_h7_end:
	s_or_b64 exec, exec, s[16:17]
	s_add_i32 s13, s13, 4
	s_waitcnt lgkmcnt(0)
	s_mov_b64 s[14:15], 0x8000
	v_lshl_add_u64 v[140:141], v[140:141], 0, s[14:15]
	v_lshl_add_u64 v[144:145], v[144:145], 0, s[14:15]
	v_add_u32_e32 v185, 0x100, v185
	s_mov_b32 s12, 8
	s_mov_b64 s[6:7], 0x400
	s_add_i32 s8, s8, 0x200
	s_add_u32 s2, s2, 32
	s_addc_u32 s3, s3, 0
	v_lshl_add_u64 v[128:129], v[128:129], 0, 32
	v_and_b32_e32 v2, 7, v157
	v_cmp_eq_u32_e32 vcc, 0, v2

.LBB0_814:
	v_bfe_u32 v214, v193, 4, 1
	v_mul_u32_u24_e32 v214, 24, v214
	v_mov_b32_e32 v215, 0
	v_lshl_add_u32 v148, s12, 8, v209
	v_lshl_or_b32 v144, s8, 8, v211
	v_ashrrev_i32_e32 v145, 31, v144
	v_ashrrev_i32_e32 v149, 31, v148
	v_lshl_add_u64 v[146:147], v[144:145], 1, s[20:21]
	v_lshlrev_b64 v[150:151], 11, v[148:149]
	v_or_b32_e32 v168, 16, v148
	v_lshl_add_u64 v[150:151], v[146:147], 0, v[150:151]
	v_ashrrev_i32_e32 v169, 31, v168
	v_lshl_add_u64 v[150:151], v[150:151], 0, v[214:215]
	global_load_dwordx4 v[216:219], v[150:151], off
	global_load_dwordx4 v[220:223], v[150:151], off offset:256
	v_lshlrev_b64 v[150:151], 11, v[168:169]
	v_or_b32_e32 v158, 32, v148
	v_lshl_add_u64 v[150:151], v[146:147], 0, v[150:151]
	v_ashrrev_i32_e32 v159, 31, v158
	v_lshl_add_u64 v[150:151], v[150:151], 0, v[214:215]
	global_load_dwordx4 v[224:227], v[150:151], off
	global_load_dwordx4 v[228:231], v[150:151], off offset:256
	v_lshlrev_b64 v[150:151], 11, v[158:159]
	v_lshl_add_u64 v[150:151], v[146:147], 0, v[150:151]
	v_lshl_add_u64 v[150:151], v[150:151], 0, v[214:215]
	global_load_dwordx4 v[236:239], v[150:151], off
	global_load_dwordx4 v[240:243], v[150:151], off offset:256
	v_or_b32_e32 v150, 48, v148
	v_ashrrev_i32_e32 v151, 31, v150
	v_lshlrev_b64 v[152:153], 11, v[150:151]
	v_lshl_add_u64 v[152:153], v[146:147], 0, v[152:153]
	v_lshl_add_u64 v[152:153], v[152:153], 0, v[214:215]
	global_load_dwordx4 v[244:247], v[152:153], off
	global_load_dwordx4 v[248:251], v[152:153], off offset:256
	v_cndmask_b32_e64 v180, 0, 1, s[6:7]
	v_cmp_ne_u32_e64 s[42:43], 1, v180
	v_lshlrev_b64 v[180:181], 10, v[148:149]
	s_andn2_b64 vcc, exec, s[6:7]
	s_waitcnt vmcnt(0)
	v_permlane16_swap_b32_e32 v216, v218
	v_permlane16_swap_b32_e32 v217, v219
	v_permlane16_swap_b32_e32 v220, v222
	v_permlane16_swap_b32_e32 v221, v223
	v_permlane16_swap_b32_e32 v224, v226
	v_permlane16_swap_b32_e32 v225, v227
	v_permlane16_swap_b32_e32 v228, v230
	v_permlane16_swap_b32_e32 v229, v231
	v_permlane16_swap_b32_e32 v236, v238
	v_permlane16_swap_b32_e32 v237, v239
	v_permlane16_swap_b32_e32 v240, v242
	v_permlane16_swap_b32_e32 v241, v243
	v_permlane16_swap_b32_e32 v244, v246
	v_permlane16_swap_b32_e32 v245, v247
	v_permlane16_swap_b32_e32 v248, v250
	v_permlane16_swap_b32_e32 v249, v251
	v_lshlrev_b32_e32 v196, 16, v216
	v_and_b32_e32 v197, 0xffff0000, v216
	v_lshlrev_b32_e32 v186, 16, v217
	v_and_b32_e32 v187, 0xffff0000, v217
	v_pk_add_f32 v[130:131], v[130:131], v[186:187]
	v_pk_add_f32 v[128:129], v[128:129], v[196:197]
	v_lshl_add_u64 v[186:187], v[180:181], 2, s[78:79]
	s_cbranch_vccnz .LBB0_816
	v_lshl_add_u64 v[196:197], v[144:145], 2, v[186:187]
	global_store_dwordx4 v[196:197], v[128:131], off
.LBB0_816:
	v_lshl_add_u64 v[180:181], v[180:181], 1, s[20:21]
	v_lshl_add_u64 v[180:181], v[144:145], 1, v[180:181]
	v_cvt_pk_bf16_f32 v232, v128, v129
	v_cvt_pk_bf16_f32 v233, v130, v131
	v_lshlrev_b32_e32 v196, 16, v218
	v_and_b32_e32 v197, 0xffff0000, v218
	v_lshlrev_b32_e32 v188, 16, v219
	v_and_b32_e32 v189, 0xffff0000, v219
	v_pk_add_f32 v[126:127], v[126:127], v[188:189]
	s_and_b64 vcc, exec, s[42:43]
	v_pk_add_f32 v[124:125], v[124:125], v[196:197]
	s_cbranch_vccnz .LBB0_818
	v_lshl_add_u64 v[188:189], v[144:145], 2, v[186:187]
	global_store_dwordx4 v[188:189], v[124:127], off offset:64
.LBB0_818:
	v_cvt_pk_bf16_f32 v234, v124, v125
	v_cvt_pk_bf16_f32 v235, v126, v127
	s_nop 1
	v_permlane16_swap_b32_e32 v232, v234
	v_permlane16_swap_b32_e32 v233, v235
	v_lshl_add_u64 v[180:181], v[180:181], 0, v[214:215]
	global_store_dwordx4 v[180:181], v[232:235], off
	v_lshlrev_b32_e32 v188, 16, v220
	v_and_b32_e32 v189, 0xffff0000, v220
	v_lshlrev_b32_e32 v184, 16, v221
	v_and_b32_e32 v185, 0xffff0000, v221
	v_pk_add_f32 v[122:123], v[122:123], v[184:185]
	s_and_b64 vcc, exec, s[42:43]
	v_pk_add_f32 v[120:121], v[120:121], v[188:189]
	s_movk_i32 s62, 0x1800
	s_cbranch_vccnz .LBB0_820
	v_lshl_add_u64 v[184:185], v[144:145], 2, v[186:187]
	global_store_dwordx4 v[184:185], v[120:123], off offset:512
.LBB0_820:
	v_cvt_pk_bf16_f32 v198, v120, v121
	v_cvt_pk_bf16_f32 v199, v122, v123
	v_lshlrev_b32_e32 v184, 16, v222
	v_and_b32_e32 v185, 0xffff0000, v222
	v_lshlrev_b32_e32 v182, 16, v223
	v_and_b32_e32 v183, 0xffff0000, v223
	v_pk_add_f32 v[118:119], v[118:119], v[182:183]
	s_and_b64 vcc, exec, s[42:43]
	v_pk_add_f32 v[116:117], v[116:117], v[184:185]
	s_cbranch_vccnz .LBB0_822
	v_lshl_add_u64 v[182:183], v[144:145], 2, v[186:187]
	global_store_dwordx4 v[182:183], v[116:119], off offset:576
.LBB0_822:
	v_mul_f32_e32 v129, v129, v129
	v_mul_f32_e32 v125, v125, v125
	v_mul_f32_e32 v121, v121, v121
	v_fmac_f32_e32 v129, v128, v128
	v_mul_f32_e32 v128, v131, v131
	v_fmac_f32_e32 v125, v124, v124
	v_mul_f32_e32 v124, v127, v127
	v_fmac_f32_e32 v121, v120, v120
	v_mul_f32_e32 v120, v123, v123
	v_fmac_f32_e32 v128, v130, v130
	v_fmac_f32_e32 v124, v126, v126
	v_fmac_f32_e32 v120, v122, v122
	v_add_f32_e32 v128, v129, v128
	v_add_f32_e32 v124, v125, v124
	v_add_f32_e32 v120, v121, v120
	v_mul_f32_e32 v121, v117, v117
	v_mul_f32_e32 v122, v119, v119
	v_add_f32_e32 v124, v128, v124
	v_fmac_f32_e32 v121, v116, v116
	v_fmac_f32_e32 v122, v118, v118
	v_add_f32_e32 v120, v124, v120
	v_add_f32_e32 v121, v121, v122
	v_and_b32_e32 v122, 64, v193
	v_add_f32_e32 v121, v120, v121
	v_xor_b32_e32 v120, 16, v193
	v_add_u32_e32 v123, 64, v122
	v_cmp_lt_i32_e32 vcc, v120, v123
	s_lshl_b32 s44, s8, 2
	s_ashr_i32 s45, s44, 31
	v_cndmask_b32_e32 v120, v193, v120, vcc
	v_lshlrev_b32_e32 v120, 2, v120
	ds_bpermute_b32 v122, v120, v121
	v_cvt_pk_bf16_f32 v200, v116, v117
	v_cvt_pk_bf16_f32 v201, v118, v119
	s_nop 1
	v_permlane16_swap_b32_e32 v198, v200
	v_permlane16_swap_b32_e32 v199, v201
	global_store_dwordx4 v[180:181], v[198:201], off offset:256
	s_waitcnt lgkmcnt(0)
	v_add_f32_e32 v122, v121, v122
	v_xor_b32_e32 v121, 32, v193
	v_cmp_lt_i32_e32 vcc, v121, v123
	s_nop 1
	v_cndmask_b32_e32 v121, v193, v121, vcc
	v_lshlrev_b32_e32 v121, 2, v121
	ds_bpermute_b32 v123, v121, v122
	s_and_saveexec_b64 s[22:23], s[38:39]
	s_cbranch_execz .LBB0_824
	v_lshlrev_b64 v[116:117], 6, v[148:149]
	v_lshl_add_u64 v[116:117], s[74:75], 0, v[116:117]
	v_lshl_add_u64 v[116:117], s[44:45], 2, v[116:117]
	s_lshl_b32 s8, s51, 2
	v_lshl_add_u64 v[116:117], v[116:117], 0, s[8:9]
	s_waitcnt lgkmcnt(0)
	v_add_f32_e32 v118, v122, v123
	global_store_dword v[116:117], v118, off
.LBB0_824:
	s_or_b64 exec, exec, s[22:23]
	v_lshlrev_b64 v[116:117], 10, v[168:169]
	v_lshlrev_b32_e32 v118, 16, v224
	v_and_b32_e32 v119, 0xffff0000, v224
	v_lshlrev_b32_e32 v122, 16, v225
	s_waitcnt lgkmcnt(0)
	v_and_b32_e32 v123, 0xffff0000, v225
	v_pk_add_f32 v[114:115], v[114:115], v[122:123]
	v_pk_add_f32 v[112:113], v[112:113], v[118:119]
	s_and_b64 vcc, exec, s[42:43]
	v_lshl_add_u64 v[118:119], v[116:117], 2, s[78:79]
	s_cbranch_vccnz .LBB0_826
	v_lshl_add_u64 v[122:123], v[144:145], 2, v[118:119]
	global_store_dwordx4 v[122:123], v[112:115], off
.LBB0_826:
	v_lshl_add_u64 v[116:117], v[116:117], 1, s[20:21]
	v_lshl_add_u64 v[116:117], v[144:145], 1, v[116:117]
	v_cvt_pk_bf16_f32 v232, v112, v113
	v_cvt_pk_bf16_f32 v233, v114, v115
	v_lshlrev_b32_e32 v122, 16, v226
	v_and_b32_e32 v123, 0xffff0000, v226
	v_lshlrev_b32_e32 v124, 16, v227
	v_and_b32_e32 v125, 0xffff0000, v227
	v_pk_add_f32 v[110:111], v[110:111], v[124:125]
	s_and_b64 vcc, exec, s[42:43]
	v_pk_add_f32 v[108:109], v[108:109], v[122:123]
	s_cbranch_vccnz .LBB0_828
	v_lshl_add_u64 v[122:123], v[144:145], 2, v[118:119]
	global_store_dwordx4 v[122:123], v[108:111], off offset:64
.LBB0_828:
	v_cvt_pk_bf16_f32 v234, v108, v109
	v_cvt_pk_bf16_f32 v235, v110, v111
	s_nop 1
	v_permlane16_swap_b32_e32 v232, v234
	v_permlane16_swap_b32_e32 v233, v235
	v_lshl_add_u64 v[116:117], v[116:117], 0, v[214:215]
	global_store_dwordx4 v[116:117], v[232:235], off
	v_lshlrev_b32_e32 v122, 16, v228
	v_and_b32_e32 v123, 0xffff0000, v228
	v_lshlrev_b32_e32 v124, 16, v229
	v_and_b32_e32 v125, 0xffff0000, v229
	v_pk_add_f32 v[106:107], v[106:107], v[124:125]
	s_and_b64 vcc, exec, s[42:43]
	v_pk_add_f32 v[104:105], v[104:105], v[122:123]
	s_cbranch_vccnz .LBB0_830
	v_lshl_add_u64 v[122:123], v[144:145], 2, v[118:119]
	global_store_dwordx4 v[122:123], v[104:107], off offset:512
.LBB0_830:
	v_cvt_pk_bf16_f32 v198, v104, v105
	v_cvt_pk_bf16_f32 v199, v106, v107
	v_lshlrev_b32_e32 v122, 16, v230
	v_and_b32_e32 v123, 0xffff0000, v230
	v_lshlrev_b32_e32 v124, 16, v231
	v_and_b32_e32 v125, 0xffff0000, v231
	v_pk_add_f32 v[102:103], v[102:103], v[124:125]
	s_and_b64 vcc, exec, s[42:43]
	v_pk_add_f32 v[100:101], v[100:101], v[122:123]
	s_cbranch_vccnz .LBB0_832
	v_lshl_add_u64 v[118:119], v[144:145], 2, v[118:119]
	global_store_dwordx4 v[118:119], v[100:103], off offset:576
.LBB0_832:
	v_mul_f32_e32 v113, v113, v113
	v_mul_f32_e32 v109, v109, v109
	v_mul_f32_e32 v105, v105, v105
	v_fmac_f32_e32 v113, v112, v112
	v_mul_f32_e32 v112, v115, v115
	v_fmac_f32_e32 v109, v108, v108
	v_mul_f32_e32 v108, v111, v111
	v_fmac_f32_e32 v105, v104, v104
	v_mul_f32_e32 v104, v107, v107
	v_fmac_f32_e32 v112, v114, v114
	v_fmac_f32_e32 v108, v110, v110
	v_fmac_f32_e32 v104, v106, v106
	v_add_f32_e32 v112, v113, v112
	v_add_f32_e32 v108, v109, v108
	v_add_f32_e32 v104, v105, v104
	v_mul_f32_e32 v105, v101, v101
	v_mul_f32_e32 v106, v103, v103
	v_add_f32_e32 v108, v112, v108
	v_fmac_f32_e32 v105, v100, v100
	v_fmac_f32_e32 v106, v102, v102
	v_add_f32_e32 v104, v108, v104
	v_add_f32_e32 v105, v105, v106
	v_add_f32_e32 v104, v104, v105
	ds_bpermute_b32 v105, v120, v104
	v_cvt_pk_bf16_f32 v200, v100, v101
	v_cvt_pk_bf16_f32 v201, v102, v103
	s_nop 1
	v_permlane16_swap_b32_e32 v198, v200
	v_permlane16_swap_b32_e32 v199, v201
	global_store_dwordx4 v[116:117], v[198:201], off offset:256
	s_waitcnt lgkmcnt(0)
	v_add_f32_e32 v104, v104, v105
	ds_bpermute_b32 v105, v121, v104
	s_and_saveexec_b64 s[22:23], s[38:39]
	s_cbranch_execz .LBB0_834
	v_lshlrev_b64 v[100:101], 6, v[168:169]
	v_lshl_add_u64 v[100:101], s[74:75], 0, v[100:101]
	v_lshl_add_u64 v[100:101], s[44:45], 2, v[100:101]
	s_lshl_b32 s8, s51, 2
	v_lshl_add_u64 v[100:101], v[100:101], 0, s[8:9]
	s_waitcnt lgkmcnt(0)
	v_add_f32_e32 v102, v104, v105
	global_store_dword v[100:101], v102, off
.LBB0_834:
	s_or_b64 exec, exec, s[22:23]
	v_lshlrev_b64 v[100:101], 10, v[158:159]
	v_lshlrev_b32_e32 v102, 16, v236
	v_and_b32_e32 v103, 0xffff0000, v236
	v_lshlrev_b32_e32 v104, 16, v237
	s_waitcnt lgkmcnt(0)
	v_and_b32_e32 v105, 0xffff0000, v237
	v_pk_add_f32 v[98:99], v[98:99], v[104:105]
	v_pk_add_f32 v[96:97], v[96:97], v[102:103]
	s_and_b64 vcc, exec, s[42:43]
	v_lshl_add_u64 v[102:103], v[100:101], 2, s[78:79]
	s_cbranch_vccnz .LBB0_836
	v_lshl_add_u64 v[104:105], v[144:145], 2, v[102:103]
	global_store_dwordx4 v[104:105], v[96:99], off
.LBB0_836:
	v_lshl_add_u64 v[100:101], v[100:101], 1, s[20:21]
	v_lshl_add_u64 v[100:101], v[144:145], 1, v[100:101]
	v_cvt_pk_bf16_f32 v232, v96, v97
	v_cvt_pk_bf16_f32 v233, v98, v99
	v_lshlrev_b32_e32 v104, 16, v238
	v_and_b32_e32 v105, 0xffff0000, v238
	v_lshlrev_b32_e32 v106, 16, v239
	v_and_b32_e32 v107, 0xffff0000, v239
	v_pk_add_f32 v[94:95], v[94:95], v[106:107]
	s_and_b64 vcc, exec, s[42:43]
	v_pk_add_f32 v[92:93], v[92:93], v[104:105]
	s_cbranch_vccnz .LBB0_838
	v_lshl_add_u64 v[104:105], v[144:145], 2, v[102:103]
	global_store_dwordx4 v[104:105], v[92:95], off offset:64
.LBB0_838:
	v_cvt_pk_bf16_f32 v234, v92, v93
	v_cvt_pk_bf16_f32 v235, v94, v95
	s_nop 1
	v_permlane16_swap_b32_e32 v232, v234
	v_permlane16_swap_b32_e32 v233, v235
	v_lshl_add_u64 v[100:101], v[100:101], 0, v[214:215]
	global_store_dwordx4 v[100:101], v[232:235], off
	v_lshlrev_b32_e32 v104, 16, v240
	v_and_b32_e32 v105, 0xffff0000, v240
	v_lshlrev_b32_e32 v106, 16, v241
	v_and_b32_e32 v107, 0xffff0000, v241
	v_pk_add_f32 v[90:91], v[90:91], v[106:107]
	s_and_b64 vcc, exec, s[42:43]
	v_pk_add_f32 v[88:89], v[88:89], v[104:105]
	s_cbranch_vccnz .LBB0_840
	v_lshl_add_u64 v[104:105], v[144:145], 2, v[102:103]
	global_store_dwordx4 v[104:105], v[88:91], off offset:512
.LBB0_840:
	v_cvt_pk_bf16_f32 v198, v88, v89
	v_cvt_pk_bf16_f32 v199, v90, v91
	v_lshlrev_b32_e32 v104, 16, v242
	v_and_b32_e32 v105, 0xffff0000, v242
	v_lshlrev_b32_e32 v106, 16, v243
	v_and_b32_e32 v107, 0xffff0000, v243
	v_pk_add_f32 v[86:87], v[86:87], v[106:107]
	s_and_b64 vcc, exec, s[42:43]
	v_pk_add_f32 v[84:85], v[84:85], v[104:105]
	s_cbranch_vccnz .LBB0_842
	v_lshl_add_u64 v[102:103], v[144:145], 2, v[102:103]
	global_store_dwordx4 v[102:103], v[84:87], off offset:576
.LBB0_842:
	v_mul_f32_e32 v97, v97, v97
	v_mul_f32_e32 v93, v93, v93
	v_mul_f32_e32 v89, v89, v89
	v_fmac_f32_e32 v97, v96, v96
	v_mul_f32_e32 v96, v99, v99
	v_fmac_f32_e32 v93, v92, v92
	v_mul_f32_e32 v92, v95, v95
	v_fmac_f32_e32 v89, v88, v88
	v_mul_f32_e32 v88, v91, v91
	v_fmac_f32_e32 v96, v98, v98
	v_fmac_f32_e32 v92, v94, v94
	v_fmac_f32_e32 v88, v90, v90
	v_add_f32_e32 v96, v97, v96
	v_add_f32_e32 v92, v93, v92
	v_add_f32_e32 v88, v89, v88
	v_mul_f32_e32 v89, v85, v85
	v_mul_f32_e32 v90, v87, v87
	v_add_f32_e32 v92, v96, v92
	v_fmac_f32_e32 v89, v84, v84
	v_fmac_f32_e32 v90, v86, v86
	v_add_f32_e32 v88, v92, v88
	v_add_f32_e32 v89, v89, v90
	v_add_f32_e32 v88, v88, v89
	ds_bpermute_b32 v89, v120, v88
	v_cvt_pk_bf16_f32 v200, v84, v85
	v_cvt_pk_bf16_f32 v201, v86, v87
	s_nop 1
	v_permlane16_swap_b32_e32 v198, v200
	v_permlane16_swap_b32_e32 v199, v201
	global_store_dwordx4 v[100:101], v[198:201], off offset:256
	s_waitcnt lgkmcnt(0)
	v_add_f32_e32 v88, v88, v89
	ds_bpermute_b32 v89, v121, v88
	s_and_saveexec_b64 s[22:23], s[38:39]
	s_cbranch_execz .LBB0_844
	v_lshlrev_b64 v[84:85], 6, v[158:159]
	v_lshl_add_u64 v[84:85], s[74:75], 0, v[84:85]
	v_lshl_add_u64 v[84:85], s[44:45], 2, v[84:85]
	s_lshl_b32 s8, s51, 2
	v_lshl_add_u64 v[84:85], v[84:85], 0, s[8:9]
	s_waitcnt lgkmcnt(0)
	v_add_f32_e32 v86, v88, v89
	global_store_dword v[84:85], v86, off
.LBB0_844:
	s_or_b64 exec, exec, s[22:23]
	v_lshlrev_b64 v[84:85], 10, v[150:151]
	v_lshlrev_b32_e32 v86, 16, v244
	v_and_b32_e32 v87, 0xffff0000, v244
	v_lshlrev_b32_e32 v88, 16, v245
	s_waitcnt lgkmcnt(0)
	v_and_b32_e32 v89, 0xffff0000, v245
	v_pk_add_f32 v[82:83], v[82:83], v[88:89]
	v_pk_add_f32 v[80:81], v[80:81], v[86:87]
	s_and_b64 vcc, exec, s[42:43]
	v_lshl_add_u64 v[86:87], v[84:85], 2, s[78:79]
	s_cbranch_vccnz .LBB0_846
	v_lshl_add_u64 v[88:89], v[144:145], 2, v[86:87]
	global_store_dwordx4 v[88:89], v[80:83], off
.LBB0_846:
	v_lshl_add_u64 v[84:85], v[84:85], 1, s[20:21]
	v_lshl_add_u64 v[84:85], v[144:145], 1, v[84:85]
	v_cvt_pk_bf16_f32 v232, v80, v81
	v_cvt_pk_bf16_f32 v233, v82, v83
	v_lshlrev_b32_e32 v88, 16, v246
	v_and_b32_e32 v89, 0xffff0000, v246
	v_lshlrev_b32_e32 v90, 16, v247
	v_and_b32_e32 v91, 0xffff0000, v247
	v_pk_add_f32 v[78:79], v[78:79], v[90:91]
	s_and_b64 vcc, exec, s[42:43]
	v_pk_add_f32 v[76:77], v[76:77], v[88:89]
	s_cbranch_vccnz .LBB0_848
	v_lshl_add_u64 v[88:89], v[144:145], 2, v[86:87]
	global_store_dwordx4 v[88:89], v[76:79], off offset:64
.LBB0_848:
	v_cvt_pk_bf16_f32 v234, v76, v77
	v_cvt_pk_bf16_f32 v235, v78, v79
	s_nop 1
	v_permlane16_swap_b32_e32 v232, v234
	v_permlane16_swap_b32_e32 v233, v235
	v_lshl_add_u64 v[84:85], v[84:85], 0, v[214:215]
	global_store_dwordx4 v[84:85], v[232:235], off
	v_lshlrev_b32_e32 v88, 16, v248
	v_and_b32_e32 v89, 0xffff0000, v248
	v_lshlrev_b32_e32 v90, 16, v249
	v_and_b32_e32 v91, 0xffff0000, v249
	v_pk_add_f32 v[74:75], v[74:75], v[90:91]
	s_and_b64 vcc, exec, s[42:43]
	v_pk_add_f32 v[72:73], v[72:73], v[88:89]
	s_cbranch_vccnz .LBB0_850
	v_lshl_add_u64 v[88:89], v[144:145], 2, v[86:87]
	global_store_dwordx4 v[88:89], v[72:75], off offset:512
.LBB0_850:
	v_cvt_pk_bf16_f32 v198, v72, v73
	v_cvt_pk_bf16_f32 v199, v74, v75
	v_lshlrev_b32_e32 v88, 16, v250
	v_and_b32_e32 v89, 0xffff0000, v250
	v_lshlrev_b32_e32 v90, 16, v251
	v_and_b32_e32 v91, 0xffff0000, v251
	v_pk_add_f32 v[70:71], v[70:71], v[90:91]
	s_and_b64 vcc, exec, s[42:43]
	v_pk_add_f32 v[68:69], v[68:69], v[88:89]
	s_cbranch_vccnz .LBB0_852
	v_lshl_add_u64 v[86:87], v[144:145], 2, v[86:87]
	global_store_dwordx4 v[86:87], v[68:71], off offset:576
.LBB0_852:
	v_mul_f32_e32 v81, v81, v81
	v_mul_f32_e32 v77, v77, v77
	v_mul_f32_e32 v73, v73, v73
	v_fmac_f32_e32 v81, v80, v80
	v_mul_f32_e32 v80, v83, v83
	v_fmac_f32_e32 v77, v76, v76
	v_mul_f32_e32 v76, v79, v79
	v_fmac_f32_e32 v73, v72, v72
	v_mul_f32_e32 v72, v75, v75
	v_fmac_f32_e32 v80, v82, v82
	v_fmac_f32_e32 v76, v78, v78
	v_fmac_f32_e32 v72, v74, v74
	v_add_f32_e32 v80, v81, v80
	v_add_f32_e32 v76, v77, v76
	v_add_f32_e32 v72, v73, v72
	v_mul_f32_e32 v73, v69, v69
	v_mul_f32_e32 v74, v71, v71
	v_add_f32_e32 v76, v80, v76
	v_fmac_f32_e32 v73, v68, v68
	v_fmac_f32_e32 v74, v70, v70
	v_add_f32_e32 v72, v76, v72
	v_add_f32_e32 v73, v73, v74
	v_add_f32_e32 v72, v72, v73
	ds_bpermute_b32 v73, v120, v72
	v_cvt_pk_bf16_f32 v200, v68, v69
	v_cvt_pk_bf16_f32 v201, v70, v71
	s_nop 1
	v_permlane16_swap_b32_e32 v198, v200
	v_permlane16_swap_b32_e32 v199, v201
	global_store_dwordx4 v[84:85], v[198:201], off offset:256
	s_waitcnt lgkmcnt(0)
	v_add_f32_e32 v72, v72, v73
	ds_bpermute_b32 v73, v121, v72
	s_and_saveexec_b64 s[22:23], s[38:39]
	s_cbranch_execz .LBB0_854
	v_lshlrev_b64 v[68:69], 6, v[150:151]
	v_lshl_add_u64 v[68:69], s[74:75], 0, v[68:69]
	v_lshl_add_u64 v[68:69], s[44:45], 2, v[68:69]
	s_lshl_b32 s8, s51, 2
	v_lshl_add_u64 v[68:69], v[68:69], 0, s[8:9]
	s_waitcnt lgkmcnt(0)
	v_add_f32_e32 v70, v72, v73
	global_store_dword v[68:69], v70, off
.LBB0_854:
	s_or_b64 exec, exec, s[22:23]
	v_add_u32_e32 v96, 0x80, v148
	v_ashrrev_i32_e32 v97, 31, v96
	v_lshlrev_b64 v[68:69], 11, v[96:97]
	v_add_u32_e32 v86, 0x90, v148
	v_lshl_add_u64 v[68:69], v[146:147], 0, v[68:69]
	v_ashrrev_i32_e32 v87, 31, v86
	v_lshl_add_u64 v[68:69], v[68:69], 0, v[214:215]
	global_load_dwordx4 v[216:219], v[68:69], off
	global_load_dwordx4 v[220:223], v[68:69], off offset:256
	v_lshlrev_b64 v[68:69], 11, v[86:87]
	v_add_u32_e32 v76, 0xa0, v148
	v_lshl_add_u64 v[68:69], v[146:147], 0, v[68:69]
	v_ashrrev_i32_e32 v77, 31, v76
	v_lshl_add_u64 v[68:69], v[68:69], 0, v[214:215]
	global_load_dwordx4 v[224:227], v[68:69], off
	global_load_dwordx4 v[228:231], v[68:69], off offset:256
	v_lshlrev_b64 v[68:69], 11, v[76:77]
	v_lshl_add_u64 v[68:69], v[146:147], 0, v[68:69]
	v_lshl_add_u64 v[68:69], v[68:69], 0, v[214:215]
	global_load_dwordx4 v[236:239], v[68:69], off
	global_load_dwordx4 v[240:243], v[68:69], off offset:256
	v_add_u32_e32 v68, 0xb0, v148
	v_ashrrev_i32_e32 v69, 31, v68
	v_lshlrev_b64 v[70:71], 11, v[68:69]
	v_lshl_add_u64 v[70:71], v[146:147], 0, v[70:71]
	v_lshl_add_u64 v[70:71], v[70:71], 0, v[214:215]
	global_load_dwordx4 v[244:247], v[70:71], off
	s_waitcnt lgkmcnt(0)
	global_load_dwordx4 v[248:251], v[70:71], off offset:256
	v_lshlrev_b64 v[100:101], 10, v[96:97]
	s_and_b64 vcc, exec, s[42:43]
	s_waitcnt vmcnt(0)
	v_permlane16_swap_b32_e32 v216, v218
	v_permlane16_swap_b32_e32 v217, v219
	v_permlane16_swap_b32_e32 v220, v222
	v_permlane16_swap_b32_e32 v221, v223
	v_permlane16_swap_b32_e32 v224, v226
	v_permlane16_swap_b32_e32 v225, v227
	v_permlane16_swap_b32_e32 v228, v230
	v_permlane16_swap_b32_e32 v229, v231
	v_permlane16_swap_b32_e32 v236, v238
	v_permlane16_swap_b32_e32 v237, v239
	v_permlane16_swap_b32_e32 v240, v242
	v_permlane16_swap_b32_e32 v241, v243
	v_permlane16_swap_b32_e32 v244, v246
	v_permlane16_swap_b32_e32 v245, v247
	v_permlane16_swap_b32_e32 v248, v250
	v_permlane16_swap_b32_e32 v249, v251
	v_lshlrev_b32_e32 v110, 16, v216
	v_and_b32_e32 v111, 0xffff0000, v216
	v_lshlrev_b32_e32 v106, 16, v217
	v_and_b32_e32 v107, 0xffff0000, v217
	v_pk_add_f32 v[66:67], v[66:67], v[106:107]
	v_pk_add_f32 v[64:65], v[64:65], v[110:111]
	v_lshl_add_u64 v[106:107], v[100:101], 2, s[78:79]
	s_cbranch_vccnz .LBB0_856
	v_lshl_add_u64 v[110:111], v[144:145], 2, v[106:107]
	global_store_dwordx4 v[110:111], v[64:67], off
.LBB0_856:
	v_lshl_add_u64 v[100:101], v[100:101], 1, s[20:21]
	v_lshl_add_u64 v[100:101], v[144:145], 1, v[100:101]
	v_cvt_pk_bf16_f32 v232, v64, v65
	v_cvt_pk_bf16_f32 v233, v66, v67
	s_waitcnt vmcnt(15)
	v_lshlrev_b32_e32 v110, 16, v218
	v_and_b32_e32 v111, 0xffff0000, v218
	v_lshlrev_b32_e32 v108, 16, v219
	v_and_b32_e32 v109, 0xffff0000, v219
	v_pk_add_f32 v[62:63], v[62:63], v[108:109]
	s_and_b64 vcc, exec, s[42:43]
	v_pk_add_f32 v[60:61], v[60:61], v[110:111]
	s_cbranch_vccnz .LBB0_858
	v_lshl_add_u64 v[108:109], v[144:145], 2, v[106:107]
	global_store_dwordx4 v[108:109], v[60:63], off offset:64
.LBB0_858:
	v_cvt_pk_bf16_f32 v234, v60, v61
	v_cvt_pk_bf16_f32 v235, v62, v63
	s_nop 1
	v_permlane16_swap_b32_e32 v232, v234
	v_permlane16_swap_b32_e32 v233, v235
	v_lshl_add_u64 v[100:101], v[100:101], 0, v[214:215]
	global_store_dwordx4 v[100:101], v[232:235], off
	s_waitcnt vmcnt(15)
	v_lshlrev_b32_e32 v108, 16, v220
	v_and_b32_e32 v109, 0xffff0000, v220
	v_lshlrev_b32_e32 v104, 16, v221
	v_and_b32_e32 v105, 0xffff0000, v221
	v_pk_add_f32 v[58:59], v[58:59], v[104:105]
	s_and_b64 vcc, exec, s[42:43]
	v_pk_add_f32 v[56:57], v[56:57], v[108:109]
	s_cbranch_vccnz .LBB0_860
	v_lshl_add_u64 v[104:105], v[144:145], 2, v[106:107]
	global_store_dwordx4 v[104:105], v[56:59], off offset:512
.LBB0_860:
	v_cvt_pk_bf16_f32 v198, v56, v57
	v_cvt_pk_bf16_f32 v199, v58, v59
	s_waitcnt vmcnt(15)
	v_lshlrev_b32_e32 v104, 16, v222
	v_and_b32_e32 v105, 0xffff0000, v222
	v_lshlrev_b32_e32 v102, 16, v223
	v_and_b32_e32 v103, 0xffff0000, v223
	v_pk_add_f32 v[54:55], v[54:55], v[102:103]
	s_and_b64 vcc, exec, s[42:43]
	v_pk_add_f32 v[52:53], v[52:53], v[104:105]
	s_cbranch_vccnz .LBB0_862
	v_lshl_add_u64 v[102:103], v[144:145], 2, v[106:107]
	global_store_dwordx4 v[102:103], v[52:55], off offset:576
.LBB0_862:
	v_mul_f32_e32 v65, v65, v65
	v_mul_f32_e32 v61, v61, v61
	v_mul_f32_e32 v57, v57, v57
	v_fmac_f32_e32 v65, v64, v64
	v_mul_f32_e32 v64, v67, v67
	v_fmac_f32_e32 v61, v60, v60
	v_mul_f32_e32 v60, v63, v63
	v_fmac_f32_e32 v57, v56, v56
	v_mul_f32_e32 v56, v59, v59
	v_fmac_f32_e32 v64, v66, v66
	v_fmac_f32_e32 v60, v62, v62
	v_fmac_f32_e32 v56, v58, v58
	v_add_f32_e32 v64, v65, v64
	v_add_f32_e32 v60, v61, v60
	v_add_f32_e32 v56, v57, v56
	v_mul_f32_e32 v57, v53, v53
	v_mul_f32_e32 v58, v55, v55
	v_add_f32_e32 v60, v64, v60
	v_fmac_f32_e32 v57, v52, v52
	v_fmac_f32_e32 v58, v54, v54
	v_add_f32_e32 v56, v60, v56
	v_add_f32_e32 v57, v57, v58
	v_add_f32_e32 v56, v56, v57
	ds_bpermute_b32 v57, v120, v56
	v_cvt_pk_bf16_f32 v200, v52, v53
	v_cvt_pk_bf16_f32 v201, v54, v55
	s_nop 1
	v_permlane16_swap_b32_e32 v198, v200
	v_permlane16_swap_b32_e32 v199, v201
	global_store_dwordx4 v[100:101], v[198:201], off offset:256
	s_waitcnt lgkmcnt(0)
	v_add_f32_e32 v56, v56, v57
	ds_bpermute_b32 v57, v121, v56
	s_and_saveexec_b64 s[22:23], s[38:39]
	s_cbranch_execz .LBB0_864
	v_lshlrev_b64 v[52:53], 6, v[96:97]
	v_lshl_add_u64 v[52:53], s[74:75], 0, v[52:53]
	v_lshl_add_u64 v[52:53], s[44:45], 2, v[52:53]
	s_lshl_b32 s8, s51, 2
	v_lshl_add_u64 v[52:53], v[52:53], 0, s[8:9]
	s_waitcnt lgkmcnt(0)
	v_add_f32_e32 v54, v56, v57
	global_store_dword v[52:53], v54, off
.LBB0_864:
	s_or_b64 exec, exec, s[22:23]
	v_lshlrev_b64 v[52:53], 10, v[86:87]
	s_waitcnt vmcnt(15)
	v_lshlrev_b32_e32 v54, 16, v224
	v_and_b32_e32 v55, 0xffff0000, v224
	v_lshlrev_b32_e32 v56, 16, v225
	s_waitcnt lgkmcnt(0)
	v_and_b32_e32 v57, 0xffff0000, v225
	v_pk_add_f32 v[50:51], v[50:51], v[56:57]
	v_pk_add_f32 v[48:49], v[48:49], v[54:55]
	s_and_b64 vcc, exec, s[42:43]
	v_lshl_add_u64 v[54:55], v[52:53], 2, s[78:79]
	s_cbranch_vccnz .LBB0_866
	v_lshl_add_u64 v[56:57], v[144:145], 2, v[54:55]
	global_store_dwordx4 v[56:57], v[48:51], off
.LBB0_866:
	v_lshl_add_u64 v[52:53], v[52:53], 1, s[20:21]
	v_lshl_add_u64 v[52:53], v[144:145], 1, v[52:53]
	v_cvt_pk_bf16_f32 v232, v48, v49
	v_cvt_pk_bf16_f32 v233, v50, v51
	s_waitcnt vmcnt(15)
	v_lshlrev_b32_e32 v56, 16, v226
	v_and_b32_e32 v57, 0xffff0000, v226
	v_lshlrev_b32_e32 v58, 16, v227
	v_and_b32_e32 v59, 0xffff0000, v227
	v_pk_add_f32 v[46:47], v[46:47], v[58:59]
	s_and_b64 vcc, exec, s[42:43]
	v_pk_add_f32 v[44:45], v[44:45], v[56:57]
	s_cbranch_vccnz .LBB0_868
	v_lshl_add_u64 v[56:57], v[144:145], 2, v[54:55]
	global_store_dwordx4 v[56:57], v[44:47], off offset:64
.LBB0_868:
	v_cvt_pk_bf16_f32 v234, v44, v45
	v_cvt_pk_bf16_f32 v235, v46, v47
	s_nop 1
	v_permlane16_swap_b32_e32 v232, v234
	v_permlane16_swap_b32_e32 v233, v235
	v_lshl_add_u64 v[52:53], v[52:53], 0, v[214:215]
	global_store_dwordx4 v[52:53], v[232:235], off
	s_waitcnt vmcnt(15)
	v_lshlrev_b32_e32 v56, 16, v228
	v_and_b32_e32 v57, 0xffff0000, v228
	v_lshlrev_b32_e32 v58, 16, v229
	v_and_b32_e32 v59, 0xffff0000, v229
	v_pk_add_f32 v[42:43], v[42:43], v[58:59]
	s_and_b64 vcc, exec, s[42:43]
	v_pk_add_f32 v[40:41], v[40:41], v[56:57]
	s_cbranch_vccnz .LBB0_870
	v_lshl_add_u64 v[56:57], v[144:145], 2, v[54:55]
	global_store_dwordx4 v[56:57], v[40:43], off offset:512
.LBB0_870:
	v_cvt_pk_bf16_f32 v198, v40, v41
	v_cvt_pk_bf16_f32 v199, v42, v43
	s_waitcnt vmcnt(15)
	v_lshlrev_b32_e32 v56, 16, v230
	v_and_b32_e32 v57, 0xffff0000, v230
	v_lshlrev_b32_e32 v58, 16, v231
	v_and_b32_e32 v59, 0xffff0000, v231
	v_pk_add_f32 v[38:39], v[38:39], v[58:59]
	s_and_b64 vcc, exec, s[42:43]
	v_pk_add_f32 v[36:37], v[36:37], v[56:57]
	s_cbranch_vccnz .LBB0_872
	v_lshl_add_u64 v[54:55], v[144:145], 2, v[54:55]
	global_store_dwordx4 v[54:55], v[36:39], off offset:576
.LBB0_872:
	v_mul_f32_e32 v49, v49, v49
	v_mul_f32_e32 v45, v45, v45
	v_mul_f32_e32 v41, v41, v41
	v_fmac_f32_e32 v49, v48, v48
	v_mul_f32_e32 v48, v51, v51
	v_fmac_f32_e32 v45, v44, v44
	v_mul_f32_e32 v44, v47, v47
	v_fmac_f32_e32 v41, v40, v40
	v_mul_f32_e32 v40, v43, v43
	v_fmac_f32_e32 v48, v50, v50
	v_fmac_f32_e32 v44, v46, v46
	v_fmac_f32_e32 v40, v42, v42
	v_add_f32_e32 v48, v49, v48
	v_add_f32_e32 v44, v45, v44
	v_add_f32_e32 v40, v41, v40
	v_mul_f32_e32 v41, v37, v37
	v_mul_f32_e32 v42, v39, v39
	v_add_f32_e32 v44, v48, v44
	v_fmac_f32_e32 v41, v36, v36
	v_fmac_f32_e32 v42, v38, v38
	v_add_f32_e32 v40, v44, v40
	v_add_f32_e32 v41, v41, v42
	v_add_f32_e32 v40, v40, v41
	ds_bpermute_b32 v41, v120, v40
	v_cvt_pk_bf16_f32 v200, v36, v37
	v_cvt_pk_bf16_f32 v201, v38, v39
	s_nop 1
	v_permlane16_swap_b32_e32 v198, v200
	v_permlane16_swap_b32_e32 v199, v201
	global_store_dwordx4 v[52:53], v[198:201], off offset:256
	s_waitcnt lgkmcnt(0)
	v_add_f32_e32 v40, v40, v41
	ds_bpermute_b32 v41, v121, v40
	s_and_saveexec_b64 s[22:23], s[38:39]
	s_cbranch_execz .LBB0_874
	v_lshlrev_b64 v[36:37], 6, v[86:87]
	v_lshl_add_u64 v[36:37], s[74:75], 0, v[36:37]
	v_lshl_add_u64 v[36:37], s[44:45], 2, v[36:37]
	s_lshl_b32 s8, s51, 2
	v_lshl_add_u64 v[36:37], v[36:37], 0, s[8:9]
	s_waitcnt lgkmcnt(0)
	v_add_f32_e32 v38, v40, v41
	global_store_dword v[36:37], v38, off
.LBB0_874:
	s_or_b64 exec, exec, s[22:23]
	v_lshlrev_b64 v[36:37], 10, v[76:77]
	s_waitcnt vmcnt(15)
	v_lshlrev_b32_e32 v38, 16, v236
	v_and_b32_e32 v39, 0xffff0000, v236
	v_lshlrev_b32_e32 v40, 16, v237
	s_waitcnt lgkmcnt(0)
	v_and_b32_e32 v41, 0xffff0000, v237
	v_pk_add_f32 v[34:35], v[34:35], v[40:41]
	v_pk_add_f32 v[32:33], v[32:33], v[38:39]
	s_and_b64 vcc, exec, s[42:43]
	v_lshl_add_u64 v[38:39], v[36:37], 2, s[78:79]
	s_cbranch_vccnz .LBB0_876
	v_lshl_add_u64 v[40:41], v[144:145], 2, v[38:39]
	global_store_dwordx4 v[40:41], v[32:35], off
.LBB0_876:
	v_lshl_add_u64 v[36:37], v[36:37], 1, s[20:21]
	v_lshl_add_u64 v[36:37], v[144:145], 1, v[36:37]
	v_cvt_pk_bf16_f32 v232, v32, v33
	v_cvt_pk_bf16_f32 v233, v34, v35
	s_waitcnt vmcnt(15)
	v_lshlrev_b32_e32 v40, 16, v238
	v_and_b32_e32 v41, 0xffff0000, v238
	v_lshlrev_b32_e32 v42, 16, v239
	v_and_b32_e32 v43, 0xffff0000, v239
	v_pk_add_f32 v[30:31], v[30:31], v[42:43]
	s_and_b64 vcc, exec, s[42:43]
	v_pk_add_f32 v[28:29], v[28:29], v[40:41]
	s_cbranch_vccnz .LBB0_878
	v_lshl_add_u64 v[40:41], v[144:145], 2, v[38:39]
	global_store_dwordx4 v[40:41], v[28:31], off offset:64
.LBB0_878:
	v_cvt_pk_bf16_f32 v234, v28, v29
	v_cvt_pk_bf16_f32 v235, v30, v31
	s_nop 1
	v_permlane16_swap_b32_e32 v232, v234
	v_permlane16_swap_b32_e32 v233, v235
	v_lshl_add_u64 v[36:37], v[36:37], 0, v[214:215]
	global_store_dwordx4 v[36:37], v[232:235], off
	s_waitcnt vmcnt(15)
	v_lshlrev_b32_e32 v40, 16, v240
	v_and_b32_e32 v41, 0xffff0000, v240
	v_lshlrev_b32_e32 v42, 16, v241
	v_and_b32_e32 v43, 0xffff0000, v241
	v_pk_add_f32 v[26:27], v[26:27], v[42:43]
	s_and_b64 vcc, exec, s[42:43]
	v_pk_add_f32 v[24:25], v[24:25], v[40:41]
	s_cbranch_vccnz .LBB0_880
	v_lshl_add_u64 v[40:41], v[144:145], 2, v[38:39]
	global_store_dwordx4 v[40:41], v[24:27], off offset:512
.LBB0_880:
	v_cvt_pk_bf16_f32 v198, v24, v25
	v_cvt_pk_bf16_f32 v199, v26, v27
	s_waitcnt vmcnt(15)
	v_lshlrev_b32_e32 v40, 16, v242
	v_and_b32_e32 v41, 0xffff0000, v242
	v_lshlrev_b32_e32 v42, 16, v243
	v_and_b32_e32 v43, 0xffff0000, v243
	v_pk_add_f32 v[22:23], v[22:23], v[42:43]
	s_and_b64 vcc, exec, s[42:43]
	v_pk_add_f32 v[20:21], v[20:21], v[40:41]
	s_cbranch_vccnz .LBB0_882
	v_lshl_add_u64 v[38:39], v[144:145], 2, v[38:39]
	global_store_dwordx4 v[38:39], v[20:23], off offset:576
.LBB0_882:
	v_mul_f32_e32 v33, v33, v33
	v_mul_f32_e32 v29, v29, v29
	v_mul_f32_e32 v25, v25, v25
	v_fmac_f32_e32 v33, v32, v32
	v_mul_f32_e32 v32, v35, v35
	v_fmac_f32_e32 v29, v28, v28
	v_mul_f32_e32 v28, v31, v31
	v_fmac_f32_e32 v25, v24, v24
	v_mul_f32_e32 v24, v27, v27
	v_fmac_f32_e32 v32, v34, v34
	v_fmac_f32_e32 v28, v30, v30
	v_fmac_f32_e32 v24, v26, v26
	v_add_f32_e32 v32, v33, v32
	v_add_f32_e32 v28, v29, v28
	v_add_f32_e32 v24, v25, v24
	v_mul_f32_e32 v25, v21, v21
	v_mul_f32_e32 v26, v23, v23
	v_add_f32_e32 v28, v32, v28
	v_fmac_f32_e32 v25, v20, v20
	v_fmac_f32_e32 v26, v22, v22
	v_add_f32_e32 v24, v28, v24
	v_add_f32_e32 v25, v25, v26
	v_add_f32_e32 v24, v24, v25
	ds_bpermute_b32 v25, v120, v24
	v_cvt_pk_bf16_f32 v200, v20, v21
	v_cvt_pk_bf16_f32 v201, v22, v23
	s_nop 1
	v_permlane16_swap_b32_e32 v198, v200
	v_permlane16_swap_b32_e32 v199, v201
	global_store_dwordx4 v[36:37], v[198:201], off offset:256
	s_waitcnt lgkmcnt(0)
	v_add_f32_e32 v24, v24, v25
	ds_bpermute_b32 v25, v121, v24
	s_and_saveexec_b64 s[22:23], s[38:39]
	s_cbranch_execz .LBB0_884
	v_lshlrev_b64 v[20:21], 6, v[76:77]
	v_lshl_add_u64 v[20:21], s[74:75], 0, v[20:21]
	v_lshl_add_u64 v[20:21], s[44:45], 2, v[20:21]
	s_lshl_b32 s8, s51, 2
	v_lshl_add_u64 v[20:21], v[20:21], 0, s[8:9]
	s_waitcnt lgkmcnt(0)
	v_add_f32_e32 v22, v24, v25
	global_store_dword v[20:21], v22, off
.LBB0_884:
	s_or_b64 exec, exec, s[22:23]
	v_lshlrev_b64 v[20:21], 10, v[68:69]
	s_waitcnt vmcnt(15)
	v_lshlrev_b32_e32 v22, 16, v244
	v_and_b32_e32 v23, 0xffff0000, v244
	v_lshlrev_b32_e32 v24, 16, v245
	s_waitcnt lgkmcnt(0)
	v_and_b32_e32 v25, 0xffff0000, v245
	v_pk_add_f32 v[18:19], v[18:19], v[24:25]
	v_pk_add_f32 v[16:17], v[16:17], v[22:23]
	s_and_b64 vcc, exec, s[42:43]
	v_lshl_add_u64 v[22:23], v[20:21], 2, s[78:79]
	s_cbranch_vccnz .LBB0_886
	v_lshl_add_u64 v[24:25], v[144:145], 2, v[22:23]
	global_store_dwordx4 v[24:25], v[16:19], off
.LBB0_886:
	v_lshl_add_u64 v[20:21], v[20:21], 1, s[20:21]
	v_lshl_add_u64 v[20:21], v[144:145], 1, v[20:21]
	v_cvt_pk_bf16_f32 v232, v16, v17
	v_cvt_pk_bf16_f32 v233, v18, v19
	s_waitcnt vmcnt(15)
	v_lshlrev_b32_e32 v24, 16, v246
	v_and_b32_e32 v25, 0xffff0000, v246
	v_lshlrev_b32_e32 v26, 16, v247
	v_and_b32_e32 v27, 0xffff0000, v247
	v_pk_add_f32 v[14:15], v[14:15], v[26:27]
	s_and_b64 vcc, exec, s[42:43]
	v_pk_add_f32 v[12:13], v[12:13], v[24:25]
	s_cbranch_vccnz .LBB0_888
	v_lshl_add_u64 v[24:25], v[144:145], 2, v[22:23]
	global_store_dwordx4 v[24:25], v[12:15], off offset:64
.LBB0_888:
	v_cvt_pk_bf16_f32 v234, v12, v13
	v_cvt_pk_bf16_f32 v235, v14, v15
	s_nop 1
	v_permlane16_swap_b32_e32 v232, v234
	v_permlane16_swap_b32_e32 v233, v235
	v_lshl_add_u64 v[20:21], v[20:21], 0, v[214:215]
	global_store_dwordx4 v[20:21], v[232:235], off
	s_waitcnt vmcnt(15)
	v_lshlrev_b32_e32 v24, 16, v248
	v_and_b32_e32 v25, 0xffff0000, v248
	v_lshlrev_b32_e32 v26, 16, v249
	v_and_b32_e32 v27, 0xffff0000, v249
	v_pk_add_f32 v[10:11], v[10:11], v[26:27]
	s_and_b64 vcc, exec, s[42:43]
	v_pk_add_f32 v[8:9], v[8:9], v[24:25]
	s_cbranch_vccnz .LBB0_890
	v_lshl_add_u64 v[24:25], v[144:145], 2, v[22:23]
	global_store_dwordx4 v[24:25], v[8:11], off offset:512
.LBB0_890:
	v_cvt_pk_bf16_f32 v198, v8, v9
	v_cvt_pk_bf16_f32 v199, v10, v11
	s_waitcnt vmcnt(15)
	v_lshlrev_b32_e32 v24, 16, v250
	v_and_b32_e32 v25, 0xffff0000, v250
	v_lshlrev_b32_e32 v26, 16, v251
	v_and_b32_e32 v27, 0xffff0000, v251
	v_pk_add_f32 v[6:7], v[6:7], v[26:27]
	s_and_b64 vcc, exec, s[42:43]
	v_pk_add_f32 v[4:5], v[4:5], v[24:25]
	s_cbranch_vccnz .LBB0_892
	v_lshl_add_u64 v[22:23], v[144:145], 2, v[22:23]
	global_store_dwordx4 v[22:23], v[4:7], off offset:576
.LBB0_892:
	v_mul_f32_e32 v17, v17, v17
	v_mul_f32_e32 v13, v13, v13
	v_mul_f32_e32 v9, v9, v9
	v_fmac_f32_e32 v17, v16, v16
	v_mul_f32_e32 v16, v19, v19
	v_fmac_f32_e32 v13, v12, v12
	v_mul_f32_e32 v12, v15, v15
	v_fmac_f32_e32 v9, v8, v8
	v_mul_f32_e32 v8, v11, v11
	v_fmac_f32_e32 v16, v18, v18
	v_fmac_f32_e32 v12, v14, v14
	v_fmac_f32_e32 v8, v10, v10
	v_add_f32_e32 v16, v17, v16
	v_add_f32_e32 v12, v13, v12
	v_add_f32_e32 v8, v9, v8
	v_mul_f32_e32 v9, v5, v5
	v_mul_f32_e32 v10, v7, v7
	v_add_f32_e32 v12, v16, v12
	v_fmac_f32_e32 v9, v4, v4
	v_fmac_f32_e32 v10, v6, v6
	v_add_f32_e32 v8, v12, v8
	v_add_f32_e32 v9, v9, v10
	v_add_f32_e32 v8, v8, v9
	ds_bpermute_b32 v9, v120, v8
	v_cvt_pk_bf16_f32 v200, v4, v5
	v_cvt_pk_bf16_f32 v201, v6, v7
	s_nop 1
	v_permlane16_swap_b32_e32 v198, v200
	v_permlane16_swap_b32_e32 v199, v201
	global_store_dwordx4 v[20:21], v[198:201], off offset:256
	s_waitcnt lgkmcnt(0)
	v_add_f32_e32 v8, v8, v9
	ds_bpermute_b32 v9, v121, v8
	s_and_saveexec_b64 s[22:23], s[38:39]
	s_cbranch_execz .LBB0_894
	v_lshlrev_b64 v[4:5], 6, v[68:69]
	v_lshl_add_u64 v[4:5], s[74:75], 0, v[4:5]
	v_lshl_add_u64 v[4:5], s[44:45], 2, v[4:5]
	s_lshl_b32 s8, s51, 2
	v_lshl_add_u64 v[4:5], v[4:5], 0, s[8:9]
	s_waitcnt lgkmcnt(0)
	v_add_f32_e32 v6, v8, v9
	global_store_dword v[4:5], v6, off
